# v083 + old-scheme K-loops (all phases except P7): per-segment s_setprio toggles removed, one static s_setprio 1 for the trailing half after its stagger barrier
# baseline (speedup 1.0000x reference)
.LBB0_197:
	s_add_u32 s11, s56, 0x7c00000
	s_addc_u32 s1, s57, 0
	s_add_u32 s14, s56, 0x8000000
	s_addc_u32 s0, s57, 0
	s_add_u32 s12, s56, 0xc400000
	s_addc_u32 s13, s57, 0
	v_writelane_b32 v240, s18, 29
	s_add_u32 s18, s56, 0x10400000
	v_writelane_b32 v240, s36, 30
	s_addc_u32 s19, s57, 0
	s_andn2_b64 vcc, exec, s[46:47]
	v_writelane_b32 v240, s37, 31
	s_cbranch_vccnz .LBB0_256
	v_ashrrev_i32_e32 v1, 31, v8
	v_lshrrev_b32_e32 v1, 26, v1
	v_add_u32_e32 v1, v8, v1
	v_ashrrev_i32_e32 v9, 6, v1
	v_bfe_i32 v1, v8, 27, 1
	v_lshlrev_b32_e32 v0, 4, v8
	v_lshrrev_b32_e32 v1, 22, v1
	v_add_u32_e32 v1, v0, v1
	v_and_b32_e32 v1, 0xfffffc00, v1
	v_sub_u32_e32 v1, v0, v1
	v_lshrrev_b32_e32 v2, 4, v1
	v_bitop3_b32 v1, v2, v1, 32 bitop3:0x6c
	v_ashrrev_i32_e32 v3, 31, v1
	v_lshrrev_b32_e32 v3, 26, v3
	v_add_u32_e32 v3, v1, v3
	v_lshlrev_b32_e32 v2, 3, v9
	v_ashrrev_i32_e32 v10, 6, v3
	v_and_b32_e32 v3, 0xc0, v3
	v_and_b32_e32 v2, -16, v2
	v_sub_u32_e32 v1, v1, v3
	v_mov_b32_e32 v3, 1
	v_add_u32_e32 v2, v10, v2
	v_ashrrev_i16_sdwa v1, v3, sext(v1) dst_sel:DWORD dst_unused:UNUSED_PAD src0_sel:DWORD src1_sel:BYTE_0
	v_lshlrev_b32_e32 v4, 5, v9
	v_bfe_i32 v11, v1, 0, 16
	v_lshlrev_b32_e32 v1, 1, v2
	v_lshrrev_b32_e32 v5, 2, v2
	v_and_b32_e32 v6, 3, v10
	s_mov_b32 s6, 0xfffe0
	v_and_b32_e32 v4, 32, v4
	v_and_b32_e32 v1, 24, v1
	v_and_b32_e32 v5, 4, v5
	v_and_or_b32 v6, v2, s6, v6
	v_or3_b32 v1, v6, v5, v1
	v_add_lshl_u32 v4, v4, v11, 1
	v_add_u32_e32 v0, 0x2000, v0
	v_lshl_add_u32 v146, v1, 12, v4
	v_ashrrev_i32_e32 v1, 31, v0
	v_lshrrev_b32_e32 v1, 22, v1
	v_add_u32_e32 v1, v0, v1
	v_ashrrev_i32_e32 v12, 10, v1
	v_mul_i32_i24_e32 v1, 0x400, v12
	v_sub_u32_e32 v0, v0, v1
	v_lshrrev_b32_e32 v1, 4, v0
	v_bitop3_b32 v0, v1, v0, 32 bitop3:0x6c
	v_lshl_add_u32 v144, v2, 12, v4
	v_ashrrev_i32_e32 v2, 31, v0
	v_lshrrev_b32_e32 v2, 26, v2
	v_add_u32_e32 v2, v0, v2
	v_lshlrev_b32_e32 v1, 3, v12
	v_ashrrev_i32_e32 v13, 6, v2
	v_and_b32_e32 v2, 0xc0, v2
	v_and_b32_e32 v1, -16, v1
	v_sub_u32_e32 v0, v0, v2
	s_ashr_i32 s33, s16, 6
	v_add_u32_e32 v1, v13, v1
	v_ashrrev_i16_sdwa v0, v3, sext(v0) dst_sel:DWORD dst_unused:UNUSED_PAD src0_sel:DWORD src1_sel:BYTE_0
	s_lshl_b32 s17, s33, 10
	v_lshlrev_b32_e32 v4, 5, v12
	v_bfe_i32 v14, v0, 0, 16
	v_lshlrev_b32_e32 v0, 1, v1
	v_lshrrev_b32_e32 v2, 2, v1
	v_and_b32_e32 v3, 3, v13
	s_add_i32 s21, s17, 0
	v_and_b32_e32 v4, 32, v4
	v_and_b32_e32 v0, 24, v0
	v_and_b32_e32 v2, 4, v2
	v_and_or_b32 v3, v1, s6, v3
	s_add_i32 m0, s21, 0x10000
	s_ashr_i32 s7, s16, 8
	v_or3_b32 v0, v3, v2, v0
	v_add_lshl_u32 v2, v4, v14, 1
	global_load_lds_dwordx4 v146, s[92:93]
	s_add_i32 m0, s21, 0x12000
	v_lshl_add_u32 v150, v0, 12, v2
	s_add_u32 s36, s92, 0x80000
	global_load_lds_dwordx4 v150, s[92:93]
	s_addc_u32 s37, s93, 0
	s_add_i32 m0, s21, 0x14000
	s_add_i32 s39, s21, 0x2000
	global_load_lds_dwordx4 v146, s[36:37]
	s_add_i32 m0, s21, 0x16000
	v_lshl_add_u32 v148, v1, 12, v2
	global_load_lds_dwordx4 v150, s[36:37]
	s_mov_b32 m0, s21
	s_add_u32 s36, s26, 0x80000
	global_load_lds_dwordx4 v144, s[26:27]
	s_mov_b32 m0, s39
	s_addc_u32 s37, s27, 0
	s_add_i32 s6, s21, 0x4000
	global_load_lds_dwordx4 v148, s[26:27]
	s_mov_b32 m0, s6
	s_add_i32 s10, s21, 0x6000
	global_load_lds_dwordx4 v144, s[36:37]
	s_mov_b32 m0, s10
	v_writelane_b32 v240, s42, 32
	global_load_lds_dwordx4 v148, s[36:37]
	v_writelane_b32 v240, s40, 33
	v_mov_b32_e32 v153, 0
	v_mov_b32_e32 v147, v153
	v_writelane_b32 v240, s41, 34
	v_writelane_b32 v240, s74, 35
	v_mov_b32_e32 v151, v153
	v_mov_b32_e32 v145, v153
	v_writelane_b32 v240, s75, 36
	v_writelane_b32 v240, s84, 37
	v_mov_b32_e32 v149, v153
	s_cmp_eq_u32 s7, 1
	v_writelane_b32 v240, s85, 38
	v_writelane_b32 v240, s72, 39
	v_writelane_b32 v240, s96, 40
	s_mov_b32 s37, 0
	v_lshl_add_u64 v[6:7], s[92:93], 0, v[146:147]
	v_writelane_b32 v240, s97, 41
	v_writelane_b32 v240, s89, 42
	v_writelane_b32 v240, s88, 43
	v_lshl_add_u64 v[2:3], s[92:93], 0, v[150:151]
	s_mov_b64 s[46:47], 0x80000
	v_lshl_add_u64 v[0:1], s[26:27], 0, v[144:145]
	s_cselect_b64 s[48:49], -1, 0
	s_cmp_lg_u32 s7, 1
	v_lshl_add_u64 v[4:5], s[26:27], 0, v[148:149]
	v_writelane_b32 v240, s87, 44
	s_cbranch_scc1 .LBB0_200
	s_barrier
	s_setprio 1

.LBB0_241:
	s_add_u32 s94, s26, s92
	s_addc_u32 s95, s27, s93
	s_add_u32 s94, s94, 0x100
	s_addc_u32 s95, s95, 0
	s_add_u32 vcc_lo, s41, s92
	s_addc_u32 vcc_hi, s44, s93
	s_add_i32 s43, 0, 0x10000
	v_add_u32_e32 v152, s43, v171
	ds_read_b128 v[132:135], v152
	ds_read_b128 v[136:139], v152 offset:1024
	ds_read_b128 v[140:143], v152 offset:2048
	ds_read_b128 v[166:169], v152 offset:3072
	v_add_u32_e32 v152, s8, v171
	ds_read_b128 v[178:181], v152
	ds_read_b128 v[182:185], v152 offset:1024
	ds_read_b128 v[186:189], v152 offset:2048
	ds_read_b128 v[190:193], v152 offset:3072
	s_cmpk_eq_i32 s92, 0xf00
	s_cselect_b32 s97, s45, s95
	s_cselect_b32 s96, s50, s94
	s_cselect_b32 s95, s51, vcc_hi
	s_cselect_b32 s94, s81, vcc_lo
	v_lshl_add_u64 v[226:227], v[128:129], 0, s[92:93]
	s_add_i32 m0, s21, 0xc000
	ds_read_b128 v[194:197], v173
	ds_read_b128 v[198:201], v173 offset:1024
	ds_read_b128 v[202:205], v173 offset:2048
	ds_read_b128 v[206:209], v173 offset:3072
	ds_read_b128 v[210:213], v173 offset:4096
	ds_read_b128 v[214:217], v173 offset:5120
	ds_read_b128 v[218:221], v173 offset:6144
	ds_read_b128 v[222:225], v173 offset:7168
	global_load_lds_dwordx4 v[226:227], off
	v_lshl_add_u64 v[226:227], v[130:131], 0, s[92:93]
	s_add_i32 m0, s21, 0xe000
	s_nop 0
	global_load_lds_dwordx4 v[226:227], off
	s_waitcnt vmcnt(8)
	s_waitcnt lgkmcnt(0)
	s_barrier
	s_waitcnt lgkmcnt(0)
	v_mfma_f32_16x16x32_bf16 v[124:127], v[132:135], v[194:197], v[124:127]
	v_mfma_f32_16x16x32_bf16 v[124:127], v[136:139], v[198:201], v[124:127]
	v_mfma_f32_16x16x32_bf16 v[120:123], v[140:143], v[194:197], v[120:123]
	v_mfma_f32_16x16x32_bf16 v[120:123], v[166:169], v[198:201], v[120:123]
	v_mfma_f32_16x16x32_bf16 v[116:119], v[132:135], v[202:205], v[116:119]
	v_mfma_f32_16x16x32_bf16 v[116:119], v[136:139], v[206:209], v[116:119]
	v_mfma_f32_16x16x32_bf16 v[112:115], v[140:143], v[202:205], v[112:115]
	v_mfma_f32_16x16x32_bf16 v[112:115], v[166:169], v[206:209], v[112:115]
	v_mfma_f32_16x16x32_bf16 v[108:111], v[132:135], v[210:213], v[108:111]
	v_mfma_f32_16x16x32_bf16 v[108:111], v[136:139], v[214:217], v[108:111]
	v_mfma_f32_16x16x32_bf16 v[104:107], v[140:143], v[210:213], v[104:107]
	v_mfma_f32_16x16x32_bf16 v[104:107], v[166:169], v[214:217], v[104:107]
	v_mfma_f32_16x16x32_bf16 v[100:103], v[132:135], v[218:221], v[100:103]
	v_mfma_f32_16x16x32_bf16 v[100:103], v[136:139], v[222:225], v[100:103]
	v_mfma_f32_16x16x32_bf16 v[96:99], v[140:143], v[218:221], v[96:99]
	v_mfma_f32_16x16x32_bf16 v[96:99], v[166:169], v[222:225], v[96:99]
	v_mfma_f32_16x16x32_bf16 v[92:95], v[178:181], v[194:197], v[92:95]
	v_mfma_f32_16x16x32_bf16 v[92:95], v[182:185], v[198:201], v[92:95]
	v_mfma_f32_16x16x32_bf16 v[88:91], v[186:189], v[194:197], v[88:91]
	v_mfma_f32_16x16x32_bf16 v[88:91], v[190:193], v[198:201], v[88:91]
	v_mfma_f32_16x16x32_bf16 v[84:87], v[178:181], v[202:205], v[84:87]
	v_mfma_f32_16x16x32_bf16 v[84:87], v[182:185], v[206:209], v[84:87]
	v_mfma_f32_16x16x32_bf16 v[80:83], v[186:189], v[202:205], v[80:83]
	v_mfma_f32_16x16x32_bf16 v[80:83], v[190:193], v[206:209], v[80:83]
	v_mfma_f32_16x16x32_bf16 v[76:79], v[178:181], v[210:213], v[76:79]
	v_mfma_f32_16x16x32_bf16 v[76:79], v[182:185], v[214:217], v[76:79]
	v_mfma_f32_16x16x32_bf16 v[72:75], v[186:189], v[210:213], v[72:75]
	v_mfma_f32_16x16x32_bf16 v[72:75], v[190:193], v[214:217], v[72:75]
	v_mfma_f32_16x16x32_bf16 v[68:71], v[178:181], v[218:221], v[68:71]
	v_mfma_f32_16x16x32_bf16 v[68:71], v[182:185], v[222:225], v[68:71]
	v_mfma_f32_16x16x32_bf16 v[64:67], v[186:189], v[218:221], v[64:67]
	v_mfma_f32_16x16x32_bf16 v[64:67], v[190:193], v[222:225], v[64:67]
	s_barrier
	s_add_i32 s43, s43, s17
	s_add_u32 s98, s94, s70
	s_addc_u32 s99, s95, s71
	s_mov_b32 m0, s43
	ds_read_b128 v[194:197], v173 offset:16384
	ds_read_b128 v[198:201], v173 offset:17408
	ds_read_b128 v[202:205], v173 offset:18432
	ds_read_b128 v[206:209], v173 offset:19456
	ds_read_b128 v[210:213], v173 offset:20480
	ds_read_b128 v[214:217], v173 offset:21504
	ds_read_b128 v[218:221], v173 offset:22528
	ds_read_b128 v[222:225], v173 offset:23552
	global_load_lds_dwordx4 v146, s[94:95]
	s_add_i32 m0, s43, 0x2000
	s_add_u32 vcc_lo, s94, 0x80000
	s_addc_u32 vcc_hi, s95, 0
	s_add_i32 s43, s8, s17
	global_load_lds_dwordx4 v150, s[94:95]
	s_mov_b32 m0, s43
	s_nop 0
	global_load_lds_dwordx4 v146, vcc
	s_add_i32 m0, s43, 0x2000
	s_nop 0
	global_load_lds_dwordx4 v150, vcc
	s_add_u32 s100, s96, s70
	s_addc_u32 s101, s97, s71
	s_mov_b32 m0, s21
	s_nop 0
	global_load_lds_dwordx4 v144, s[96:97]
	s_mov_b32 m0, s39
	s_nop 0
	global_load_lds_dwordx4 v148, s[96:97]
	s_waitcnt vmcnt(8)
	s_waitcnt lgkmcnt(0)
	s_barrier
	s_waitcnt lgkmcnt(0)
	v_mfma_f32_16x16x32_bf16 v[60:63], v[132:135], v[194:197], v[60:63]
	v_mfma_f32_16x16x32_bf16 v[60:63], v[136:139], v[198:201], v[60:63]
	v_mfma_f32_16x16x32_bf16 v[56:59], v[140:143], v[194:197], v[56:59]
	v_mfma_f32_16x16x32_bf16 v[56:59], v[166:169], v[198:201], v[56:59]
	v_mfma_f32_16x16x32_bf16 v[52:55], v[132:135], v[202:205], v[52:55]
	v_mfma_f32_16x16x32_bf16 v[52:55], v[136:139], v[206:209], v[52:55]
	v_mfma_f32_16x16x32_bf16 v[48:51], v[140:143], v[202:205], v[48:51]
	v_mfma_f32_16x16x32_bf16 v[48:51], v[166:169], v[206:209], v[48:51]
	v_mfma_f32_16x16x32_bf16 v[44:47], v[132:135], v[210:213], v[44:47]
	v_mfma_f32_16x16x32_bf16 v[44:47], v[136:139], v[214:217], v[44:47]
	v_mfma_f32_16x16x32_bf16 v[40:43], v[140:143], v[210:213], v[40:43]
	v_mfma_f32_16x16x32_bf16 v[40:43], v[166:169], v[214:217], v[40:43]
	v_mfma_f32_16x16x32_bf16 v[36:39], v[132:135], v[218:221], v[36:39]
	v_mfma_f32_16x16x32_bf16 v[36:39], v[136:139], v[222:225], v[36:39]
	v_mfma_f32_16x16x32_bf16 v[32:35], v[140:143], v[218:221], v[32:35]
	v_mfma_f32_16x16x32_bf16 v[32:35], v[166:169], v[222:225], v[32:35]
	v_mfma_f32_16x16x32_bf16 v[28:31], v[178:181], v[194:197], v[28:31]
	v_mfma_f32_16x16x32_bf16 v[28:31], v[182:185], v[198:201], v[28:31]
	v_mfma_f32_16x16x32_bf16 v[24:27], v[186:189], v[194:197], v[24:27]
	v_mfma_f32_16x16x32_bf16 v[24:27], v[190:193], v[198:201], v[24:27]
	v_mfma_f32_16x16x32_bf16 v[20:23], v[178:181], v[202:205], v[20:23]
	v_mfma_f32_16x16x32_bf16 v[20:23], v[182:185], v[206:209], v[20:23]
	v_mfma_f32_16x16x32_bf16 v[16:19], v[186:189], v[202:205], v[16:19]
	v_mfma_f32_16x16x32_bf16 v[16:19], v[190:193], v[206:209], v[16:19]
	v_mfma_f32_16x16x32_bf16 v[12:15], v[178:181], v[210:213], v[12:15]
	v_mfma_f32_16x16x32_bf16 v[12:15], v[182:185], v[214:217], v[12:15]
	v_mfma_f32_16x16x32_bf16 v[8:11], v[186:189], v[210:213], v[8:11]
	v_mfma_f32_16x16x32_bf16 v[8:11], v[190:193], v[214:217], v[8:11]
	v_mfma_f32_16x16x32_bf16 v[4:7], v[178:181], v[218:221], v[4:7]
	v_mfma_f32_16x16x32_bf16 v[4:7], v[182:185], v[222:225], v[4:7]
	v_mfma_f32_16x16x32_bf16 v[0:3], v[186:189], v[218:221], v[0:3]
	v_mfma_f32_16x16x32_bf16 v[0:3], v[190:193], v[222:225], v[0:3]
	s_barrier
	s_add_i32 s43, 0, 0x18000
	v_add_u32_e32 v152, s43, v171
	s_add_i32 vcc_lo, 0, 0x1c000
	ds_read_b128 v[132:135], v152
	ds_read_b128 v[136:139], v152 offset:1024
	ds_read_b128 v[140:143], v152 offset:2048
	ds_read_b128 v[166:169], v152 offset:3072
	v_add_u32_e32 v152, vcc_lo, v171
	ds_read_b128 v[178:181], v152
	ds_read_b128 v[182:185], v152 offset:1024
	ds_read_b128 v[186:189], v152 offset:2048
	ds_read_b128 v[190:193], v152 offset:3072
	s_add_u32 s96, s96, 0x80000
	s_addc_u32 s97, s97, 0
	s_mov_b32 m0, s6
	ds_read_b128 v[194:197], v173 offset:32768
	ds_read_b128 v[198:201], v173 offset:33792
	ds_read_b128 v[202:205], v173 offset:34816
	ds_read_b128 v[206:209], v173 offset:35840
	ds_read_b128 v[210:213], v173 offset:36864
	ds_read_b128 v[214:217], v173 offset:37888
	ds_read_b128 v[218:221], v173 offset:38912
	ds_read_b128 v[222:225], v173 offset:39936
	global_load_lds_dwordx4 v144, s[96:97]
	s_mov_b32 m0, s10
	s_nop 0
	global_load_lds_dwordx4 v148, s[96:97]
	s_waitcnt vmcnt(8)
	s_waitcnt lgkmcnt(0)
	s_barrier
	s_waitcnt lgkmcnt(0)
	v_mfma_f32_16x16x32_bf16 v[124:127], v[132:135], v[194:197], v[124:127]
	v_mfma_f32_16x16x32_bf16 v[124:127], v[136:139], v[198:201], v[124:127]
	v_mfma_f32_16x16x32_bf16 v[120:123], v[140:143], v[194:197], v[120:123]
	v_mfma_f32_16x16x32_bf16 v[120:123], v[166:169], v[198:201], v[120:123]
	v_mfma_f32_16x16x32_bf16 v[116:119], v[132:135], v[202:205], v[116:119]
	v_mfma_f32_16x16x32_bf16 v[116:119], v[136:139], v[206:209], v[116:119]
	v_mfma_f32_16x16x32_bf16 v[112:115], v[140:143], v[202:205], v[112:115]
	v_mfma_f32_16x16x32_bf16 v[112:115], v[166:169], v[206:209], v[112:115]
	v_mfma_f32_16x16x32_bf16 v[108:111], v[132:135], v[210:213], v[108:111]
	v_mfma_f32_16x16x32_bf16 v[108:111], v[136:139], v[214:217], v[108:111]
	v_mfma_f32_16x16x32_bf16 v[104:107], v[140:143], v[210:213], v[104:107]
	v_mfma_f32_16x16x32_bf16 v[104:107], v[166:169], v[214:217], v[104:107]
	v_mfma_f32_16x16x32_bf16 v[100:103], v[132:135], v[218:221], v[100:103]
	v_mfma_f32_16x16x32_bf16 v[100:103], v[136:139], v[222:225], v[100:103]
	v_mfma_f32_16x16x32_bf16 v[96:99], v[140:143], v[218:221], v[96:99]
	v_mfma_f32_16x16x32_bf16 v[96:99], v[166:169], v[222:225], v[96:99]
	v_mfma_f32_16x16x32_bf16 v[92:95], v[178:181], v[194:197], v[92:95]
	v_mfma_f32_16x16x32_bf16 v[92:95], v[182:185], v[198:201], v[92:95]
	v_mfma_f32_16x16x32_bf16 v[88:91], v[186:189], v[194:197], v[88:91]
	v_mfma_f32_16x16x32_bf16 v[88:91], v[190:193], v[198:201], v[88:91]
	v_mfma_f32_16x16x32_bf16 v[84:87], v[178:181], v[202:205], v[84:87]
	v_mfma_f32_16x16x32_bf16 v[84:87], v[182:185], v[206:209], v[84:87]
	v_mfma_f32_16x16x32_bf16 v[80:83], v[186:189], v[202:205], v[80:83]
	v_mfma_f32_16x16x32_bf16 v[80:83], v[190:193], v[206:209], v[80:83]
	v_mfma_f32_16x16x32_bf16 v[76:79], v[178:181], v[210:213], v[76:79]
	v_mfma_f32_16x16x32_bf16 v[76:79], v[182:185], v[214:217], v[76:79]
	v_mfma_f32_16x16x32_bf16 v[72:75], v[186:189], v[210:213], v[72:75]
	v_mfma_f32_16x16x32_bf16 v[72:75], v[190:193], v[214:217], v[72:75]
	v_mfma_f32_16x16x32_bf16 v[68:71], v[178:181], v[218:221], v[68:71]
	v_mfma_f32_16x16x32_bf16 v[68:71], v[182:185], v[222:225], v[68:71]
	v_mfma_f32_16x16x32_bf16 v[64:67], v[186:189], v[218:221], v[64:67]
	v_mfma_f32_16x16x32_bf16 v[64:67], v[190:193], v[222:225], v[64:67]
	s_barrier
	s_add_i32 s43, s43, s17
	s_mov_b32 m0, s43
	ds_read_b128 v[194:197], v173 offset:49152
	ds_read_b128 v[198:201], v173 offset:50176
	ds_read_b128 v[202:205], v173 offset:51200
	ds_read_b128 v[206:209], v173 offset:52224
	ds_read_b128 v[210:213], v173 offset:53248
	ds_read_b128 v[214:217], v173 offset:54272
	ds_read_b128 v[218:221], v173 offset:55296
	ds_read_b128 v[222:225], v173 offset:56320
	global_load_lds_dwordx4 v146, s[98:99]
	s_add_i32 m0, s43, 0x2000
	s_add_u32 s94, s94, 0x80080
	s_addc_u32 s95, s95, 0
	s_add_i32 s43, vcc_lo, s17
	global_load_lds_dwordx4 v150, s[98:99]
	s_mov_b32 m0, s43
	s_nop 0
	global_load_lds_dwordx4 v146, s[94:95]
	s_add_i32 m0, s43, 0x2000
	s_nop 0
	global_load_lds_dwordx4 v150, s[94:95]
	s_mov_b32 m0, s33
	s_nop 0
	global_load_lds_dwordx4 v144, s[100:101]
	s_mov_b32 m0, s7
	s_nop 0
	global_load_lds_dwordx4 v148, s[100:101]
	s_waitcnt vmcnt(8)
	s_waitcnt lgkmcnt(0)
	s_barrier
	s_waitcnt lgkmcnt(0)
	v_mfma_f32_16x16x32_bf16 v[60:63], v[132:135], v[194:197], v[60:63]
	v_mfma_f32_16x16x32_bf16 v[60:63], v[136:139], v[198:201], v[60:63]
	v_mfma_f32_16x16x32_bf16 v[56:59], v[140:143], v[194:197], v[56:59]
	v_mfma_f32_16x16x32_bf16 v[56:59], v[166:169], v[198:201], v[56:59]
	v_mfma_f32_16x16x32_bf16 v[52:55], v[132:135], v[202:205], v[52:55]
	v_mfma_f32_16x16x32_bf16 v[52:55], v[136:139], v[206:209], v[52:55]
	v_mfma_f32_16x16x32_bf16 v[48:51], v[140:143], v[202:205], v[48:51]
	v_mfma_f32_16x16x32_bf16 v[48:51], v[166:169], v[206:209], v[48:51]
	v_mfma_f32_16x16x32_bf16 v[44:47], v[132:135], v[210:213], v[44:47]
	v_mfma_f32_16x16x32_bf16 v[44:47], v[136:139], v[214:217], v[44:47]
	v_mfma_f32_16x16x32_bf16 v[40:43], v[140:143], v[210:213], v[40:43]
	v_mfma_f32_16x16x32_bf16 v[40:43], v[166:169], v[214:217], v[40:43]
	v_mfma_f32_16x16x32_bf16 v[36:39], v[132:135], v[218:221], v[36:39]
	v_mfma_f32_16x16x32_bf16 v[36:39], v[136:139], v[222:225], v[36:39]
	v_mfma_f32_16x16x32_bf16 v[32:35], v[140:143], v[218:221], v[32:35]
	v_mfma_f32_16x16x32_bf16 v[32:35], v[166:169], v[222:225], v[32:35]
	v_mfma_f32_16x16x32_bf16 v[28:31], v[178:181], v[194:197], v[28:31]
	v_mfma_f32_16x16x32_bf16 v[28:31], v[182:185], v[198:201], v[28:31]
	v_mfma_f32_16x16x32_bf16 v[24:27], v[186:189], v[194:197], v[24:27]
	v_mfma_f32_16x16x32_bf16 v[24:27], v[190:193], v[198:201], v[24:27]
	v_mfma_f32_16x16x32_bf16 v[20:23], v[178:181], v[202:205], v[20:23]
	v_mfma_f32_16x16x32_bf16 v[20:23], v[182:185], v[206:209], v[20:23]
	v_mfma_f32_16x16x32_bf16 v[16:19], v[186:189], v[202:205], v[16:19]
	v_mfma_f32_16x16x32_bf16 v[16:19], v[190:193], v[206:209], v[16:19]
	v_mfma_f32_16x16x32_bf16 v[12:15], v[178:181], v[210:213], v[12:15]
	v_mfma_f32_16x16x32_bf16 v[12:15], v[182:185], v[214:217], v[12:15]
	v_mfma_f32_16x16x32_bf16 v[8:11], v[186:189], v[210:213], v[8:11]
	v_mfma_f32_16x16x32_bf16 v[8:11], v[190:193], v[214:217], v[8:11]
	v_mfma_f32_16x16x32_bf16 v[4:7], v[178:181], v[218:221], v[4:7]
	v_mfma_f32_16x16x32_bf16 v[4:7], v[182:185], v[222:225], v[4:7]
	v_mfma_f32_16x16x32_bf16 v[0:3], v[186:189], v[218:221], v[0:3]
	v_mfma_f32_16x16x32_bf16 v[0:3], v[190:193], v[222:225], v[0:3]
	s_barrier
	s_add_i32 s83, s83, 2
	s_add_u32 s92, s92, 0x100
	s_addc_u32 s93, s93, 0
	s_cmp_gt_u32 s83, 29
	s_cbranch_scc0 .LBB0_241
	s_and_b64 vcc, exec, s[72:73]
	s_cbranch_vccz .LBB0_244
	s_barrier

.LBB0_256:
	s_add_u32 s73, s56, 0x18800000
	s_addc_u32 s74, s57, 0
	s_add_u32 s70, s56, 0x16400000
	s_addc_u32 s71, s57, 0
	s_bfe_u32 s90, s2, 0x20003
	s_add_u32 s75, s56, 0x1500000
	v_mov_b32_e32 v10, v174
	s_addc_u32 s76, s57, 0
	s_andn2_b64 vcc, exec, s[40:41]
	v_readfirstlane_b32 s4, v10
	s_cbranch_vccnz .LBB0_280
	v_lshlrev_b32_e32 v0, 4, v10
	v_add_u32_e32 v1, 0x2000, v0
	v_ashrrev_i32_e32 v2, 31, v1
	v_lshrrev_b32_e32 v2, 22, v2
	v_add_u32_e32 v2, v1, v2
	v_ashrrev_i32_e32 v8, 10, v2
	v_mul_i32_i24_e32 v2, 0x400, v8
	v_sub_u32_e32 v1, v1, v2
	v_lshrrev_b32_e32 v2, 4, v1
	v_bitop3_b32 v1, v2, v1, 32 bitop3:0x6c
	v_ashrrev_i32_e32 v2, 31, v1
	v_lshrrev_b32_e32 v2, 26, v2
	v_add_u32_e32 v2, v1, v2
	v_lshlrev_b32_e32 v3, 3, v8
	v_ashrrev_i32_e32 v9, 6, v2
	v_and_b32_e32 v3, -16, v3
	v_add_u32_e32 v3, v9, v3
	v_and_b32_e32 v4, 3, v9
	s_mov_b32 s10, 0xfffe0
	v_lshrrev_b32_e32 v5, 2, v3
	v_lshlrev_b32_e32 v6, 1, v3
	v_and_b32_e32 v2, 0xc0, v2
	v_and_or_b32 v4, v3, s10, v4
	v_and_b32_e32 v5, 4, v5
	v_and_b32_e32 v6, 24, v6
	v_sub_u32_e32 v1, v1, v2
	v_mov_b32_e32 v2, 1
	v_or3_b32 v4, v4, v5, v6
	v_lshlrev_b32_e32 v5, 5, v8
	v_ashrrev_i16_sdwa v1, v2, sext(v1) dst_sel:DWORD dst_unused:UNUSED_PAD src0_sel:DWORD src1_sel:BYTE_0
	v_and_b32_e32 v5, 32, v5
	v_bfe_i32 v11, v1, 0, 16
	v_add_lshl_u32 v1, v5, v11, 1
	v_lshl_add_u32 v128, v4, 12, v1
	v_lshl_add_u32 v130, v3, 12, v1
	v_bfe_i32 v1, v10, 27, 1
	v_lshrrev_b32_e32 v1, 22, v1
	v_add_u32_e32 v1, v0, v1
	s_add_i32 s7, s2, 0x80
	v_and_b32_e32 v1, 0xfffffc00, v1
	s_ashr_i32 s9, s7, 3
	v_sub_u32_e32 v0, v0, v1
	s_ashr_i32 s5, s4, 6
	s_lshr_b32 s8, s2, 2
	s_and_b32 s9, s9, -4
	v_lshrrev_b32_e32 v1, 4, v0
	v_ashrrev_i32_e32 v3, 31, v10
	s_ashr_i32 s16, s4, 8
	s_lshl_b32 s6, s5, 10
	s_bitset1_b32 s8, 12
	s_or_b32 s9, s9, s90
	v_bitop3_b32 v0, v1, v0, 32 bitop3:0x6c
	v_lshrrev_b32_e32 v3, 26, v3
	s_cmp_lt_i32 s2, 0
	v_ashrrev_i32_e32 v1, 31, v0
	v_add_u32_e32 v3, v10, v3
	v_lshrrev_b32_e32 v1, 26, v1
	v_ashrrev_i32_e32 v13, 6, v3
	s_cselect_b32 s77, s9, s8
	v_add_u32_e32 v1, v0, v1
	v_lshlrev_b32_e32 v3, 3, v13
	s_cselect_b32 s8, 7, 3
	s_lshl_b32 s9, s77, 18
	v_ashrrev_i32_e32 v12, 6, v1
	v_and_b32_e32 v3, -16, v3
	s_and_b32 s51, s8, s7
	s_and_b32 s8, s77, 0x1000
	s_and_b32 s9, s9, 0x3ff00000
	v_add_u32_e32 v3, v12, v3
	v_and_b32_e32 v4, 3, v12
	s_add_u32 s9, s11, s9
	v_and_or_b32 v4, v3, s10, v4
	s_addc_u32 s10, s1, 0
	s_lshl_b32 s17, s77, 10
	s_and_b32 s17, s17, 0xc00
	s_add_u32 s9, s9, s17
	s_addc_u32 s20, s10, 0
	s_lshl_b32 s10, s51, 20
	s_add_u32 s21, s73, s10
	s_addc_u32 s22, s74, 0
	s_add_u32 s10, s75, s10
	s_addc_u32 s23, s76, 0
	s_add_u32 s17, s10, s17
	s_addc_u32 s23, s23, 0
	s_add_i32 s10, s6, 0
	s_add_i32 m0, s10, 0x10000
	s_add_i32 s26, s10, 0x12000
	s_lshl_b32 s27, s77, 20
	v_lshrrev_b32_e32 v5, 2, v3
	v_lshlrev_b32_e32 v6, 1, v3
	v_and_b32_e32 v1, 0xc0, v1
	s_add_u32 s27, s34, s27
	v_and_b32_e32 v5, 4, v5
	v_and_b32_e32 v6, 24, v6
	v_sub_u32_e32 v0, v0, v1
	s_addc_u32 s33, s35, 0
	s_lshl_b32 s36, s51, 9
	v_or3_b32 v4, v4, v5, v6
	v_lshlrev_b32_e32 v5, 5, v13
	v_ashrrev_i16_sdwa v0, v2, sext(v0) dst_sel:DWORD dst_unused:UNUSED_PAD src0_sel:DWORD src1_sel:BYTE_0
	s_add_u32 s27, s27, s36
	v_and_b32_e32 v5, 32, v5
	v_bfe_i32 v14, v0, 0, 16
	s_addc_u32 s33, s33, 0
	v_add_lshl_u32 v0, v5, v14, 1
	s_cmp_eq_u32 s8, 0
	v_lshl_add_u32 v132, v4, 12, v0
	s_cselect_b32 s49, s23, s22
	s_cselect_b32 s48, s17, s21
	global_load_lds_dwordx4 v132, s[48:49]
	s_mov_b32 m0, s26
	s_cselect_b32 s46, s9, s27
	s_cselect_b32 s47, s20, s33
	s_add_u32 s8, s48, 0x80000
	global_load_lds_dwordx4 v128, s[48:49]
	s_addc_u32 s9, s49, 0
	s_add_i32 m0, s10, 0x14000
	s_add_i32 s22, s10, 0x2000
	global_load_lds_dwordx4 v132, s[8:9]
	s_add_i32 m0, s10, 0x16000
	v_lshl_add_u32 v134, v3, 12, v0
	global_load_lds_dwordx4 v128, s[8:9]
	s_mov_b32 m0, s10
	s_add_u32 s8, s46, 0x80000
	global_load_lds_dwordx4 v134, s[46:47]
	s_mov_b32 m0, s22
	s_addc_u32 s9, s47, 0
	s_add_i32 s23, s10, 0x4000
	global_load_lds_dwordx4 v130, s[46:47]
	s_mov_b32 m0, s23
	s_add_i32 s33, s10, 0x6000
	global_load_lds_dwordx4 v134, s[8:9]
	s_mov_b32 m0, s33
	v_mov_b32_e32 v133, 0
	global_load_lds_dwordx4 v130, s[8:9]
	v_mov_b32_e32 v129, v133
	v_mov_b32_e32 v135, v133
	v_mov_b32_e32 v131, v133
	s_cmp_eq_u32 s16, 1
	s_mov_b32 s36, 0
	v_lshl_add_u64 v[6:7], s[48:49], 0, v[132:133]
	v_lshl_add_u64 v[2:3], s[48:49], 0, v[128:129]
	v_lshl_add_u64 v[0:1], s[46:47], 0, v[134:135]
	s_cselect_b64 s[8:9], -1, 0
	s_cmp_lg_u32 s16, 1
	v_lshl_add_u64 v[4:5], s[46:47], 0, v[130:131]
	s_cbranch_scc1 .LBB0_259
	s_barrier
	s_setprio 1

.LBB0_273:
	ds_read_b128 v[146:149], v141
	ds_read_b128 v[150:153], v141 offset:1024
	ds_read_b128 v[154:157], v141 offset:2048
	ds_read_b128 v[158:161], v141 offset:3072
	ds_read_b128 v[162:165], v142
	ds_read_b128 v[166:169], v142 offset:1024
	ds_read_b128 v[170:173], v142 offset:2048
	ds_read_b128 v[176:179], v142 offset:3072
	s_add_u32 s48, s46, 0xfff80080
	s_addc_u32 s49, s47, -1
	s_cmp_eq_u32 s80, 4
	s_cselect_b32 s69, s39, s49
	s_cselect_b32 s68, s38, s48
	s_cselect_b32 s49, s43, s79
	s_cselect_b32 s48, s42, s27
	s_add_i32 m0, s10, 0xc000
	ds_read_b128 v[180:183], v143
	ds_read_b128 v[184:187], v143 offset:1024
	ds_read_b128 v[188:191], v143 offset:2048
	ds_read_b128 v[192:195], v143 offset:3072
	ds_read_b128 v[196:199], v143 offset:4096
	ds_read_b128 v[200:203], v143 offset:5120
	ds_read_b128 v[204:207], v143 offset:6144
	ds_read_b128 v[208:211], v143 offset:7168
	global_load_lds_dwordx4 v136, s[46:47]
	s_add_i32 m0, s10, 0xe000
	s_nop 0
	global_load_lds_dwordx4 v138, s[46:47]
	s_waitcnt vmcnt(8)
	s_waitcnt lgkmcnt(0)
	s_barrier
	s_waitcnt lgkmcnt(0)
	v_mfma_f32_16x16x32_bf16 v[124:127], v[146:149], v[180:183], v[124:127]
	v_mfma_f32_16x16x32_bf16 v[124:127], v[150:153], v[184:187], v[124:127]
	v_mfma_f32_16x16x32_bf16 v[120:123], v[154:157], v[180:183], v[120:123]
	v_mfma_f32_16x16x32_bf16 v[120:123], v[158:161], v[184:187], v[120:123]
	v_mfma_f32_16x16x32_bf16 v[116:119], v[146:149], v[188:191], v[116:119]
	v_mfma_f32_16x16x32_bf16 v[116:119], v[150:153], v[192:195], v[116:119]
	v_mfma_f32_16x16x32_bf16 v[112:115], v[154:157], v[188:191], v[112:115]
	v_mfma_f32_16x16x32_bf16 v[112:115], v[158:161], v[192:195], v[112:115]
	v_mfma_f32_16x16x32_bf16 v[100:103], v[146:149], v[196:199], v[100:103]
	v_mfma_f32_16x16x32_bf16 v[100:103], v[150:153], v[200:203], v[100:103]
	v_mfma_f32_16x16x32_bf16 v[96:99], v[154:157], v[196:199], v[96:99]
	v_mfma_f32_16x16x32_bf16 v[96:99], v[158:161], v[200:203], v[96:99]
	v_mfma_f32_16x16x32_bf16 v[84:87], v[146:149], v[204:207], v[84:87]
	v_mfma_f32_16x16x32_bf16 v[84:87], v[150:153], v[208:211], v[84:87]
	v_mfma_f32_16x16x32_bf16 v[80:83], v[154:157], v[204:207], v[80:83]
	v_mfma_f32_16x16x32_bf16 v[80:83], v[158:161], v[208:211], v[80:83]
	v_mfma_f32_16x16x32_bf16 v[108:111], v[162:165], v[180:183], v[108:111]
	v_mfma_f32_16x16x32_bf16 v[108:111], v[166:169], v[184:187], v[108:111]
	v_mfma_f32_16x16x32_bf16 v[104:107], v[170:173], v[180:183], v[104:107]
	v_mfma_f32_16x16x32_bf16 v[104:107], v[176:179], v[184:187], v[104:107]
	v_mfma_f32_16x16x32_bf16 v[92:95], v[162:165], v[188:191], v[92:95]
	v_mfma_f32_16x16x32_bf16 v[92:95], v[166:169], v[192:195], v[92:95]
	v_mfma_f32_16x16x32_bf16 v[88:91], v[170:173], v[188:191], v[88:91]
	v_mfma_f32_16x16x32_bf16 v[88:91], v[176:179], v[192:195], v[88:91]
	v_mfma_f32_16x16x32_bf16 v[76:79], v[162:165], v[196:199], v[76:79]
	v_mfma_f32_16x16x32_bf16 v[76:79], v[166:169], v[200:203], v[76:79]
	v_mfma_f32_16x16x32_bf16 v[72:75], v[170:173], v[196:199], v[72:75]
	v_mfma_f32_16x16x32_bf16 v[72:75], v[176:179], v[200:203], v[72:75]
	v_mfma_f32_16x16x32_bf16 v[68:71], v[162:165], v[204:207], v[68:71]
	v_mfma_f32_16x16x32_bf16 v[68:71], v[166:169], v[208:211], v[68:71]
	v_mfma_f32_16x16x32_bf16 v[64:67], v[170:173], v[204:207], v[64:67]
	v_mfma_f32_16x16x32_bf16 v[64:67], v[176:179], v[208:211], v[64:67]
	s_barrier
	s_add_i32 s81, s45, s6
	s_add_u32 s98, s48, s16
	s_addc_u32 s99, s49, s17
	s_mov_b32 m0, s81
	ds_read_b128 v[180:183], v143 offset:16384
	ds_read_b128 v[184:187], v143 offset:17408
	ds_read_b128 v[188:191], v143 offset:18432
	ds_read_b128 v[192:195], v143 offset:19456
	ds_read_b128 v[196:199], v143 offset:20480
	ds_read_b128 v[200:203], v143 offset:21504
	ds_read_b128 v[204:207], v143 offset:22528
	ds_read_b128 v[208:211], v143 offset:23552
	global_load_lds_dwordx4 v132, s[48:49]
	s_add_i32 m0, s81, 0x2000
	s_add_u32 s82, s48, 0x80000
	s_addc_u32 s83, s49, 0
	s_add_i32 s81, s50, s6
	global_load_lds_dwordx4 v128, s[48:49]
	s_mov_b32 m0, s81
	s_nop 0
	global_load_lds_dwordx4 v132, s[82:83]
	s_add_i32 m0, s81, 0x2000
	s_nop 0
	global_load_lds_dwordx4 v128, s[82:83]
	s_add_u32 s100, s68, s16
	s_addc_u32 s101, s69, s17
	s_mov_b32 m0, s10
	s_nop 0
	global_load_lds_dwordx4 v134, s[68:69]
	s_mov_b32 m0, s22
	s_nop 0
	global_load_lds_dwordx4 v130, s[68:69]
	s_waitcnt vmcnt(8)
	s_waitcnt lgkmcnt(0)
	s_barrier
	s_waitcnt lgkmcnt(0)
	v_mfma_f32_16x16x32_bf16 v[60:63], v[146:149], v[180:183], v[60:63]
	v_mfma_f32_16x16x32_bf16 v[60:63], v[150:153], v[184:187], v[60:63]
	v_mfma_f32_16x16x32_bf16 v[56:59], v[154:157], v[180:183], v[56:59]
	v_mfma_f32_16x16x32_bf16 v[56:59], v[158:161], v[184:187], v[56:59]
	v_mfma_f32_16x16x32_bf16 v[52:55], v[146:149], v[188:191], v[52:55]
	v_mfma_f32_16x16x32_bf16 v[52:55], v[150:153], v[192:195], v[52:55]
	v_mfma_f32_16x16x32_bf16 v[48:51], v[154:157], v[188:191], v[48:51]
	v_mfma_f32_16x16x32_bf16 v[48:51], v[158:161], v[192:195], v[48:51]
	v_mfma_f32_16x16x32_bf16 v[36:39], v[146:149], v[196:199], v[36:39]
	v_mfma_f32_16x16x32_bf16 v[36:39], v[150:153], v[200:203], v[36:39]
	v_mfma_f32_16x16x32_bf16 v[32:35], v[154:157], v[196:199], v[32:35]
	v_mfma_f32_16x16x32_bf16 v[32:35], v[158:161], v[200:203], v[32:35]
	v_mfma_f32_16x16x32_bf16 v[20:23], v[146:149], v[204:207], v[20:23]
	v_mfma_f32_16x16x32_bf16 v[20:23], v[150:153], v[208:211], v[20:23]
	v_mfma_f32_16x16x32_bf16 v[16:19], v[154:157], v[204:207], v[16:19]
	v_mfma_f32_16x16x32_bf16 v[16:19], v[158:161], v[208:211], v[16:19]
	v_mfma_f32_16x16x32_bf16 v[44:47], v[162:165], v[180:183], v[44:47]
	v_mfma_f32_16x16x32_bf16 v[44:47], v[166:169], v[184:187], v[44:47]
	v_mfma_f32_16x16x32_bf16 v[40:43], v[170:173], v[180:183], v[40:43]
	v_mfma_f32_16x16x32_bf16 v[40:43], v[176:179], v[184:187], v[40:43]
	v_mfma_f32_16x16x32_bf16 v[28:31], v[162:165], v[188:191], v[28:31]
	v_mfma_f32_16x16x32_bf16 v[28:31], v[166:169], v[192:195], v[28:31]
	v_mfma_f32_16x16x32_bf16 v[24:27], v[170:173], v[188:191], v[24:27]
	v_mfma_f32_16x16x32_bf16 v[24:27], v[176:179], v[192:195], v[24:27]
	v_mfma_f32_16x16x32_bf16 v[12:15], v[162:165], v[196:199], v[12:15]
	v_mfma_f32_16x16x32_bf16 v[12:15], v[166:169], v[200:203], v[12:15]
	v_mfma_f32_16x16x32_bf16 v[8:11], v[170:173], v[196:199], v[8:11]
	v_mfma_f32_16x16x32_bf16 v[8:11], v[176:179], v[200:203], v[8:11]
	v_mfma_f32_16x16x32_bf16 v[4:7], v[162:165], v[204:207], v[4:7]
	v_mfma_f32_16x16x32_bf16 v[4:7], v[166:169], v[208:211], v[4:7]
	v_mfma_f32_16x16x32_bf16 v[0:3], v[170:173], v[204:207], v[0:3]
	v_mfma_f32_16x16x32_bf16 v[0:3], v[176:179], v[208:211], v[0:3]
	s_barrier
	s_add_i32 s81, 0, 0x18000
	v_add_u32_e32 v145, s81, v140
	s_add_i32 s82, 0, 0x1c000
	ds_read_b128 v[146:149], v145
	ds_read_b128 v[150:153], v145 offset:1024
	ds_read_b128 v[154:157], v145 offset:2048
	ds_read_b128 v[158:161], v145 offset:3072
	v_add_u32_e32 v145, s82, v140
	ds_read_b128 v[162:165], v145
	ds_read_b128 v[166:169], v145 offset:1024
	ds_read_b128 v[170:173], v145 offset:2048
	ds_read_b128 v[176:179], v145 offset:3072
	s_add_u32 s68, s68, 0x80000
	s_addc_u32 s69, s69, 0
	s_mov_b32 m0, s23
	ds_read_b128 v[180:183], v143 offset:32768
	ds_read_b128 v[184:187], v143 offset:33792
	ds_read_b128 v[188:191], v143 offset:34816
	ds_read_b128 v[192:195], v143 offset:35840
	ds_read_b128 v[196:199], v143 offset:36864
	ds_read_b128 v[200:203], v143 offset:37888
	ds_read_b128 v[204:207], v143 offset:38912
	ds_read_b128 v[208:211], v143 offset:39936
	global_load_lds_dwordx4 v134, s[68:69]
	s_mov_b32 m0, s33
	s_nop 0
	global_load_lds_dwordx4 v130, s[68:69]
	s_waitcnt vmcnt(8)
	s_waitcnt lgkmcnt(0)
	s_barrier
	s_waitcnt lgkmcnt(0)
	v_mfma_f32_16x16x32_bf16 v[124:127], v[146:149], v[180:183], v[124:127]
	v_mfma_f32_16x16x32_bf16 v[124:127], v[150:153], v[184:187], v[124:127]
	v_mfma_f32_16x16x32_bf16 v[120:123], v[154:157], v[180:183], v[120:123]
	v_mfma_f32_16x16x32_bf16 v[120:123], v[158:161], v[184:187], v[120:123]
	v_mfma_f32_16x16x32_bf16 v[116:119], v[146:149], v[188:191], v[116:119]
	v_mfma_f32_16x16x32_bf16 v[116:119], v[150:153], v[192:195], v[116:119]
	v_mfma_f32_16x16x32_bf16 v[112:115], v[154:157], v[188:191], v[112:115]
	v_mfma_f32_16x16x32_bf16 v[112:115], v[158:161], v[192:195], v[112:115]
	v_mfma_f32_16x16x32_bf16 v[100:103], v[146:149], v[196:199], v[100:103]
	v_mfma_f32_16x16x32_bf16 v[100:103], v[150:153], v[200:203], v[100:103]
	v_mfma_f32_16x16x32_bf16 v[96:99], v[154:157], v[196:199], v[96:99]
	v_mfma_f32_16x16x32_bf16 v[96:99], v[158:161], v[200:203], v[96:99]
	v_mfma_f32_16x16x32_bf16 v[84:87], v[146:149], v[204:207], v[84:87]
	v_mfma_f32_16x16x32_bf16 v[84:87], v[150:153], v[208:211], v[84:87]
	v_mfma_f32_16x16x32_bf16 v[80:83], v[154:157], v[204:207], v[80:83]
	v_mfma_f32_16x16x32_bf16 v[80:83], v[158:161], v[208:211], v[80:83]
	v_mfma_f32_16x16x32_bf16 v[108:111], v[162:165], v[180:183], v[108:111]
	v_mfma_f32_16x16x32_bf16 v[108:111], v[166:169], v[184:187], v[108:111]
	v_mfma_f32_16x16x32_bf16 v[104:107], v[170:173], v[180:183], v[104:107]
	v_mfma_f32_16x16x32_bf16 v[104:107], v[176:179], v[184:187], v[104:107]
	v_mfma_f32_16x16x32_bf16 v[92:95], v[162:165], v[188:191], v[92:95]
	v_mfma_f32_16x16x32_bf16 v[92:95], v[166:169], v[192:195], v[92:95]
	v_mfma_f32_16x16x32_bf16 v[88:91], v[170:173], v[188:191], v[88:91]
	v_mfma_f32_16x16x32_bf16 v[88:91], v[176:179], v[192:195], v[88:91]
	v_mfma_f32_16x16x32_bf16 v[76:79], v[162:165], v[196:199], v[76:79]
	v_mfma_f32_16x16x32_bf16 v[76:79], v[166:169], v[200:203], v[76:79]
	v_mfma_f32_16x16x32_bf16 v[72:75], v[170:173], v[196:199], v[72:75]
	v_mfma_f32_16x16x32_bf16 v[72:75], v[176:179], v[200:203], v[72:75]
	v_mfma_f32_16x16x32_bf16 v[68:71], v[162:165], v[204:207], v[68:71]
	v_mfma_f32_16x16x32_bf16 v[68:71], v[166:169], v[208:211], v[68:71]
	v_mfma_f32_16x16x32_bf16 v[64:67], v[170:173], v[204:207], v[64:67]
	v_mfma_f32_16x16x32_bf16 v[64:67], v[176:179], v[208:211], v[64:67]
	s_barrier
	s_add_i32 s68, s81, s6
	s_mov_b32 m0, s68
	ds_read_b128 v[180:183], v143 offset:49152
	ds_read_b128 v[184:187], v143 offset:50176
	ds_read_b128 v[188:191], v143 offset:51200
	ds_read_b128 v[192:195], v143 offset:52224
	ds_read_b128 v[196:199], v143 offset:53248
	ds_read_b128 v[200:203], v143 offset:54272
	ds_read_b128 v[204:207], v143 offset:55296
	ds_read_b128 v[208:211], v143 offset:56320
	global_load_lds_dwordx4 v132, s[98:99]
	s_add_i32 m0, s68, 0x2000
	s_add_u32 s48, s48, 0x80080
	s_addc_u32 s49, s49, 0
	s_add_i32 s68, s82, s6
	global_load_lds_dwordx4 v128, s[98:99]
	s_mov_b32 m0, s68
	s_nop 0
	global_load_lds_dwordx4 v132, s[48:49]
	s_add_i32 m0, s68, 0x2000
	s_nop 0
	global_load_lds_dwordx4 v128, s[48:49]
	s_mov_b32 m0, s41
	s_nop 0
	global_load_lds_dwordx4 v134, s[100:101]
	s_mov_b32 m0, s44
	s_nop 0
	global_load_lds_dwordx4 v130, s[100:101]
	s_waitcnt vmcnt(8)
	s_waitcnt lgkmcnt(0)
	s_barrier
	s_waitcnt lgkmcnt(0)
	v_mfma_f32_16x16x32_bf16 v[60:63], v[146:149], v[180:183], v[60:63]
	v_mfma_f32_16x16x32_bf16 v[60:63], v[150:153], v[184:187], v[60:63]
	v_mfma_f32_16x16x32_bf16 v[56:59], v[154:157], v[180:183], v[56:59]
	v_mfma_f32_16x16x32_bf16 v[56:59], v[158:161], v[184:187], v[56:59]
	v_mfma_f32_16x16x32_bf16 v[52:55], v[146:149], v[188:191], v[52:55]
	v_mfma_f32_16x16x32_bf16 v[52:55], v[150:153], v[192:195], v[52:55]
	v_mfma_f32_16x16x32_bf16 v[48:51], v[154:157], v[188:191], v[48:51]
	v_mfma_f32_16x16x32_bf16 v[48:51], v[158:161], v[192:195], v[48:51]
	v_mfma_f32_16x16x32_bf16 v[36:39], v[146:149], v[196:199], v[36:39]
	v_mfma_f32_16x16x32_bf16 v[36:39], v[150:153], v[200:203], v[36:39]
	v_mfma_f32_16x16x32_bf16 v[32:35], v[154:157], v[196:199], v[32:35]
	v_mfma_f32_16x16x32_bf16 v[32:35], v[158:161], v[200:203], v[32:35]
	v_mfma_f32_16x16x32_bf16 v[20:23], v[146:149], v[204:207], v[20:23]
	v_mfma_f32_16x16x32_bf16 v[20:23], v[150:153], v[208:211], v[20:23]
	v_mfma_f32_16x16x32_bf16 v[16:19], v[154:157], v[204:207], v[16:19]
	v_mfma_f32_16x16x32_bf16 v[16:19], v[158:161], v[208:211], v[16:19]
	v_mfma_f32_16x16x32_bf16 v[44:47], v[162:165], v[180:183], v[44:47]
	v_mfma_f32_16x16x32_bf16 v[44:47], v[166:169], v[184:187], v[44:47]
	v_mfma_f32_16x16x32_bf16 v[40:43], v[170:173], v[180:183], v[40:43]
	v_mfma_f32_16x16x32_bf16 v[40:43], v[176:179], v[184:187], v[40:43]
	v_mfma_f32_16x16x32_bf16 v[28:31], v[162:165], v[188:191], v[28:31]
	v_mfma_f32_16x16x32_bf16 v[28:31], v[166:169], v[192:195], v[28:31]
	v_mfma_f32_16x16x32_bf16 v[24:27], v[170:173], v[188:191], v[24:27]
	v_mfma_f32_16x16x32_bf16 v[24:27], v[176:179], v[192:195], v[24:27]
	v_mfma_f32_16x16x32_bf16 v[12:15], v[162:165], v[196:199], v[12:15]
	v_mfma_f32_16x16x32_bf16 v[12:15], v[166:169], v[200:203], v[12:15]
	v_mfma_f32_16x16x32_bf16 v[8:11], v[170:173], v[196:199], v[8:11]
	v_mfma_f32_16x16x32_bf16 v[8:11], v[176:179], v[200:203], v[8:11]
	v_mfma_f32_16x16x32_bf16 v[4:7], v[162:165], v[204:207], v[4:7]
	v_mfma_f32_16x16x32_bf16 v[4:7], v[166:169], v[208:211], v[4:7]
	v_mfma_f32_16x16x32_bf16 v[0:3], v[170:173], v[204:207], v[0:3]
	v_mfma_f32_16x16x32_bf16 v[0:3], v[176:179], v[208:211], v[0:3]
	s_barrier
	s_add_i32 s80, s80, 2
	s_add_u32 s46, s46, 0x100
	s_addc_u32 s47, s47, 0
	s_add_u32 s27, s27, 0x100
	s_addc_u32 s79, s79, 0
	s_cmp_gt_u32 s80, 5
	s_cbranch_scc0 .LBB0_273
	s_and_b64 vcc, exec, s[20:21]
	s_cbranch_vccz .LBB0_276
	s_barrier

.LBB0_401:
	v_mov_b32_e32 v9, v174
	s_cmpk_gt_i32 s2, 0x7f
	v_readfirstlane_b32 s6, v9
	s_cbranch_scc1 .LBB0_421
	v_lshlrev_b32_e32 v0, 4, v9
	v_add_u32_e32 v1, 0x2000, v0
	v_ashrrev_i32_e32 v2, 31, v1
	v_lshrrev_b32_e32 v2, 22, v2
	v_add_u32_e32 v2, v1, v2
	v_ashrrev_i32_e32 v8, 10, v2
	v_mul_i32_i24_e32 v2, 0x400, v8
	v_sub_u32_e32 v1, v1, v2
	v_lshrrev_b32_e32 v2, 4, v1
	v_bitop3_b32 v1, v2, v1, 32 bitop3:0x6c
	v_ashrrev_i32_e32 v2, 31, v1
	v_lshrrev_b32_e32 v2, 26, v2
	v_add_u32_e32 v2, v1, v2
	v_lshlrev_b32_e32 v3, 3, v8
	v_ashrrev_i32_e32 v10, 6, v2
	v_and_b32_e32 v3, -16, v3
	v_add_u32_e32 v3, v10, v3
	v_and_b32_e32 v4, 3, v10
	s_mov_b32 s8, 0xfffe0
	v_lshrrev_b32_e32 v5, 2, v3
	v_lshlrev_b32_e32 v6, 1, v3
	v_and_b32_e32 v2, 0xc0, v2
	v_and_or_b32 v4, v3, s8, v4
	v_and_b32_e32 v5, 4, v5
	v_and_b32_e32 v6, 24, v6
	v_sub_u32_e32 v1, v1, v2
	v_mov_b32_e32 v2, 1
	v_or3_b32 v4, v4, v5, v6
	v_lshlrev_b32_e32 v5, 5, v8
	v_ashrrev_i16_sdwa v1, v2, sext(v1) dst_sel:DWORD dst_unused:UNUSED_PAD src0_sel:DWORD src1_sel:BYTE_0
	v_and_b32_e32 v5, 32, v5
	v_bfe_i32 v11, v1, 0, 16
	v_add_lshl_u32 v1, v5, v11, 1
	v_lshl_add_u32 v128, v4, 12, v1
	v_lshl_add_u32 v130, v3, 12, v1
	v_bfe_i32 v1, v9, 27, 1
	v_lshrrev_b32_e32 v1, 22, v1
	v_add_u32_e32 v1, v0, v1
	v_and_b32_e32 v1, 0xfffffc00, v1
	v_sub_u32_e32 v0, v0, v1
	v_lshrrev_b32_e32 v1, 4, v0
	v_ashrrev_i32_e32 v3, 31, v9
	v_bitop3_b32 v0, v1, v0, 32 bitop3:0x6c
	v_lshrrev_b32_e32 v3, 26, v3
	v_ashrrev_i32_e32 v1, 31, v0
	v_add_u32_e32 v3, v9, v3
	v_lshrrev_b32_e32 v1, 26, v1
	v_ashrrev_i32_e32 v13, 6, v3
	v_add_u32_e32 v1, v0, v1
	v_lshlrev_b32_e32 v3, 3, v13
	v_ashrrev_i32_e32 v12, 6, v1
	v_and_b32_e32 v3, -16, v3
	v_add_u32_e32 v3, v12, v3
	v_and_b32_e32 v4, 3, v12
	v_and_or_b32 v4, v3, s8, v4
	s_ashr_i32 s8, s2, 3
	s_ashr_i32 s7, s6, 6
	s_and_b32 s9, s8, -4
	s_lshl_b32 s8, s8, 18
	s_ashr_i32 s24, s6, 8
	s_lshl_b32 s10, s7, 10
	s_or_b32 s80, s9, s90
	s_and_b32 s79, s2, 7
	s_and_b32 s9, s2, 0x8000
	s_and_b32 s8, s8, 0x3ff00000
	s_add_u32 s8, s11, s8
	s_addc_u32 s22, s1, 0
	s_lshl_b32 s23, s90, 10
	s_add_u32 s8, s8, s23
	s_addc_u32 s25, s22, 0
	s_lshl_b32 s22, s79, 20
	s_add_u32 s33, s73, s22
	s_addc_u32 s36, s74, 0
	s_add_u32 s22, s75, s22
	s_addc_u32 s37, s76, 0
	s_add_u32 s23, s22, s23
	s_addc_u32 s37, s37, 0
	s_add_i32 s22, s10, 0
	s_add_i32 m0, s22, 0x10000
	s_add_i32 s38, s22, 0x12000
	s_lshl_b32 s39, s80, 20
	v_lshrrev_b32_e32 v5, 2, v3
	v_lshlrev_b32_e32 v6, 1, v3
	v_and_b32_e32 v1, 0xc0, v1
	s_add_u32 s39, s34, s39
	v_and_b32_e32 v5, 4, v5
	v_and_b32_e32 v6, 24, v6
	v_sub_u32_e32 v0, v0, v1
	s_addc_u32 s40, s35, 0
	s_lshl_b32 s41, s79, 9
	v_or3_b32 v4, v4, v5, v6
	v_lshlrev_b32_e32 v5, 5, v13
	v_ashrrev_i16_sdwa v0, v2, sext(v0) dst_sel:DWORD dst_unused:UNUSED_PAD src0_sel:DWORD src1_sel:BYTE_0
	s_add_u32 s39, s39, s41
	v_and_b32_e32 v5, 32, v5
	v_bfe_i32 v14, v0, 0, 16
	s_addc_u32 s40, s40, 0
	v_add_lshl_u32 v0, v5, v14, 1
	s_cmp_eq_u32 s9, 0
	v_lshl_add_u32 v132, v4, 12, v0
	s_cselect_b32 s47, s37, s36
	s_cselect_b32 s46, s23, s33
	global_load_lds_dwordx4 v132, s[46:47]
	s_mov_b32 m0, s38
	s_cselect_b32 s44, s8, s39
	s_cselect_b32 s45, s25, s40
	s_add_u32 s8, s46, 0x80000
	global_load_lds_dwordx4 v128, s[46:47]
	s_addc_u32 s9, s47, 0
	s_add_i32 m0, s22, 0x14000
	s_add_i32 s23, s22, 0x2000
	global_load_lds_dwordx4 v132, s[8:9]
	s_add_i32 m0, s22, 0x16000
	v_lshl_add_u32 v134, v3, 12, v0
	global_load_lds_dwordx4 v128, s[8:9]
	s_mov_b32 m0, s22
	s_add_u32 s8, s44, 0x80000
	global_load_lds_dwordx4 v134, s[44:45]
	s_mov_b32 m0, s23
	s_addc_u32 s9, s45, 0
	s_add_i32 s33, s22, 0x4000
	global_load_lds_dwordx4 v130, s[44:45]
	s_mov_b32 m0, s33
	s_add_i32 s50, s22, 0x6000
	global_load_lds_dwordx4 v134, s[8:9]
	s_mov_b32 m0, s50
	v_mov_b32_e32 v133, 0
	global_load_lds_dwordx4 v130, s[8:9]
	v_mov_b32_e32 v129, v133
	v_mov_b32_e32 v135, v133
	v_mov_b32_e32 v131, v133
	s_cmp_eq_u32 s24, 1
	s_mov_b32 s51, 0
	v_lshl_add_u64 v[6:7], s[46:47], 0, v[132:133]
	v_lshl_add_u64 v[2:3], s[46:47], 0, v[128:129]
	v_lshl_add_u64 v[0:1], s[44:45], 0, v[134:135]
	s_cselect_b64 s[8:9], -1, 0
	s_cmp_lg_u32 s24, 1
	v_lshl_add_u64 v[4:5], s[44:45], 0, v[130:131]
	s_cbranch_scc1 .LBB0_404
	s_barrier
	s_setprio 1

.LBB0_414:
	ds_read_b128 v[146:149], v141
	ds_read_b128 v[150:153], v141 offset:1024
	ds_read_b128 v[154:157], v141 offset:2048
	ds_read_b128 v[158:161], v141 offset:3072
	ds_read_b128 v[162:165], v142
	ds_read_b128 v[166:169], v142 offset:1024
	ds_read_b128 v[170:173], v142 offset:2048
	ds_read_b128 v[176:179], v142 offset:3072
	s_add_u32 s46, s44, 0xfff80080
	s_addc_u32 s47, s45, -1
	s_cmp_eq_u32 s82, 4
	s_cselect_b32 s49, s41, s47
	s_cselect_b32 s48, s40, s46
	s_cselect_b32 s47, s43, s81
	s_cselect_b32 s46, s42, s39
	s_mov_b32 m0, s64
	ds_read_b128 v[180:183], v143
	ds_read_b128 v[184:187], v143 offset:1024
	ds_read_b128 v[188:191], v143 offset:2048
	ds_read_b128 v[192:195], v143 offset:3072
	ds_read_b128 v[196:199], v143 offset:4096
	ds_read_b128 v[200:203], v143 offset:5120
	ds_read_b128 v[204:207], v143 offset:6144
	ds_read_b128 v[208:211], v143 offset:7168
	global_load_lds_dwordx4 v136, s[44:45]
	s_mov_b32 m0, s65
	s_nop 0
	global_load_lds_dwordx4 v138, s[44:45]
	s_waitcnt vmcnt(8)
	s_waitcnt lgkmcnt(0)
	s_barrier
	s_waitcnt lgkmcnt(0)
	v_mfma_f32_16x16x32_bf16 v[124:127], v[146:149], v[180:183], v[124:127]
	v_mfma_f32_16x16x32_bf16 v[124:127], v[150:153], v[184:187], v[124:127]
	v_mfma_f32_16x16x32_bf16 v[120:123], v[154:157], v[180:183], v[120:123]
	v_mfma_f32_16x16x32_bf16 v[120:123], v[158:161], v[184:187], v[120:123]
	v_mfma_f32_16x16x32_bf16 v[116:119], v[146:149], v[188:191], v[116:119]
	v_mfma_f32_16x16x32_bf16 v[116:119], v[150:153], v[192:195], v[116:119]
	v_mfma_f32_16x16x32_bf16 v[112:115], v[154:157], v[188:191], v[112:115]
	v_mfma_f32_16x16x32_bf16 v[112:115], v[158:161], v[192:195], v[112:115]
	v_mfma_f32_16x16x32_bf16 v[100:103], v[146:149], v[196:199], v[100:103]
	v_mfma_f32_16x16x32_bf16 v[100:103], v[150:153], v[200:203], v[100:103]
	v_mfma_f32_16x16x32_bf16 v[96:99], v[154:157], v[196:199], v[96:99]
	v_mfma_f32_16x16x32_bf16 v[96:99], v[158:161], v[200:203], v[96:99]
	v_mfma_f32_16x16x32_bf16 v[84:87], v[146:149], v[204:207], v[84:87]
	v_mfma_f32_16x16x32_bf16 v[84:87], v[150:153], v[208:211], v[84:87]
	v_mfma_f32_16x16x32_bf16 v[80:83], v[154:157], v[204:207], v[80:83]
	v_mfma_f32_16x16x32_bf16 v[80:83], v[158:161], v[208:211], v[80:83]
	v_mfma_f32_16x16x32_bf16 v[108:111], v[162:165], v[180:183], v[108:111]
	v_mfma_f32_16x16x32_bf16 v[108:111], v[166:169], v[184:187], v[108:111]
	v_mfma_f32_16x16x32_bf16 v[104:107], v[170:173], v[180:183], v[104:107]
	v_mfma_f32_16x16x32_bf16 v[104:107], v[176:179], v[184:187], v[104:107]
	v_mfma_f32_16x16x32_bf16 v[92:95], v[162:165], v[188:191], v[92:95]
	v_mfma_f32_16x16x32_bf16 v[92:95], v[166:169], v[192:195], v[92:95]
	v_mfma_f32_16x16x32_bf16 v[88:91], v[170:173], v[188:191], v[88:91]
	v_mfma_f32_16x16x32_bf16 v[88:91], v[176:179], v[192:195], v[88:91]
	v_mfma_f32_16x16x32_bf16 v[76:79], v[162:165], v[196:199], v[76:79]
	v_mfma_f32_16x16x32_bf16 v[76:79], v[166:169], v[200:203], v[76:79]
	v_mfma_f32_16x16x32_bf16 v[72:75], v[170:173], v[196:199], v[72:75]
	v_mfma_f32_16x16x32_bf16 v[72:75], v[176:179], v[200:203], v[72:75]
	v_mfma_f32_16x16x32_bf16 v[68:71], v[162:165], v[204:207], v[68:71]
	v_mfma_f32_16x16x32_bf16 v[68:71], v[166:169], v[208:211], v[68:71]
	v_mfma_f32_16x16x32_bf16 v[64:67], v[170:173], v[204:207], v[64:67]
	v_mfma_f32_16x16x32_bf16 v[64:67], v[176:179], v[208:211], v[64:67]
	s_barrier
	s_mov_b32 m0, s68
	s_add_u32 s98, s46, s24
	s_addc_u32 s99, s47, s25
	s_add_u32 s84, s46, 0x80000
	ds_read_b128 v[180:183], v143 offset:16384
	ds_read_b128 v[184:187], v143 offset:17408
	ds_read_b128 v[188:191], v143 offset:18432
	ds_read_b128 v[192:195], v143 offset:19456
	ds_read_b128 v[196:199], v143 offset:20480
	ds_read_b128 v[200:203], v143 offset:21504
	ds_read_b128 v[204:207], v143 offset:22528
	ds_read_b128 v[208:211], v143 offset:23552
	global_load_lds_dwordx4 v132, s[46:47]
	s_mov_b32 m0, s69
	s_addc_u32 s85, s47, 0
	global_load_lds_dwordx4 v128, s[46:47]
	s_mov_b32 m0, s77
	s_nop 0
	global_load_lds_dwordx4 v132, s[84:85]
	s_add_i32 m0, s77, 0x2000
	s_nop 0
	global_load_lds_dwordx4 v128, s[84:85]
	s_add_u32 s100, s48, s24
	s_addc_u32 s101, s49, s25
	s_mov_b32 m0, s22
	s_nop 0
	global_load_lds_dwordx4 v134, s[48:49]
	s_mov_b32 m0, s23
	s_nop 0
	global_load_lds_dwordx4 v130, s[48:49]
	s_waitcnt vmcnt(8)
	s_waitcnt lgkmcnt(0)
	s_barrier
	s_waitcnt lgkmcnt(0)
	v_mfma_f32_16x16x32_bf16 v[60:63], v[146:149], v[180:183], v[60:63]
	v_mfma_f32_16x16x32_bf16 v[60:63], v[150:153], v[184:187], v[60:63]
	v_mfma_f32_16x16x32_bf16 v[56:59], v[154:157], v[180:183], v[56:59]
	v_mfma_f32_16x16x32_bf16 v[56:59], v[158:161], v[184:187], v[56:59]
	v_mfma_f32_16x16x32_bf16 v[52:55], v[146:149], v[188:191], v[52:55]
	v_mfma_f32_16x16x32_bf16 v[52:55], v[150:153], v[192:195], v[52:55]
	v_mfma_f32_16x16x32_bf16 v[48:51], v[154:157], v[188:191], v[48:51]
	v_mfma_f32_16x16x32_bf16 v[48:51], v[158:161], v[192:195], v[48:51]
	v_mfma_f32_16x16x32_bf16 v[36:39], v[146:149], v[196:199], v[36:39]
	v_mfma_f32_16x16x32_bf16 v[36:39], v[150:153], v[200:203], v[36:39]
	v_mfma_f32_16x16x32_bf16 v[32:35], v[154:157], v[196:199], v[32:35]
	v_mfma_f32_16x16x32_bf16 v[32:35], v[158:161], v[200:203], v[32:35]
	v_mfma_f32_16x16x32_bf16 v[20:23], v[146:149], v[204:207], v[20:23]
	v_mfma_f32_16x16x32_bf16 v[20:23], v[150:153], v[208:211], v[20:23]
	v_mfma_f32_16x16x32_bf16 v[16:19], v[154:157], v[204:207], v[16:19]
	v_mfma_f32_16x16x32_bf16 v[16:19], v[158:161], v[208:211], v[16:19]
	v_mfma_f32_16x16x32_bf16 v[44:47], v[162:165], v[180:183], v[44:47]
	v_mfma_f32_16x16x32_bf16 v[44:47], v[166:169], v[184:187], v[44:47]
	v_mfma_f32_16x16x32_bf16 v[40:43], v[170:173], v[180:183], v[40:43]
	v_mfma_f32_16x16x32_bf16 v[40:43], v[176:179], v[184:187], v[40:43]
	v_mfma_f32_16x16x32_bf16 v[28:31], v[162:165], v[188:191], v[28:31]
	v_mfma_f32_16x16x32_bf16 v[28:31], v[166:169], v[192:195], v[28:31]
	v_mfma_f32_16x16x32_bf16 v[24:27], v[170:173], v[188:191], v[24:27]
	v_mfma_f32_16x16x32_bf16 v[24:27], v[176:179], v[192:195], v[24:27]
	v_mfma_f32_16x16x32_bf16 v[12:15], v[162:165], v[196:199], v[12:15]
	v_mfma_f32_16x16x32_bf16 v[12:15], v[166:169], v[200:203], v[12:15]
	v_mfma_f32_16x16x32_bf16 v[8:11], v[170:173], v[196:199], v[8:11]
	v_mfma_f32_16x16x32_bf16 v[8:11], v[176:179], v[200:203], v[8:11]
	v_mfma_f32_16x16x32_bf16 v[4:7], v[162:165], v[204:207], v[4:7]
	v_mfma_f32_16x16x32_bf16 v[4:7], v[166:169], v[208:211], v[4:7]
	v_mfma_f32_16x16x32_bf16 v[0:3], v[170:173], v[204:207], v[0:3]
	v_mfma_f32_16x16x32_bf16 v[0:3], v[176:179], v[208:211], v[0:3]
	s_barrier
	s_add_i32 s83, 0, 0x18000
	v_add_u32_e32 v145, s83, v140
	s_add_i32 s84, 0, 0x1c000
	ds_read_b128 v[146:149], v145
	ds_read_b128 v[150:153], v145 offset:1024
	ds_read_b128 v[154:157], v145 offset:2048
	ds_read_b128 v[158:161], v145 offset:3072
	v_add_u32_e32 v145, s84, v140
	ds_read_b128 v[162:165], v145
	ds_read_b128 v[166:169], v145 offset:1024
	ds_read_b128 v[170:173], v145 offset:2048
	ds_read_b128 v[176:179], v145 offset:3072
	s_add_u32 s48, s48, 0x80000
	s_addc_u32 s49, s49, 0
	s_mov_b32 m0, s33
	ds_read_b128 v[180:183], v143 offset:32768
	ds_read_b128 v[184:187], v143 offset:33792
	ds_read_b128 v[188:191], v143 offset:34816
	ds_read_b128 v[192:195], v143 offset:35840
	ds_read_b128 v[196:199], v143 offset:36864
	ds_read_b128 v[200:203], v143 offset:37888
	ds_read_b128 v[204:207], v143 offset:38912
	ds_read_b128 v[208:211], v143 offset:39936
	global_load_lds_dwordx4 v134, s[48:49]
	s_mov_b32 m0, s50
	s_nop 0
	global_load_lds_dwordx4 v130, s[48:49]
	s_waitcnt vmcnt(8)
	s_waitcnt lgkmcnt(0)
	s_barrier
	s_waitcnt lgkmcnt(0)
	v_mfma_f32_16x16x32_bf16 v[124:127], v[146:149], v[180:183], v[124:127]
	v_mfma_f32_16x16x32_bf16 v[124:127], v[150:153], v[184:187], v[124:127]
	v_mfma_f32_16x16x32_bf16 v[120:123], v[154:157], v[180:183], v[120:123]
	v_mfma_f32_16x16x32_bf16 v[120:123], v[158:161], v[184:187], v[120:123]
	v_mfma_f32_16x16x32_bf16 v[116:119], v[146:149], v[188:191], v[116:119]
	v_mfma_f32_16x16x32_bf16 v[116:119], v[150:153], v[192:195], v[116:119]
	v_mfma_f32_16x16x32_bf16 v[112:115], v[154:157], v[188:191], v[112:115]
	v_mfma_f32_16x16x32_bf16 v[112:115], v[158:161], v[192:195], v[112:115]
	v_mfma_f32_16x16x32_bf16 v[100:103], v[146:149], v[196:199], v[100:103]
	v_mfma_f32_16x16x32_bf16 v[100:103], v[150:153], v[200:203], v[100:103]
	v_mfma_f32_16x16x32_bf16 v[96:99], v[154:157], v[196:199], v[96:99]
	v_mfma_f32_16x16x32_bf16 v[96:99], v[158:161], v[200:203], v[96:99]
	v_mfma_f32_16x16x32_bf16 v[84:87], v[146:149], v[204:207], v[84:87]
	v_mfma_f32_16x16x32_bf16 v[84:87], v[150:153], v[208:211], v[84:87]
	v_mfma_f32_16x16x32_bf16 v[80:83], v[154:157], v[204:207], v[80:83]
	v_mfma_f32_16x16x32_bf16 v[80:83], v[158:161], v[208:211], v[80:83]
	v_mfma_f32_16x16x32_bf16 v[108:111], v[162:165], v[180:183], v[108:111]
	v_mfma_f32_16x16x32_bf16 v[108:111], v[166:169], v[184:187], v[108:111]
	v_mfma_f32_16x16x32_bf16 v[104:107], v[170:173], v[180:183], v[104:107]
	v_mfma_f32_16x16x32_bf16 v[104:107], v[176:179], v[184:187], v[104:107]
	v_mfma_f32_16x16x32_bf16 v[92:95], v[162:165], v[188:191], v[92:95]
	v_mfma_f32_16x16x32_bf16 v[92:95], v[166:169], v[192:195], v[92:95]
	v_mfma_f32_16x16x32_bf16 v[88:91], v[170:173], v[188:191], v[88:91]
	v_mfma_f32_16x16x32_bf16 v[88:91], v[176:179], v[192:195], v[88:91]
	v_mfma_f32_16x16x32_bf16 v[76:79], v[162:165], v[196:199], v[76:79]
	v_mfma_f32_16x16x32_bf16 v[76:79], v[166:169], v[200:203], v[76:79]
	v_mfma_f32_16x16x32_bf16 v[72:75], v[170:173], v[196:199], v[72:75]
	v_mfma_f32_16x16x32_bf16 v[72:75], v[176:179], v[200:203], v[72:75]
	v_mfma_f32_16x16x32_bf16 v[68:71], v[162:165], v[204:207], v[68:71]
	v_mfma_f32_16x16x32_bf16 v[68:71], v[166:169], v[208:211], v[68:71]
	v_mfma_f32_16x16x32_bf16 v[64:67], v[170:173], v[204:207], v[64:67]
	v_mfma_f32_16x16x32_bf16 v[64:67], v[176:179], v[208:211], v[64:67]
	s_barrier
	s_add_i32 s48, s83, s10
	s_mov_b32 m0, s48
	ds_read_b128 v[180:183], v143 offset:49152
	ds_read_b128 v[184:187], v143 offset:50176
	ds_read_b128 v[188:191], v143 offset:51200
	ds_read_b128 v[192:195], v143 offset:52224
	ds_read_b128 v[196:199], v143 offset:53248
	ds_read_b128 v[200:203], v143 offset:54272
	ds_read_b128 v[204:207], v143 offset:55296
	ds_read_b128 v[208:211], v143 offset:56320
	global_load_lds_dwordx4 v132, s[98:99]
	s_add_i32 m0, s48, 0x2000
	s_add_u32 s46, s46, 0x80080
	s_addc_u32 s47, s47, 0
	s_add_i32 s48, s84, s10
	global_load_lds_dwordx4 v128, s[98:99]
	s_mov_b32 m0, s48
	s_nop 0
	global_load_lds_dwordx4 v132, s[46:47]
	s_add_i32 m0, s48, 0x2000
	s_nop 0
	global_load_lds_dwordx4 v128, s[46:47]
	s_mov_b32 m0, s62
	s_nop 0
	global_load_lds_dwordx4 v134, s[100:101]
	s_mov_b32 m0, s63
	s_nop 0
	global_load_lds_dwordx4 v130, s[100:101]
	s_waitcnt vmcnt(8)
	s_waitcnt lgkmcnt(0)
	s_barrier
	s_waitcnt lgkmcnt(0)
	v_mfma_f32_16x16x32_bf16 v[60:63], v[146:149], v[180:183], v[60:63]
	v_mfma_f32_16x16x32_bf16 v[60:63], v[150:153], v[184:187], v[60:63]
	v_mfma_f32_16x16x32_bf16 v[56:59], v[154:157], v[180:183], v[56:59]
	v_mfma_f32_16x16x32_bf16 v[56:59], v[158:161], v[184:187], v[56:59]
	v_mfma_f32_16x16x32_bf16 v[52:55], v[146:149], v[188:191], v[52:55]
	v_mfma_f32_16x16x32_bf16 v[52:55], v[150:153], v[192:195], v[52:55]
	v_mfma_f32_16x16x32_bf16 v[48:51], v[154:157], v[188:191], v[48:51]
	v_mfma_f32_16x16x32_bf16 v[48:51], v[158:161], v[192:195], v[48:51]
	v_mfma_f32_16x16x32_bf16 v[36:39], v[146:149], v[196:199], v[36:39]
	v_mfma_f32_16x16x32_bf16 v[36:39], v[150:153], v[200:203], v[36:39]
	v_mfma_f32_16x16x32_bf16 v[32:35], v[154:157], v[196:199], v[32:35]
	v_mfma_f32_16x16x32_bf16 v[32:35], v[158:161], v[200:203], v[32:35]
	v_mfma_f32_16x16x32_bf16 v[20:23], v[146:149], v[204:207], v[20:23]
	v_mfma_f32_16x16x32_bf16 v[20:23], v[150:153], v[208:211], v[20:23]
	v_mfma_f32_16x16x32_bf16 v[16:19], v[154:157], v[204:207], v[16:19]
	v_mfma_f32_16x16x32_bf16 v[16:19], v[158:161], v[208:211], v[16:19]
	v_mfma_f32_16x16x32_bf16 v[44:47], v[162:165], v[180:183], v[44:47]
	v_mfma_f32_16x16x32_bf16 v[44:47], v[166:169], v[184:187], v[44:47]
	v_mfma_f32_16x16x32_bf16 v[40:43], v[170:173], v[180:183], v[40:43]
	v_mfma_f32_16x16x32_bf16 v[40:43], v[176:179], v[184:187], v[40:43]
	v_mfma_f32_16x16x32_bf16 v[28:31], v[162:165], v[188:191], v[28:31]
	v_mfma_f32_16x16x32_bf16 v[28:31], v[166:169], v[192:195], v[28:31]
	v_mfma_f32_16x16x32_bf16 v[24:27], v[170:173], v[188:191], v[24:27]
	v_mfma_f32_16x16x32_bf16 v[24:27], v[176:179], v[192:195], v[24:27]
	v_mfma_f32_16x16x32_bf16 v[12:15], v[162:165], v[196:199], v[12:15]
	v_mfma_f32_16x16x32_bf16 v[12:15], v[166:169], v[200:203], v[12:15]
	v_mfma_f32_16x16x32_bf16 v[8:11], v[170:173], v[196:199], v[8:11]
	v_mfma_f32_16x16x32_bf16 v[8:11], v[176:179], v[200:203], v[8:11]
	v_mfma_f32_16x16x32_bf16 v[4:7], v[162:165], v[204:207], v[4:7]
	v_mfma_f32_16x16x32_bf16 v[4:7], v[166:169], v[208:211], v[4:7]
	v_mfma_f32_16x16x32_bf16 v[0:3], v[170:173], v[204:207], v[0:3]
	v_mfma_f32_16x16x32_bf16 v[0:3], v[176:179], v[208:211], v[0:3]
	s_barrier
	s_add_i32 s82, s82, 2
	s_add_u32 s44, s44, 0x100
	s_addc_u32 s45, s45, 0
	s_add_u32 s39, s39, 0x100
	s_addc_u32 s81, s81, 0
	s_cmp_gt_u32 s82, 5
	s_cbranch_scc0 .LBB0_414
	s_and_b64 vcc, exec, s[36:37]
	s_cbranch_vccz .LBB0_417
	s_barrier

.LBB0_421:
	v_readlane_b32 s7, v240, 18
	s_lshr_b32 s1, s7, 25
	s_mul_i32 s1, s1, s15
	s_sub_i32 s1, 0x80, s1
	s_sub_i32 s6, s1, s15
	s_cmp_ge_u32 s1, s15
	s_cselect_b32 s1, s6, s1
	s_sub_i32 s6, s1, s15
	s_cmp_ge_u32 s1, s15
	s_cselect_b32 s1, s6, s1
	s_sub_i32 s1, s72, s1
	s_ashr_i32 s6, s1, 31
	s_abs_i32 s1, s1
	s_mul_hi_u32 s7, s1, s7
	s_mul_i32 s7, s7, s15
	s_sub_i32 s1, s1, s7
	s_sub_i32 s7, s1, s15
	s_cmp_ge_u32 s1, s15
	s_cselect_b32 s1, s7, s1
	s_sub_i32 s7, s1, s15
	s_cmp_ge_u32 s1, s15
	s_cselect_b32 s1, s7, s1
	s_xor_b32 s1, s1, s6
	s_sub_i32 s1, s1, s6
	s_add_u32 s24, s56, 0x17800000
	s_addc_u32 s25, s57, 0
	v_mov_b32_e32 v9, v174
	s_cmpk_gt_i32 s1, 0x7f
	v_readfirstlane_b32 s40, v9
	s_cbranch_scc1 .LBB0_435
	v_lshlrev_b32_e32 v0, 4, v9
	v_add_u32_e32 v1, 0x2000, v0
	v_ashrrev_i32_e32 v2, 31, v1
	v_lshrrev_b32_e32 v2, 22, v2
	v_add_u32_e32 v2, v1, v2
	v_ashrrev_i32_e32 v8, 10, v2
	v_mul_i32_i24_e32 v2, 0x400, v8
	v_sub_u32_e32 v1, v1, v2
	v_lshrrev_b32_e32 v2, 4, v1
	v_bitop3_b32 v1, v2, v1, 32 bitop3:0x6c
	v_ashrrev_i32_e32 v2, 31, v1
	v_lshrrev_b32_e32 v2, 26, v2
	v_add_u32_e32 v2, v1, v2
	v_lshlrev_b32_e32 v3, 3, v8
	v_ashrrev_i32_e32 v10, 6, v2
	v_and_b32_e32 v3, -16, v3
	v_add_u32_e32 v3, v10, v3
	v_and_b32_e32 v4, 3, v10
	s_mov_b32 s6, 0xfffe0
	v_lshrrev_b32_e32 v5, 2, v3
	v_lshlrev_b32_e32 v6, 1, v3
	v_and_b32_e32 v2, 0xc0, v2
	v_and_or_b32 v4, v3, s6, v4
	v_and_b32_e32 v5, 4, v5
	v_and_b32_e32 v6, 24, v6
	v_sub_u32_e32 v1, v1, v2
	v_mov_b32_e32 v2, 1
	v_or3_b32 v4, v4, v5, v6
	v_lshlrev_b32_e32 v5, 5, v8
	v_ashrrev_i16_sdwa v1, v2, sext(v1) dst_sel:DWORD dst_unused:UNUSED_PAD src0_sel:DWORD src1_sel:BYTE_0
	v_and_b32_e32 v5, 32, v5
	v_bfe_i32 v11, v1, 0, 16
	v_add_lshl_u32 v1, v5, v11, 1
	v_lshl_add_u32 v128, v4, 12, v1
	v_lshl_add_u32 v130, v3, 12, v1
	v_bfe_i32 v1, v9, 27, 1
	v_lshrrev_b32_e32 v1, 22, v1
	v_add_u32_e32 v1, v0, v1
	v_and_b32_e32 v1, 0xfffffc00, v1
	v_sub_u32_e32 v0, v0, v1
	v_lshrrev_b32_e32 v1, 4, v0
	v_ashrrev_i32_e32 v3, 31, v9
	v_bitop3_b32 v0, v1, v0, 32 bitop3:0x6c
	v_lshrrev_b32_e32 v3, 26, v3
	v_ashrrev_i32_e32 v1, 31, v0
	v_add_u32_e32 v3, v9, v3
	v_lshrrev_b32_e32 v1, 26, v1
	v_ashrrev_i32_e32 v13, 6, v3
	v_add_u32_e32 v1, v0, v1
	v_lshlrev_b32_e32 v3, 3, v13
	v_ashrrev_i32_e32 v12, 6, v1
	v_and_b32_e32 v3, -16, v3
	v_add_u32_e32 v3, v12, v3
	v_and_b32_e32 v4, 3, v12
	v_and_or_b32 v4, v3, s6, v4
	s_ashr_i32 s6, s1, 5
	s_ashr_i32 s39, s40, 6
	s_ashr_i32 s7, s6, 31
	s_ashr_i32 s41, s40, 8
	s_lshl_b32 s10, s39, 10
	s_and_b32 s11, s1, 3
	s_bfe_u32 s38, s1, 0x30002
	v_lshrrev_b32_e32 v5, 2, v3
	v_lshlrev_b32_e32 v6, 1, v3
	v_and_b32_e32 v1, 0xc0, v1
	s_lshl_b64 s[6:7], s[6:7], 20
	v_and_b32_e32 v5, 4, v5
	v_and_b32_e32 v6, 24, v6
	v_sub_u32_e32 v0, v0, v1
	s_add_u32 s6, s14, s6
	v_or3_b32 v4, v4, v5, v6
	v_lshlrev_b32_e32 v5, 5, v13
	v_ashrrev_i16_sdwa v0, v2, sext(v0) dst_sel:DWORD dst_unused:UNUSED_PAD src0_sel:DWORD src1_sel:BYTE_0
	s_addc_u32 s7, s0, s7
	s_lshl_b32 s22, s11, 10
	v_and_b32_e32 v5, 32, v5
	v_bfe_i32 v14, v0, 0, 16
	s_add_u32 s6, s6, s22
	v_add_lshl_u32 v0, v5, v14, 1
	s_addc_u32 s7, s7, 0
	s_add_i32 s15, s10, 0
	v_lshl_add_u32 v132, v4, 12, v0
	s_add_i32 m0, s15, 0x10000
	s_lshl_b32 s8, s38, 20
	global_load_lds_dwordx4 v132, s[6:7]
	s_add_i32 m0, s15, 0x12000
	s_add_u32 s23, s26, s8
	s_addc_u32 s33, s27, 0
	s_add_u32 s8, s6, 0x80000
	global_load_lds_dwordx4 v128, s[6:7]
	s_addc_u32 s9, s7, 0
	s_add_i32 m0, s15, 0x14000
	v_lshl_add_u32 v134, v3, 12, v0
	global_load_lds_dwordx4 v132, s[8:9]
	s_add_i32 m0, s15, 0x16000
	v_mov_b32_e32 v137, 0
	global_load_lds_dwordx4 v128, s[8:9]
	s_add_u32 s8, s23, s22
	s_addc_u32 s9, s33, 0
	s_add_i32 s22, s15, 0x2000
	s_mov_b32 m0, s15
	s_add_u32 s36, s8, 0x80000
	global_load_lds_dwordx4 v134, s[8:9]
	s_mov_b32 m0, s22
	s_addc_u32 s37, s9, 0
	s_add_i32 s23, s15, 0x4000
	global_load_lds_dwordx4 v130, s[8:9]
	s_mov_b32 m0, s23
	s_add_i32 s33, s15, 0x6000
	global_load_lds_dwordx4 v134, s[36:37]
	s_mov_b32 m0, s33
	v_mov_b32_e32 v133, v137
	global_load_lds_dwordx4 v130, s[36:37]
	v_mov_b32_e32 v129, v137
	v_mov_b32_e32 v135, v137
	v_mov_b32_e32 v131, v137
	s_cmp_eq_u32 s41, 1
	s_mov_b32 s60, 0
	v_lshl_add_u64 v[6:7], s[6:7], 0, v[132:133]
	v_lshl_add_u64 v[4:5], s[6:7], 0, v[128:129]
	v_lshl_add_u64 v[0:1], s[8:9], 0, v[134:135]
	s_cselect_b64 s[36:37], -1, 0
	s_cmp_lg_u32 s41, 1
	v_lshl_add_u64 v[2:3], s[8:9], 0, v[130:131]
	s_cbranch_scc1 .LBB0_424
	s_barrier
	s_setprio 1

.LBB0_428:
	ds_read_b128 v[148:151], v143
	ds_read_b128 v[152:155], v143 offset:1024
	ds_read_b128 v[156:159], v143 offset:2048
	ds_read_b128 v[160:163], v143 offset:3072
	ds_read_b128 v[164:167], v144
	ds_read_b128 v[168:171], v144 offset:1024
	ds_read_b128 v[176:179], v144 offset:2048
	ds_read_b128 v[180:183], v144 offset:3072
	s_add_u32 s48, s46, 0xfff80080
	s_addc_u32 s49, s47, -1
	s_cmp_eq_u32 s83, 4
	s_cselect_b32 s51, s77, s49
	s_cselect_b32 s50, s78, s48
	s_cselect_b32 s49, s79, s82
	s_cselect_b32 s48, s80, s81
	s_add_i32 m0, s15, 0xc000
	ds_read_b128 v[184:187], v145
	ds_read_b128 v[188:191], v145 offset:1024
	ds_read_b128 v[192:195], v145 offset:2048
	ds_read_b128 v[196:199], v145 offset:3072
	ds_read_b128 v[200:203], v145 offset:4096
	ds_read_b128 v[204:207], v145 offset:5120
	ds_read_b128 v[208:211], v145 offset:6144
	ds_read_b128 v[212:215], v145 offset:7168
	global_load_lds_dwordx4 v138, s[46:47]
	s_add_i32 m0, s15, 0xe000
	s_nop 0
	global_load_lds_dwordx4 v140, s[46:47]
	s_waitcnt vmcnt(8)
	s_waitcnt lgkmcnt(0)
	s_barrier
	s_waitcnt lgkmcnt(0)
	v_mfma_f32_16x16x32_bf16 v[124:127], v[148:151], v[184:187], v[124:127]
	v_mfma_f32_16x16x32_bf16 v[124:127], v[152:155], v[188:191], v[124:127]
	v_mfma_f32_16x16x32_bf16 v[120:123], v[156:159], v[184:187], v[120:123]
	v_mfma_f32_16x16x32_bf16 v[120:123], v[160:163], v[188:191], v[120:123]
	v_mfma_f32_16x16x32_bf16 v[116:119], v[148:151], v[192:195], v[116:119]
	v_mfma_f32_16x16x32_bf16 v[116:119], v[152:155], v[196:199], v[116:119]
	v_mfma_f32_16x16x32_bf16 v[112:115], v[156:159], v[192:195], v[112:115]
	v_mfma_f32_16x16x32_bf16 v[112:115], v[160:163], v[196:199], v[112:115]
	v_mfma_f32_16x16x32_bf16 v[100:103], v[148:151], v[200:203], v[100:103]
	v_mfma_f32_16x16x32_bf16 v[100:103], v[152:155], v[204:207], v[100:103]
	v_mfma_f32_16x16x32_bf16 v[96:99], v[156:159], v[200:203], v[96:99]
	v_mfma_f32_16x16x32_bf16 v[96:99], v[160:163], v[204:207], v[96:99]
	v_mfma_f32_16x16x32_bf16 v[84:87], v[148:151], v[208:211], v[84:87]
	v_mfma_f32_16x16x32_bf16 v[84:87], v[152:155], v[212:215], v[84:87]
	v_mfma_f32_16x16x32_bf16 v[80:83], v[156:159], v[208:211], v[80:83]
	v_mfma_f32_16x16x32_bf16 v[80:83], v[160:163], v[212:215], v[80:83]
	v_mfma_f32_16x16x32_bf16 v[108:111], v[164:167], v[184:187], v[108:111]
	v_mfma_f32_16x16x32_bf16 v[108:111], v[168:171], v[188:191], v[108:111]
	v_mfma_f32_16x16x32_bf16 v[104:107], v[176:179], v[184:187], v[104:107]
	v_mfma_f32_16x16x32_bf16 v[104:107], v[180:183], v[188:191], v[104:107]
	v_mfma_f32_16x16x32_bf16 v[92:95], v[164:167], v[192:195], v[92:95]
	v_mfma_f32_16x16x32_bf16 v[92:95], v[168:171], v[196:199], v[92:95]
	v_mfma_f32_16x16x32_bf16 v[88:91], v[176:179], v[192:195], v[88:91]
	v_mfma_f32_16x16x32_bf16 v[88:91], v[180:183], v[196:199], v[88:91]
	v_mfma_f32_16x16x32_bf16 v[76:79], v[164:167], v[200:203], v[76:79]
	v_mfma_f32_16x16x32_bf16 v[76:79], v[168:171], v[204:207], v[76:79]
	v_mfma_f32_16x16x32_bf16 v[72:75], v[176:179], v[200:203], v[72:75]
	v_mfma_f32_16x16x32_bf16 v[72:75], v[180:183], v[204:207], v[72:75]
	v_mfma_f32_16x16x32_bf16 v[68:71], v[164:167], v[208:211], v[68:71]
	v_mfma_f32_16x16x32_bf16 v[68:71], v[168:171], v[212:215], v[68:71]
	v_mfma_f32_16x16x32_bf16 v[64:67], v[176:179], v[208:211], v[64:67]
	v_mfma_f32_16x16x32_bf16 v[64:67], v[180:183], v[212:215], v[64:67]
	s_barrier
	s_add_i32 s84, s68, s10
	s_add_u32 s98, s48, s38
	s_addc_u32 s99, s49, s39
	s_mov_b32 m0, s84
	ds_read_b128 v[184:187], v145 offset:16384
	ds_read_b128 v[188:191], v145 offset:17408
	ds_read_b128 v[192:195], v145 offset:18432
	ds_read_b128 v[196:199], v145 offset:19456
	ds_read_b128 v[200:203], v145 offset:20480
	ds_read_b128 v[204:207], v145 offset:21504
	ds_read_b128 v[208:211], v145 offset:22528
	ds_read_b128 v[212:215], v145 offset:23552
	global_load_lds_dwordx4 v132, s[48:49]
	s_add_i32 m0, s84, 0x2000
	s_add_u32 s84, s48, 0x80000
	s_addc_u32 s85, s49, 0
	s_add_i32 s86, s69, s10
	global_load_lds_dwordx4 v128, s[48:49]
	s_mov_b32 m0, s86
	s_nop 0
	global_load_lds_dwordx4 v132, s[84:85]
	s_add_i32 m0, s86, 0x2000
	s_nop 0
	global_load_lds_dwordx4 v128, s[84:85]
	s_add_u32 s100, s50, s38
	s_addc_u32 s101, s51, s39
	s_mov_b32 m0, s15
	s_nop 0
	global_load_lds_dwordx4 v134, s[50:51]
	s_mov_b32 m0, s22
	s_nop 0
	global_load_lds_dwordx4 v130, s[50:51]
	s_waitcnt vmcnt(8)
	s_waitcnt lgkmcnt(0)
	s_barrier
	s_waitcnt lgkmcnt(0)
	v_mfma_f32_16x16x32_bf16 v[60:63], v[148:151], v[184:187], v[60:63]
	v_mfma_f32_16x16x32_bf16 v[60:63], v[152:155], v[188:191], v[60:63]
	v_mfma_f32_16x16x32_bf16 v[56:59], v[156:159], v[184:187], v[56:59]
	v_mfma_f32_16x16x32_bf16 v[56:59], v[160:163], v[188:191], v[56:59]
	v_mfma_f32_16x16x32_bf16 v[52:55], v[148:151], v[192:195], v[52:55]
	v_mfma_f32_16x16x32_bf16 v[52:55], v[152:155], v[196:199], v[52:55]
	v_mfma_f32_16x16x32_bf16 v[48:51], v[156:159], v[192:195], v[48:51]
	v_mfma_f32_16x16x32_bf16 v[48:51], v[160:163], v[196:199], v[48:51]
	v_mfma_f32_16x16x32_bf16 v[36:39], v[148:151], v[200:203], v[36:39]
	v_mfma_f32_16x16x32_bf16 v[36:39], v[152:155], v[204:207], v[36:39]
	v_mfma_f32_16x16x32_bf16 v[32:35], v[156:159], v[200:203], v[32:35]
	v_mfma_f32_16x16x32_bf16 v[32:35], v[160:163], v[204:207], v[32:35]
	v_mfma_f32_16x16x32_bf16 v[20:23], v[148:151], v[208:211], v[20:23]
	v_mfma_f32_16x16x32_bf16 v[20:23], v[152:155], v[212:215], v[20:23]
	v_mfma_f32_16x16x32_bf16 v[16:19], v[156:159], v[208:211], v[16:19]
	v_mfma_f32_16x16x32_bf16 v[16:19], v[160:163], v[212:215], v[16:19]
	v_mfma_f32_16x16x32_bf16 v[44:47], v[164:167], v[184:187], v[44:47]
	v_mfma_f32_16x16x32_bf16 v[44:47], v[168:171], v[188:191], v[44:47]
	v_mfma_f32_16x16x32_bf16 v[40:43], v[176:179], v[184:187], v[40:43]
	v_mfma_f32_16x16x32_bf16 v[40:43], v[180:183], v[188:191], v[40:43]
	v_mfma_f32_16x16x32_bf16 v[28:31], v[164:167], v[192:195], v[28:31]
	v_mfma_f32_16x16x32_bf16 v[28:31], v[168:171], v[196:199], v[28:31]
	v_mfma_f32_16x16x32_bf16 v[24:27], v[176:179], v[192:195], v[24:27]
	v_mfma_f32_16x16x32_bf16 v[24:27], v[180:183], v[196:199], v[24:27]
	v_mfma_f32_16x16x32_bf16 v[12:15], v[164:167], v[200:203], v[12:15]
	v_mfma_f32_16x16x32_bf16 v[12:15], v[168:171], v[204:207], v[12:15]
	v_mfma_f32_16x16x32_bf16 v[8:11], v[176:179], v[200:203], v[8:11]
	v_mfma_f32_16x16x32_bf16 v[8:11], v[180:183], v[204:207], v[8:11]
	v_mfma_f32_16x16x32_bf16 v[4:7], v[164:167], v[208:211], v[4:7]
	v_mfma_f32_16x16x32_bf16 v[4:7], v[168:171], v[212:215], v[4:7]
	v_mfma_f32_16x16x32_bf16 v[0:3], v[176:179], v[208:211], v[0:3]
	v_mfma_f32_16x16x32_bf16 v[0:3], v[180:183], v[212:215], v[0:3]
	s_barrier
	s_add_i32 s84, 0, 0x18000
	v_add_u32_e32 v136, s84, v142
	s_add_i32 s85, 0, 0x1c000
	ds_read_b128 v[148:151], v136
	ds_read_b128 v[152:155], v136 offset:1024
	ds_read_b128 v[156:159], v136 offset:2048
	ds_read_b128 v[160:163], v136 offset:3072
	v_add_u32_e32 v136, s85, v142
	ds_read_b128 v[164:167], v136
	ds_read_b128 v[168:171], v136 offset:1024
	ds_read_b128 v[176:179], v136 offset:2048
	ds_read_b128 v[180:183], v136 offset:3072
	s_add_u32 s50, s50, 0x80000
	s_addc_u32 s51, s51, 0
	s_mov_b32 m0, s23
	ds_read_b128 v[184:187], v145 offset:32768
	ds_read_b128 v[188:191], v145 offset:33792
	ds_read_b128 v[192:195], v145 offset:34816
	ds_read_b128 v[196:199], v145 offset:35840
	ds_read_b128 v[200:203], v145 offset:36864
	ds_read_b128 v[204:207], v145 offset:37888
	ds_read_b128 v[208:211], v145 offset:38912
	ds_read_b128 v[212:215], v145 offset:39936
	global_load_lds_dwordx4 v134, s[50:51]
	s_mov_b32 m0, s33
	s_nop 0
	global_load_lds_dwordx4 v130, s[50:51]
	s_waitcnt vmcnt(8)
	s_waitcnt lgkmcnt(0)
	s_barrier
	s_waitcnt lgkmcnt(0)
	v_mfma_f32_16x16x32_bf16 v[124:127], v[148:151], v[184:187], v[124:127]
	v_mfma_f32_16x16x32_bf16 v[124:127], v[152:155], v[188:191], v[124:127]
	v_mfma_f32_16x16x32_bf16 v[120:123], v[156:159], v[184:187], v[120:123]
	v_mfma_f32_16x16x32_bf16 v[120:123], v[160:163], v[188:191], v[120:123]
	v_mfma_f32_16x16x32_bf16 v[116:119], v[148:151], v[192:195], v[116:119]
	v_mfma_f32_16x16x32_bf16 v[116:119], v[152:155], v[196:199], v[116:119]
	v_mfma_f32_16x16x32_bf16 v[112:115], v[156:159], v[192:195], v[112:115]
	v_mfma_f32_16x16x32_bf16 v[112:115], v[160:163], v[196:199], v[112:115]
	v_mfma_f32_16x16x32_bf16 v[100:103], v[148:151], v[200:203], v[100:103]
	v_mfma_f32_16x16x32_bf16 v[100:103], v[152:155], v[204:207], v[100:103]
	v_mfma_f32_16x16x32_bf16 v[96:99], v[156:159], v[200:203], v[96:99]
	v_mfma_f32_16x16x32_bf16 v[96:99], v[160:163], v[204:207], v[96:99]
	v_mfma_f32_16x16x32_bf16 v[84:87], v[148:151], v[208:211], v[84:87]
	v_mfma_f32_16x16x32_bf16 v[84:87], v[152:155], v[212:215], v[84:87]
	v_mfma_f32_16x16x32_bf16 v[80:83], v[156:159], v[208:211], v[80:83]
	v_mfma_f32_16x16x32_bf16 v[80:83], v[160:163], v[212:215], v[80:83]
	v_mfma_f32_16x16x32_bf16 v[108:111], v[164:167], v[184:187], v[108:111]
	v_mfma_f32_16x16x32_bf16 v[108:111], v[168:171], v[188:191], v[108:111]
	v_mfma_f32_16x16x32_bf16 v[104:107], v[176:179], v[184:187], v[104:107]
	v_mfma_f32_16x16x32_bf16 v[104:107], v[180:183], v[188:191], v[104:107]
	v_mfma_f32_16x16x32_bf16 v[92:95], v[164:167], v[192:195], v[92:95]
	v_mfma_f32_16x16x32_bf16 v[92:95], v[168:171], v[196:199], v[92:95]
	v_mfma_f32_16x16x32_bf16 v[88:91], v[176:179], v[192:195], v[88:91]
	v_mfma_f32_16x16x32_bf16 v[88:91], v[180:183], v[196:199], v[88:91]
	v_mfma_f32_16x16x32_bf16 v[76:79], v[164:167], v[200:203], v[76:79]
	v_mfma_f32_16x16x32_bf16 v[76:79], v[168:171], v[204:207], v[76:79]
	v_mfma_f32_16x16x32_bf16 v[72:75], v[176:179], v[200:203], v[72:75]
	v_mfma_f32_16x16x32_bf16 v[72:75], v[180:183], v[204:207], v[72:75]
	v_mfma_f32_16x16x32_bf16 v[68:71], v[164:167], v[208:211], v[68:71]
	v_mfma_f32_16x16x32_bf16 v[68:71], v[168:171], v[212:215], v[68:71]
	v_mfma_f32_16x16x32_bf16 v[64:67], v[176:179], v[208:211], v[64:67]
	v_mfma_f32_16x16x32_bf16 v[64:67], v[180:183], v[212:215], v[64:67]
	s_barrier
	s_add_i32 s50, s84, s10
	s_mov_b32 m0, s50
	ds_read_b128 v[184:187], v145 offset:49152
	ds_read_b128 v[188:191], v145 offset:50176
	ds_read_b128 v[192:195], v145 offset:51200
	ds_read_b128 v[196:199], v145 offset:52224
	ds_read_b128 v[200:203], v145 offset:53248
	ds_read_b128 v[204:207], v145 offset:54272
	ds_read_b128 v[208:211], v145 offset:55296
	ds_read_b128 v[212:215], v145 offset:56320
	global_load_lds_dwordx4 v132, s[98:99]
	s_add_i32 m0, s50, 0x2000
	s_add_u32 s48, s48, 0x80080
	s_addc_u32 s49, s49, 0
	s_add_i32 s50, s85, s10
	global_load_lds_dwordx4 v128, s[98:99]
	s_mov_b32 m0, s50
	s_nop 0
	global_load_lds_dwordx4 v132, s[48:49]
	s_add_i32 m0, s50, 0x2000
	s_nop 0
	global_load_lds_dwordx4 v128, s[48:49]
	s_mov_b32 m0, s64
	s_nop 0
	global_load_lds_dwordx4 v134, s[100:101]
	s_mov_b32 m0, s65
	s_nop 0
	global_load_lds_dwordx4 v130, s[100:101]
	s_waitcnt vmcnt(8)
	s_waitcnt lgkmcnt(0)
	s_barrier
	s_waitcnt lgkmcnt(0)
	v_mfma_f32_16x16x32_bf16 v[60:63], v[148:151], v[184:187], v[60:63]
	v_mfma_f32_16x16x32_bf16 v[60:63], v[152:155], v[188:191], v[60:63]
	v_mfma_f32_16x16x32_bf16 v[56:59], v[156:159], v[184:187], v[56:59]
	v_mfma_f32_16x16x32_bf16 v[56:59], v[160:163], v[188:191], v[56:59]
	v_mfma_f32_16x16x32_bf16 v[52:55], v[148:151], v[192:195], v[52:55]
	v_mfma_f32_16x16x32_bf16 v[52:55], v[152:155], v[196:199], v[52:55]
	v_mfma_f32_16x16x32_bf16 v[48:51], v[156:159], v[192:195], v[48:51]
	v_mfma_f32_16x16x32_bf16 v[48:51], v[160:163], v[196:199], v[48:51]
	v_mfma_f32_16x16x32_bf16 v[36:39], v[148:151], v[200:203], v[36:39]
	v_mfma_f32_16x16x32_bf16 v[36:39], v[152:155], v[204:207], v[36:39]
	v_mfma_f32_16x16x32_bf16 v[32:35], v[156:159], v[200:203], v[32:35]
	v_mfma_f32_16x16x32_bf16 v[32:35], v[160:163], v[204:207], v[32:35]
	v_mfma_f32_16x16x32_bf16 v[20:23], v[148:151], v[208:211], v[20:23]
	v_mfma_f32_16x16x32_bf16 v[20:23], v[152:155], v[212:215], v[20:23]
	v_mfma_f32_16x16x32_bf16 v[16:19], v[156:159], v[208:211], v[16:19]
	v_mfma_f32_16x16x32_bf16 v[16:19], v[160:163], v[212:215], v[16:19]
	v_mfma_f32_16x16x32_bf16 v[44:47], v[164:167], v[184:187], v[44:47]
	v_mfma_f32_16x16x32_bf16 v[44:47], v[168:171], v[188:191], v[44:47]
	v_mfma_f32_16x16x32_bf16 v[40:43], v[176:179], v[184:187], v[40:43]
	v_mfma_f32_16x16x32_bf16 v[40:43], v[180:183], v[188:191], v[40:43]
	v_mfma_f32_16x16x32_bf16 v[28:31], v[164:167], v[192:195], v[28:31]
	v_mfma_f32_16x16x32_bf16 v[28:31], v[168:171], v[196:199], v[28:31]
	v_mfma_f32_16x16x32_bf16 v[24:27], v[176:179], v[192:195], v[24:27]
	v_mfma_f32_16x16x32_bf16 v[24:27], v[180:183], v[196:199], v[24:27]
	v_mfma_f32_16x16x32_bf16 v[12:15], v[164:167], v[200:203], v[12:15]
	v_mfma_f32_16x16x32_bf16 v[12:15], v[168:171], v[204:207], v[12:15]
	v_mfma_f32_16x16x32_bf16 v[8:11], v[176:179], v[200:203], v[8:11]
	v_mfma_f32_16x16x32_bf16 v[8:11], v[180:183], v[204:207], v[8:11]
	v_mfma_f32_16x16x32_bf16 v[4:7], v[164:167], v[208:211], v[4:7]
	v_mfma_f32_16x16x32_bf16 v[4:7], v[168:171], v[212:215], v[4:7]
	v_mfma_f32_16x16x32_bf16 v[0:3], v[176:179], v[208:211], v[0:3]
	v_mfma_f32_16x16x32_bf16 v[0:3], v[180:183], v[212:215], v[0:3]
	s_barrier
	s_add_i32 s83, s83, 2
	s_add_u32 s46, s46, 0x100
	s_addc_u32 s47, s47, 0
	s_add_u32 s81, s81, 0x100
	s_addc_u32 s82, s82, 0
	s_cmp_gt_u32 s83, 5
	s_cbranch_scc0 .LBB0_428
	s_and_b64 vcc, exec, s[40:41]
	s_cbranch_vccz .LBB0_431
	s_barrier

.LBB0_489:
	v_readlane_b32 s0, v240, 27
	s_add_u32 s22, s56, 0x17400000
	v_readlane_b32 s1, v240, 28
	s_addc_u32 s23, s57, 0
	s_and_b64 vcc, exec, s[0:1]
	s_cbranch_vccnz .LBB0_527
	v_ashrrev_i32_e32 v1, 31, v8
	v_lshrrev_b32_e32 v1, 26, v1
	v_add_u32_e32 v1, v8, v1
	v_ashrrev_i32_e32 v9, 6, v1
	v_bfe_i32 v1, v8, 27, 1
	v_lshlrev_b32_e32 v0, 4, v8
	v_lshrrev_b32_e32 v1, 22, v1
	v_add_u32_e32 v1, v0, v1
	v_and_b32_e32 v1, 0xfffffc00, v1
	v_sub_u32_e32 v1, v0, v1
	v_lshrrev_b32_e32 v2, 4, v1
	v_bitop3_b32 v1, v2, v1, 32 bitop3:0x6c
	v_ashrrev_i32_e32 v3, 31, v1
	v_lshrrev_b32_e32 v3, 26, v3
	v_add_u32_e32 v3, v1, v3
	v_lshlrev_b32_e32 v2, 3, v9
	v_ashrrev_i32_e32 v10, 6, v3
	v_and_b32_e32 v3, 0xc0, v3
	v_and_b32_e32 v2, -16, v2
	v_sub_u32_e32 v1, v1, v3
	v_mov_b32_e32 v3, 1
	v_add_u32_e32 v2, v10, v2
	v_ashrrev_i16_sdwa v1, v3, sext(v1) dst_sel:DWORD dst_unused:UNUSED_PAD src0_sel:DWORD src1_sel:BYTE_0
	v_lshlrev_b32_e32 v4, 5, v9
	v_bfe_i32 v11, v1, 0, 16
	v_lshlrev_b32_e32 v1, 1, v2
	v_lshrrev_b32_e32 v5, 2, v2
	v_and_b32_e32 v6, 3, v10
	s_mov_b32 s0, 0xfffe0
	v_and_b32_e32 v4, 32, v4
	v_and_b32_e32 v1, 24, v1
	v_and_b32_e32 v5, 4, v5
	v_and_or_b32 v6, v2, s0, v6
	v_or3_b32 v1, v6, v5, v1
	v_add_lshl_u32 v4, v4, v11, 1
	v_add_u32_e32 v0, 0x2000, v0
	v_lshl_add_u32 v154, v1, 12, v4
	v_ashrrev_i32_e32 v1, 31, v0
	v_lshrrev_b32_e32 v1, 22, v1
	v_add_u32_e32 v1, v0, v1
	v_ashrrev_i32_e32 v12, 10, v1
	v_mul_i32_i24_e32 v1, 0x400, v12
	v_sub_u32_e32 v0, v0, v1
	v_lshrrev_b32_e32 v1, 4, v0
	v_bitop3_b32 v0, v1, v0, 32 bitop3:0x6c
	v_lshl_add_u32 v152, v2, 12, v4
	v_ashrrev_i32_e32 v2, 31, v0
	v_lshrrev_b32_e32 v2, 26, v2
	v_add_u32_e32 v2, v0, v2
	v_lshlrev_b32_e32 v1, 3, v12
	v_ashrrev_i32_e32 v13, 6, v2
	v_and_b32_e32 v2, 0xc0, v2
	v_and_b32_e32 v1, -16, v1
	v_sub_u32_e32 v0, v0, v2
	s_ashr_i32 s7, s6, 6
	v_add_u32_e32 v1, v13, v1
	v_ashrrev_i16_sdwa v0, v3, sext(v0) dst_sel:DWORD dst_unused:UNUSED_PAD src0_sel:DWORD src1_sel:BYTE_0
	v_and_b32_e32 v3, 3, v13
	s_ashr_i32 s51, s50, 31
	s_ashr_i32 s27, s26, 31
	v_and_or_b32 v3, v1, s0, v3
	s_ashr_i32 s8, s6, 8
	s_lshl_b32 s0, s7, 10
	s_lshl_b64 s[10:11], s[50:51], 20
	s_lshl_b64 s[14:15], s[26:27], 20
	s_add_u32 s62, s34, s14
	v_lshlrev_b32_e32 v4, 5, v12
	v_bfe_i32 v14, v0, 0, 16
	v_lshlrev_b32_e32 v0, 1, v1
	v_lshrrev_b32_e32 v2, 2, v1
	s_addc_u32 s63, s35, s15
	s_add_i32 s1, s0, 0
	v_and_b32_e32 v4, 32, v4
	v_and_b32_e32 v0, 24, v0
	v_and_b32_e32 v2, 4, v2
	s_add_i32 m0, s1, 0x10000
	v_or3_b32 v0, v3, v2, v0
	v_add_lshl_u32 v2, v4, v14, 1
	global_load_lds_dwordx4 v154, s[62:63]
	s_add_i32 m0, s1, 0x12000
	v_lshl_add_u32 v158, v0, 12, v2
	s_add_u32 s14, s62, 0x80000
	global_load_lds_dwordx4 v158, s[62:63]
	s_addc_u32 s15, s63, 0
	s_add_i32 m0, s1, 0x14000
	v_lshl_add_u32 v156, v1, 12, v2
	global_load_lds_dwordx4 v154, s[14:15]
	s_add_i32 m0, s1, 0x16000
	s_add_u32 s60, s66, s10
	s_addc_u32 s61, s67, s11
	s_add_i32 s10, s1, 0x2000
	global_load_lds_dwordx4 v158, s[14:15]
	s_mov_b32 m0, s1
	s_add_u32 s36, s60, 0x80000
	global_load_lds_dwordx4 v152, s[60:61]
	s_mov_b32 m0, s10
	s_addc_u32 s37, s61, 0
	s_add_i32 s11, s1, 0x4000
	global_load_lds_dwordx4 v156, s[60:61]
	s_mov_b32 m0, s11
	s_add_i32 s14, s1, 0x6000
	global_load_lds_dwordx4 v152, s[36:37]
	s_mov_b32 m0, s14
	v_mov_b32_e32 v155, 0
	global_load_lds_dwordx4 v156, s[36:37]
	v_mov_b32_e32 v159, v155
	v_mov_b32_e32 v153, v155
	v_mov_b32_e32 v157, v155
	s_cmp_eq_u32 s8, 1
	s_mov_b32 s15, 0
	v_lshl_add_u64 v[6:7], s[62:63], 0, v[154:155]
	v_lshl_add_u64 v[4:5], s[62:63], 0, v[158:159]
	v_lshl_add_u64 v[0:1], s[60:61], 0, v[152:153]
	s_cselect_b64 s[36:37], -1, 0
	s_cmp_lg_u32 s8, 1
	v_lshl_add_u64 v[2:3], s[60:61], 0, v[156:157]
	s_cbranch_scc1 .LBB0_492
	s_barrier
	s_setprio 1

.LBB0_502:
	ds_read_b128 v[128:131], v192
	ds_read_b128 v[132:135], v192 offset:1024
	ds_read_b128 v[136:139], v192 offset:2048
	ds_read_b128 v[140:143], v192 offset:3072
	ds_read_b128 v[144:147], v193
	ds_read_b128 v[148:151], v193 offset:1024
	ds_read_b128 v[168:171], v193 offset:2048
	ds_read_b128 v[196:199], v193 offset:3072
	s_add_u32 s62, s60, 0xfff80080
	s_addc_u32 s63, s61, -1
	s_cmp_eq_u32 s76, 28
	s_cselect_b32 s65, s27, s63
	s_cselect_b32 s64, s45, s62
	s_cselect_b32 s63, s43, s75
	s_cselect_b32 s62, s51, s74
	s_add_i32 m0, s1, 0xc000
	ds_read_b128 v[200:203], v194
	ds_read_b128 v[204:207], v194 offset:1024
	ds_read_b128 v[208:211], v194 offset:2048
	ds_read_b128 v[212:215], v194 offset:3072
	ds_read_b128 v[216:219], v194 offset:4096
	ds_read_b128 v[220:223], v194 offset:5120
	ds_read_b128 v[224:227], v194 offset:6144
	ds_read_b128 v[228:231], v194 offset:7168
	global_load_lds_dwordx4 v160, s[60:61]
	s_add_i32 m0, s1, 0xe000
	s_nop 0
	global_load_lds_dwordx4 v162, s[60:61]
	s_waitcnt vmcnt(8)
	s_waitcnt lgkmcnt(0)
	s_barrier
	s_waitcnt lgkmcnt(0)
	v_mfma_f32_16x16x32_bf16 v[124:127], v[128:131], v[200:203], v[124:127]
	v_mfma_f32_16x16x32_bf16 v[124:127], v[132:135], v[204:207], v[124:127]
	v_mfma_f32_16x16x32_bf16 v[120:123], v[136:139], v[200:203], v[120:123]
	v_mfma_f32_16x16x32_bf16 v[120:123], v[140:143], v[204:207], v[120:123]
	v_mfma_f32_16x16x32_bf16 v[108:111], v[128:131], v[208:211], v[108:111]
	v_mfma_f32_16x16x32_bf16 v[108:111], v[132:135], v[212:215], v[108:111]
	v_mfma_f32_16x16x32_bf16 v[104:107], v[136:139], v[208:211], v[104:107]
	v_mfma_f32_16x16x32_bf16 v[104:107], v[140:143], v[212:215], v[104:107]
	v_mfma_f32_16x16x32_bf16 v[92:95], v[128:131], v[216:219], v[92:95]
	v_mfma_f32_16x16x32_bf16 v[92:95], v[132:135], v[220:223], v[92:95]
	v_mfma_f32_16x16x32_bf16 v[88:91], v[136:139], v[216:219], v[88:91]
	v_mfma_f32_16x16x32_bf16 v[88:91], v[140:143], v[220:223], v[88:91]
	v_mfma_f32_16x16x32_bf16 v[76:79], v[128:131], v[224:227], v[76:79]
	v_mfma_f32_16x16x32_bf16 v[76:79], v[132:135], v[228:231], v[76:79]
	v_mfma_f32_16x16x32_bf16 v[72:75], v[136:139], v[224:227], v[72:75]
	v_mfma_f32_16x16x32_bf16 v[72:75], v[140:143], v[228:231], v[72:75]
	v_mfma_f32_16x16x32_bf16 v[116:119], v[144:147], v[200:203], v[116:119]
	v_mfma_f32_16x16x32_bf16 v[116:119], v[148:151], v[204:207], v[116:119]
	v_mfma_f32_16x16x32_bf16 v[112:115], v[168:171], v[200:203], v[112:115]
	v_mfma_f32_16x16x32_bf16 v[112:115], v[196:199], v[204:207], v[112:115]
	v_mfma_f32_16x16x32_bf16 v[100:103], v[144:147], v[208:211], v[100:103]
	v_mfma_f32_16x16x32_bf16 v[100:103], v[148:151], v[212:215], v[100:103]
	v_mfma_f32_16x16x32_bf16 v[96:99], v[168:171], v[208:211], v[96:99]
	v_mfma_f32_16x16x32_bf16 v[96:99], v[196:199], v[212:215], v[96:99]
	v_mfma_f32_16x16x32_bf16 v[84:87], v[144:147], v[216:219], v[84:87]
	v_mfma_f32_16x16x32_bf16 v[84:87], v[148:151], v[220:223], v[84:87]
	v_mfma_f32_16x16x32_bf16 v[80:83], v[168:171], v[216:219], v[80:83]
	v_mfma_f32_16x16x32_bf16 v[80:83], v[196:199], v[220:223], v[80:83]
	v_mfma_f32_16x16x32_bf16 v[68:71], v[144:147], v[224:227], v[68:71]
	v_mfma_f32_16x16x32_bf16 v[68:71], v[148:151], v[228:231], v[68:71]
	v_mfma_f32_16x16x32_bf16 v[64:67], v[168:171], v[224:227], v[64:67]
	v_mfma_f32_16x16x32_bf16 v[64:67], v[196:199], v[228:231], v[64:67]
	s_barrier
	s_add_i32 s77, s69, s0
	s_add_u32 s98, s62, s38
	s_addc_u32 s99, s63, s39
	s_mov_b32 m0, s77
	ds_read_b128 v[200:203], v194 offset:16384
	ds_read_b128 v[204:207], v194 offset:17408
	ds_read_b128 v[208:211], v194 offset:18432
	ds_read_b128 v[212:215], v194 offset:19456
	ds_read_b128 v[216:219], v194 offset:20480
	ds_read_b128 v[220:223], v194 offset:21504
	ds_read_b128 v[224:227], v194 offset:22528
	ds_read_b128 v[228:231], v194 offset:23552
	global_load_lds_dwordx4 v154, s[62:63]
	s_add_i32 m0, s77, 0x2000
	s_add_u32 s78, s62, 0x80000
	s_addc_u32 s79, s63, 0
	s_add_i32 s77, s73, s0
	global_load_lds_dwordx4 v158, s[62:63]
	s_mov_b32 m0, s77
	s_nop 0
	global_load_lds_dwordx4 v154, s[78:79]
	s_add_i32 m0, s77, 0x2000
	s_nop 0
	global_load_lds_dwordx4 v158, s[78:79]
	s_add_u32 s100, s64, s38
	s_addc_u32 s101, s65, s39
	s_mov_b32 m0, s1
	s_nop 0
	global_load_lds_dwordx4 v152, s[64:65]
	s_mov_b32 m0, s10
	s_nop 0
	global_load_lds_dwordx4 v156, s[64:65]
	s_waitcnt vmcnt(8)
	s_waitcnt lgkmcnt(0)
	s_barrier
	s_waitcnt lgkmcnt(0)
	v_mfma_f32_16x16x32_bf16 v[60:63], v[128:131], v[200:203], v[60:63]
	v_mfma_f32_16x16x32_bf16 v[60:63], v[132:135], v[204:207], v[60:63]
	v_mfma_f32_16x16x32_bf16 v[56:59], v[136:139], v[200:203], v[56:59]
	v_mfma_f32_16x16x32_bf16 v[56:59], v[140:143], v[204:207], v[56:59]
	v_mfma_f32_16x16x32_bf16 v[44:47], v[128:131], v[208:211], v[44:47]
	v_mfma_f32_16x16x32_bf16 v[44:47], v[132:135], v[212:215], v[44:47]
	v_mfma_f32_16x16x32_bf16 v[40:43], v[136:139], v[208:211], v[40:43]
	v_mfma_f32_16x16x32_bf16 v[40:43], v[140:143], v[212:215], v[40:43]
	v_mfma_f32_16x16x32_bf16 v[28:31], v[128:131], v[216:219], v[28:31]
	v_mfma_f32_16x16x32_bf16 v[28:31], v[132:135], v[220:223], v[28:31]
	v_mfma_f32_16x16x32_bf16 v[24:27], v[136:139], v[216:219], v[24:27]
	v_mfma_f32_16x16x32_bf16 v[24:27], v[140:143], v[220:223], v[24:27]
	v_mfma_f32_16x16x32_bf16 v[12:15], v[128:131], v[224:227], v[12:15]
	v_mfma_f32_16x16x32_bf16 v[12:15], v[132:135], v[228:231], v[12:15]
	v_mfma_f32_16x16x32_bf16 v[8:11], v[136:139], v[224:227], v[8:11]
	v_mfma_f32_16x16x32_bf16 v[8:11], v[140:143], v[228:231], v[8:11]
	v_mfma_f32_16x16x32_bf16 v[52:55], v[144:147], v[200:203], v[52:55]
	v_mfma_f32_16x16x32_bf16 v[52:55], v[148:151], v[204:207], v[52:55]
	v_mfma_f32_16x16x32_bf16 v[48:51], v[168:171], v[200:203], v[48:51]
	v_mfma_f32_16x16x32_bf16 v[48:51], v[196:199], v[204:207], v[48:51]
	v_mfma_f32_16x16x32_bf16 v[36:39], v[144:147], v[208:211], v[36:39]
	v_mfma_f32_16x16x32_bf16 v[36:39], v[148:151], v[212:215], v[36:39]
	v_mfma_f32_16x16x32_bf16 v[32:35], v[168:171], v[208:211], v[32:35]
	v_mfma_f32_16x16x32_bf16 v[32:35], v[196:199], v[212:215], v[32:35]
	v_mfma_f32_16x16x32_bf16 v[20:23], v[144:147], v[216:219], v[20:23]
	v_mfma_f32_16x16x32_bf16 v[20:23], v[148:151], v[220:223], v[20:23]
	v_mfma_f32_16x16x32_bf16 v[16:19], v[168:171], v[216:219], v[16:19]
	v_mfma_f32_16x16x32_bf16 v[16:19], v[196:199], v[220:223], v[16:19]
	v_mfma_f32_16x16x32_bf16 v[4:7], v[144:147], v[224:227], v[4:7]
	v_mfma_f32_16x16x32_bf16 v[4:7], v[148:151], v[228:231], v[4:7]
	v_mfma_f32_16x16x32_bf16 v[0:3], v[168:171], v[224:227], v[0:3]
	v_mfma_f32_16x16x32_bf16 v[0:3], v[196:199], v[228:231], v[0:3]
	s_barrier
	s_add_i32 s77, 0, 0x18000
	s_add_i32 s78, 0, 0x1c000
	v_add_u32_e32 v140, s77, v177
	v_add_u32_e32 v196, s78, v177
	ds_read_b128 v[128:131], v140
	ds_read_b128 v[132:135], v140 offset:1024
	ds_read_b128 v[136:139], v140 offset:2048
	ds_read_b128 v[140:143], v140 offset:3072
	ds_read_b128 v[144:147], v196
	ds_read_b128 v[148:151], v196 offset:1024
	ds_read_b128 v[168:171], v196 offset:2048
	ds_read_b128 v[196:199], v196 offset:3072
	s_add_u32 s64, s64, 0x80000
	s_addc_u32 s65, s65, 0
	s_mov_b32 m0, s11
	ds_read_b128 v[200:203], v194 offset:32768
	ds_read_b128 v[204:207], v194 offset:33792
	ds_read_b128 v[208:211], v194 offset:34816
	ds_read_b128 v[212:215], v194 offset:35840
	ds_read_b128 v[216:219], v194 offset:36864
	ds_read_b128 v[220:223], v194 offset:37888
	ds_read_b128 v[224:227], v194 offset:38912
	ds_read_b128 v[228:231], v194 offset:39936
	global_load_lds_dwordx4 v152, s[64:65]
	s_mov_b32 m0, s14
	s_nop 0
	global_load_lds_dwordx4 v156, s[64:65]
	s_waitcnt vmcnt(8)
	s_waitcnt lgkmcnt(0)
	s_barrier
	s_waitcnt lgkmcnt(0)
	v_mfma_f32_16x16x32_bf16 v[124:127], v[128:131], v[200:203], v[124:127]
	v_mfma_f32_16x16x32_bf16 v[124:127], v[132:135], v[204:207], v[124:127]
	v_mfma_f32_16x16x32_bf16 v[120:123], v[136:139], v[200:203], v[120:123]
	v_mfma_f32_16x16x32_bf16 v[120:123], v[140:143], v[204:207], v[120:123]
	v_mfma_f32_16x16x32_bf16 v[108:111], v[128:131], v[208:211], v[108:111]
	v_mfma_f32_16x16x32_bf16 v[108:111], v[132:135], v[212:215], v[108:111]
	v_mfma_f32_16x16x32_bf16 v[104:107], v[136:139], v[208:211], v[104:107]
	v_mfma_f32_16x16x32_bf16 v[104:107], v[140:143], v[212:215], v[104:107]
	v_mfma_f32_16x16x32_bf16 v[92:95], v[128:131], v[216:219], v[92:95]
	v_mfma_f32_16x16x32_bf16 v[92:95], v[132:135], v[220:223], v[92:95]
	v_mfma_f32_16x16x32_bf16 v[88:91], v[136:139], v[216:219], v[88:91]
	v_mfma_f32_16x16x32_bf16 v[88:91], v[140:143], v[220:223], v[88:91]
	v_mfma_f32_16x16x32_bf16 v[76:79], v[128:131], v[224:227], v[76:79]
	v_mfma_f32_16x16x32_bf16 v[76:79], v[132:135], v[228:231], v[76:79]
	v_mfma_f32_16x16x32_bf16 v[72:75], v[136:139], v[224:227], v[72:75]
	v_mfma_f32_16x16x32_bf16 v[72:75], v[140:143], v[228:231], v[72:75]
	v_mfma_f32_16x16x32_bf16 v[116:119], v[144:147], v[200:203], v[116:119]
	v_mfma_f32_16x16x32_bf16 v[116:119], v[148:151], v[204:207], v[116:119]
	v_mfma_f32_16x16x32_bf16 v[112:115], v[168:171], v[200:203], v[112:115]
	v_mfma_f32_16x16x32_bf16 v[112:115], v[196:199], v[204:207], v[112:115]
	v_mfma_f32_16x16x32_bf16 v[100:103], v[144:147], v[208:211], v[100:103]
	v_mfma_f32_16x16x32_bf16 v[100:103], v[148:151], v[212:215], v[100:103]
	v_mfma_f32_16x16x32_bf16 v[96:99], v[168:171], v[208:211], v[96:99]
	v_mfma_f32_16x16x32_bf16 v[96:99], v[196:199], v[212:215], v[96:99]
	v_mfma_f32_16x16x32_bf16 v[84:87], v[144:147], v[216:219], v[84:87]
	v_mfma_f32_16x16x32_bf16 v[84:87], v[148:151], v[220:223], v[84:87]
	v_mfma_f32_16x16x32_bf16 v[80:83], v[168:171], v[216:219], v[80:83]
	v_mfma_f32_16x16x32_bf16 v[80:83], v[196:199], v[220:223], v[80:83]
	v_mfma_f32_16x16x32_bf16 v[68:71], v[144:147], v[224:227], v[68:71]
	v_mfma_f32_16x16x32_bf16 v[68:71], v[148:151], v[228:231], v[68:71]
	v_mfma_f32_16x16x32_bf16 v[64:67], v[168:171], v[224:227], v[64:67]
	v_mfma_f32_16x16x32_bf16 v[64:67], v[196:199], v[228:231], v[64:67]
	s_barrier
	s_add_i32 s64, s77, s0
	s_mov_b32 m0, s64
	ds_read_b128 v[200:203], v194 offset:49152
	ds_read_b128 v[204:207], v194 offset:50176
	ds_read_b128 v[208:211], v194 offset:51200
	ds_read_b128 v[212:215], v194 offset:52224
	ds_read_b128 v[216:219], v194 offset:53248
	ds_read_b128 v[220:223], v194 offset:54272
	ds_read_b128 v[224:227], v194 offset:55296
	ds_read_b128 v[228:231], v194 offset:56320
	global_load_lds_dwordx4 v154, s[98:99]
	s_add_i32 m0, s64, 0x2000
	s_add_u32 s62, s62, 0x80080
	s_addc_u32 s63, s63, 0
	s_add_i32 s64, s78, s0
	global_load_lds_dwordx4 v158, s[98:99]
	s_mov_b32 m0, s64
	s_nop 0
	global_load_lds_dwordx4 v154, s[62:63]
	s_add_i32 m0, s64, 0x2000
	s_nop 0
	global_load_lds_dwordx4 v158, s[62:63]
	s_mov_b32 m0, s33
	s_nop 0
	global_load_lds_dwordx4 v152, s[100:101]
	s_mov_b32 m0, s68
	s_nop 0
	global_load_lds_dwordx4 v156, s[100:101]
	s_waitcnt vmcnt(8)
	s_waitcnt lgkmcnt(0)
	s_barrier
	s_waitcnt lgkmcnt(0)
	v_mfma_f32_16x16x32_bf16 v[60:63], v[128:131], v[200:203], v[60:63]
	v_mfma_f32_16x16x32_bf16 v[60:63], v[132:135], v[204:207], v[60:63]
	v_mfma_f32_16x16x32_bf16 v[56:59], v[136:139], v[200:203], v[56:59]
	v_mfma_f32_16x16x32_bf16 v[56:59], v[140:143], v[204:207], v[56:59]
	v_mfma_f32_16x16x32_bf16 v[44:47], v[128:131], v[208:211], v[44:47]
	v_mfma_f32_16x16x32_bf16 v[44:47], v[132:135], v[212:215], v[44:47]
	v_mfma_f32_16x16x32_bf16 v[40:43], v[136:139], v[208:211], v[40:43]
	v_mfma_f32_16x16x32_bf16 v[40:43], v[140:143], v[212:215], v[40:43]
	v_mfma_f32_16x16x32_bf16 v[28:31], v[128:131], v[216:219], v[28:31]
	v_mfma_f32_16x16x32_bf16 v[28:31], v[132:135], v[220:223], v[28:31]
	v_mfma_f32_16x16x32_bf16 v[24:27], v[136:139], v[216:219], v[24:27]
	v_mfma_f32_16x16x32_bf16 v[24:27], v[140:143], v[220:223], v[24:27]
	v_mfma_f32_16x16x32_bf16 v[12:15], v[128:131], v[224:227], v[12:15]
	v_mfma_f32_16x16x32_bf16 v[12:15], v[132:135], v[228:231], v[12:15]
	v_mfma_f32_16x16x32_bf16 v[8:11], v[136:139], v[224:227], v[8:11]
	v_mfma_f32_16x16x32_bf16 v[8:11], v[140:143], v[228:231], v[8:11]
	v_mfma_f32_16x16x32_bf16 v[52:55], v[144:147], v[200:203], v[52:55]
	v_mfma_f32_16x16x32_bf16 v[52:55], v[148:151], v[204:207], v[52:55]
	v_mfma_f32_16x16x32_bf16 v[48:51], v[168:171], v[200:203], v[48:51]
	v_mfma_f32_16x16x32_bf16 v[48:51], v[196:199], v[204:207], v[48:51]
	v_mfma_f32_16x16x32_bf16 v[36:39], v[144:147], v[208:211], v[36:39]
	v_mfma_f32_16x16x32_bf16 v[36:39], v[148:151], v[212:215], v[36:39]
	v_mfma_f32_16x16x32_bf16 v[32:35], v[168:171], v[208:211], v[32:35]
	v_mfma_f32_16x16x32_bf16 v[32:35], v[196:199], v[212:215], v[32:35]
	v_mfma_f32_16x16x32_bf16 v[20:23], v[144:147], v[216:219], v[20:23]
	v_mfma_f32_16x16x32_bf16 v[20:23], v[148:151], v[220:223], v[20:23]
	v_mfma_f32_16x16x32_bf16 v[16:19], v[168:171], v[216:219], v[16:19]
	v_mfma_f32_16x16x32_bf16 v[16:19], v[196:199], v[220:223], v[16:19]
	v_mfma_f32_16x16x32_bf16 v[4:7], v[144:147], v[224:227], v[4:7]
	v_mfma_f32_16x16x32_bf16 v[4:7], v[148:151], v[228:231], v[4:7]
	v_mfma_f32_16x16x32_bf16 v[0:3], v[168:171], v[224:227], v[0:3]
	v_mfma_f32_16x16x32_bf16 v[0:3], v[196:199], v[228:231], v[0:3]
	s_barrier
	s_add_i32 s76, s76, 2
	s_add_u32 s60, s60, 0x100
	s_addc_u32 s61, s61, 0
	s_add_u32 s74, s74, 0x100
	s_addc_u32 s75, s75, 0
	s_cmp_gt_u32 s76, 29
	s_cbranch_scc0 .LBB0_502
	s_and_b64 vcc, exec, s[40:41]
	s_cbranch_vccz .LBB0_505
	s_barrier

.LBB0_586:
	s_andn2_b64 vcc, exec, s[4:5]
	s_cbranch_vccnz .LBB0_635
	v_ashrrev_i32_e32 v1, 31, v8
	v_lshrrev_b32_e32 v1, 26, v1
	v_add_u32_e32 v1, v8, v1
	v_ashrrev_i32_e32 v9, 6, v1
	v_bfe_i32 v1, v8, 27, 1
	v_lshlrev_b32_e32 v0, 4, v8
	v_lshrrev_b32_e32 v1, 22, v1
	v_add_u32_e32 v1, v0, v1
	v_and_b32_e32 v1, 0xfffffc00, v1
	v_sub_u32_e32 v1, v0, v1
	v_lshrrev_b32_e32 v2, 4, v1
	v_bitop3_b32 v1, v2, v1, 32 bitop3:0x6c
	v_ashrrev_i32_e32 v3, 31, v1
	v_lshrrev_b32_e32 v3, 26, v3
	v_add_u32_e32 v3, v1, v3
	v_lshlrev_b32_e32 v2, 3, v9
	v_ashrrev_i32_e32 v10, 6, v3
	v_and_b32_e32 v3, 0xc0, v3
	v_and_b32_e32 v2, -16, v2
	v_sub_u32_e32 v1, v1, v3
	v_mov_b32_e32 v3, 1
	v_add_u32_e32 v2, v10, v2
	v_ashrrev_i16_sdwa v1, v3, sext(v1) dst_sel:DWORD dst_unused:UNUSED_PAD src0_sel:DWORD src1_sel:BYTE_0
	v_lshlrev_b32_e32 v4, 5, v9
	v_bfe_i32 v11, v1, 0, 16
	v_lshlrev_b32_e32 v1, 1, v2
	v_lshrrev_b32_e32 v5, 2, v2
	v_and_b32_e32 v6, 3, v10
	s_mov_b32 s0, 0xfffe0
	v_and_b32_e32 v4, 32, v4
	v_and_b32_e32 v1, 24, v1
	v_and_b32_e32 v5, 4, v5
	v_and_or_b32 v6, v2, s0, v6
	v_or3_b32 v1, v6, v5, v1
	v_add_lshl_u32 v4, v4, v11, 1
	v_add_u32_e32 v0, 0x2000, v0
	v_lshl_add_u32 v130, v1, 12, v4
	v_ashrrev_i32_e32 v1, 31, v0
	v_lshrrev_b32_e32 v1, 22, v1
	v_add_u32_e32 v1, v0, v1
	v_ashrrev_i32_e32 v12, 10, v1
	v_mul_i32_i24_e32 v1, 0x400, v12
	v_sub_u32_e32 v0, v0, v1
	v_lshrrev_b32_e32 v1, 4, v0
	v_bitop3_b32 v0, v1, v0, 32 bitop3:0x6c
	v_lshl_add_u32 v128, v2, 12, v4
	v_ashrrev_i32_e32 v2, 31, v0
	v_lshrrev_b32_e32 v2, 26, v2
	v_add_u32_e32 v2, v0, v2
	s_lshl_b32 s1, s46, 6
	v_lshlrev_b32_e32 v1, 3, v12
	v_ashrrev_i32_e32 v13, 6, v2
	v_and_b32_e32 v2, 0xc0, v2
	s_and_b32 s1, s1, 0xfffffc00
	s_lshl_b32 s10, s69, 8
	v_and_b32_e32 v1, -16, v1
	v_sub_u32_e32 v0, v0, v2
	s_add_i32 s10, s1, s10
	s_ashr_i32 s4, s36, 6
	v_add_u32_e32 v1, v13, v1
	v_ashrrev_i16_sdwa v0, v3, sext(v0) dst_sel:DWORD dst_unused:UNUSED_PAD src0_sel:DWORD src1_sel:BYTE_0
	v_and_b32_e32 v3, 3, v13
	s_ashr_i32 s47, s46, 31
	s_ashr_i32 s11, s10, 31
	v_and_or_b32 v3, v1, s0, v3
	s_ashr_i32 s5, s36, 8
	s_lshl_b32 s0, s4, 10
	s_lshl_b64 s[6:7], s[46:47], 20
	s_lshl_b64 s[10:11], s[10:11], 12
	s_add_u32 s50, s70, s10
	v_lshlrev_b32_e32 v4, 5, v12
	v_bfe_i32 v14, v0, 0, 16
	v_lshlrev_b32_e32 v0, 1, v1
	v_lshrrev_b32_e32 v2, 2, v1
	s_addc_u32 s51, s71, s11
	s_add_i32 s1, s0, 0
	v_and_b32_e32 v4, 32, v4
	v_and_b32_e32 v0, 24, v0
	v_and_b32_e32 v2, 4, v2
	s_add_i32 m0, s1, 0x10000
	v_or3_b32 v0, v3, v2, v0
	v_add_lshl_u32 v2, v4, v14, 1
	global_load_lds_dwordx4 v130, s[50:51]
	s_add_i32 m0, s1, 0x12000
	v_lshl_add_u32 v134, v0, 12, v2
	s_add_u32 s10, s50, 0x80000
	global_load_lds_dwordx4 v134, s[50:51]
	s_addc_u32 s11, s51, 0
	s_add_i32 m0, s1, 0x14000
	v_lshl_add_u32 v132, v1, 12, v2
	global_load_lds_dwordx4 v130, s[10:11]
	s_add_i32 m0, s1, 0x16000
	s_add_u32 s48, s28, s6
	global_load_lds_dwordx4 v134, s[10:11]
	s_addc_u32 s49, s29, s7
	s_add_i32 s10, s1, 0x2000
	s_mov_b32 m0, s1
	s_add_u32 s6, s48, 0x80000
	global_load_lds_dwordx4 v128, s[48:49]
	s_mov_b32 m0, s10
	s_addc_u32 s7, s49, 0
	s_add_i32 s11, s1, 0x4000
	global_load_lds_dwordx4 v132, s[48:49]
	s_mov_b32 m0, s11
	s_add_i32 s14, s1, 0x6000
	global_load_lds_dwordx4 v128, s[6:7]
	s_mov_b32 m0, s14
	v_mov_b32_e32 v137, 0
	global_load_lds_dwordx4 v132, s[6:7]
	v_mov_b32_e32 v131, v137
	v_mov_b32_e32 v135, v137
	v_mov_b32_e32 v129, v137
	v_mov_b32_e32 v133, v137
	s_cmp_eq_u32 s5, 1
	s_mov_b32 s7, 0
	v_lshl_add_u64 v[6:7], s[50:51], 0, v[130:131]
	v_lshl_add_u64 v[4:5], s[50:51], 0, v[134:135]
	v_lshl_add_u64 v[0:1], s[48:49], 0, v[128:129]
	s_cselect_b64 s[26:27], -1, 0
	s_cmp_lg_u32 s5, 1
	v_lshl_add_u64 v[2:3], s[48:49], 0, v[132:133]
	s_cbranch_scc1 .LBB0_589
	s_barrier
	s_setprio 1

.LBB0_596:
	ds_read_b128 v[142:145], v159
	ds_read_b128 v[146:149], v159 offset:1024
	ds_read_b128 v[150:153], v159 offset:2048
	ds_read_b128 v[154:157], v159 offset:3072
	ds_read_b128 v[166:169], v160
	ds_read_b128 v[170:173], v160 offset:1024
	ds_read_b128 v[176:179], v160 offset:2048
	ds_read_b128 v[180:183], v160 offset:3072
	s_add_u32 s50, s48, 0xfff80080
	s_addc_u32 s51, s49, -1
	s_cmp_eq_u32 s76, 28
	s_cselect_b32 s61, s39, s51
	s_cselect_b32 s60, s47, s50
	s_cselect_b32 s51, s72, s75
	s_cselect_b32 s50, s73, s74
	s_add_i32 m0, s1, 0xc000
	ds_read_b128 v[184:187], v161
	ds_read_b128 v[188:191], v161 offset:1024
	ds_read_b128 v[192:195], v161 offset:2048
	ds_read_b128 v[196:199], v161 offset:3072
	ds_read_b128 v[200:203], v161 offset:4096
	ds_read_b128 v[204:207], v161 offset:5120
	ds_read_b128 v[208:211], v161 offset:6144
	ds_read_b128 v[212:215], v161 offset:7168
	global_load_lds_dwordx4 v138, s[48:49]
	s_add_i32 m0, s1, 0xe000
	s_nop 0
	global_load_lds_dwordx4 v140, s[48:49]
	s_waitcnt vmcnt(8)
	s_waitcnt lgkmcnt(0)
	s_barrier
	s_waitcnt lgkmcnt(0)
	v_mfma_f32_16x16x32_bf16 v[124:127], v[142:145], v[184:187], v[124:127]
	v_mfma_f32_16x16x32_bf16 v[124:127], v[146:149], v[188:191], v[124:127]
	v_mfma_f32_16x16x32_bf16 v[120:123], v[150:153], v[184:187], v[120:123]
	v_mfma_f32_16x16x32_bf16 v[120:123], v[154:157], v[188:191], v[120:123]
	v_mfma_f32_16x16x32_bf16 v[108:111], v[142:145], v[192:195], v[108:111]
	v_mfma_f32_16x16x32_bf16 v[108:111], v[146:149], v[196:199], v[108:111]
	v_mfma_f32_16x16x32_bf16 v[104:107], v[150:153], v[192:195], v[104:107]
	v_mfma_f32_16x16x32_bf16 v[104:107], v[154:157], v[196:199], v[104:107]
	v_mfma_f32_16x16x32_bf16 v[92:95], v[142:145], v[200:203], v[92:95]
	v_mfma_f32_16x16x32_bf16 v[92:95], v[146:149], v[204:207], v[92:95]
	v_mfma_f32_16x16x32_bf16 v[88:91], v[150:153], v[200:203], v[88:91]
	v_mfma_f32_16x16x32_bf16 v[88:91], v[154:157], v[204:207], v[88:91]
	v_mfma_f32_16x16x32_bf16 v[76:79], v[142:145], v[208:211], v[76:79]
	v_mfma_f32_16x16x32_bf16 v[76:79], v[146:149], v[212:215], v[76:79]
	v_mfma_f32_16x16x32_bf16 v[72:75], v[150:153], v[208:211], v[72:75]
	v_mfma_f32_16x16x32_bf16 v[72:75], v[154:157], v[212:215], v[72:75]
	v_mfma_f32_16x16x32_bf16 v[116:119], v[166:169], v[184:187], v[116:119]
	v_mfma_f32_16x16x32_bf16 v[116:119], v[170:173], v[188:191], v[116:119]
	v_mfma_f32_16x16x32_bf16 v[112:115], v[176:179], v[184:187], v[112:115]
	v_mfma_f32_16x16x32_bf16 v[112:115], v[180:183], v[188:191], v[112:115]
	v_mfma_f32_16x16x32_bf16 v[100:103], v[166:169], v[192:195], v[100:103]
	v_mfma_f32_16x16x32_bf16 v[100:103], v[170:173], v[196:199], v[100:103]
	v_mfma_f32_16x16x32_bf16 v[96:99], v[176:179], v[192:195], v[96:99]
	v_mfma_f32_16x16x32_bf16 v[96:99], v[180:183], v[196:199], v[96:99]
	v_mfma_f32_16x16x32_bf16 v[84:87], v[166:169], v[200:203], v[84:87]
	v_mfma_f32_16x16x32_bf16 v[84:87], v[170:173], v[204:207], v[84:87]
	v_mfma_f32_16x16x32_bf16 v[80:83], v[176:179], v[200:203], v[80:83]
	v_mfma_f32_16x16x32_bf16 v[80:83], v[180:183], v[204:207], v[80:83]
	v_mfma_f32_16x16x32_bf16 v[68:71], v[166:169], v[208:211], v[68:71]
	v_mfma_f32_16x16x32_bf16 v[68:71], v[170:173], v[212:215], v[68:71]
	v_mfma_f32_16x16x32_bf16 v[64:67], v[176:179], v[208:211], v[64:67]
	v_mfma_f32_16x16x32_bf16 v[64:67], v[180:183], v[212:215], v[64:67]
	s_barrier
	s_add_i32 s77, s64, s0
	s_add_u32 s98, s50, s34
	s_addc_u32 s99, s51, s35
	s_mov_b32 m0, s77
	ds_read_b128 v[184:187], v161 offset:16384
	ds_read_b128 v[188:191], v161 offset:17408
	ds_read_b128 v[192:195], v161 offset:18432
	ds_read_b128 v[196:199], v161 offset:19456
	ds_read_b128 v[200:203], v161 offset:20480
	ds_read_b128 v[204:207], v161 offset:21504
	ds_read_b128 v[208:211], v161 offset:22528
	ds_read_b128 v[212:215], v161 offset:23552
	global_load_lds_dwordx4 v130, s[50:51]
	s_add_i32 m0, s77, 0x2000
	s_add_u32 s78, s50, 0x80000
	s_addc_u32 s79, s51, 0
	s_add_i32 s77, s65, s0
	global_load_lds_dwordx4 v134, s[50:51]
	s_mov_b32 m0, s77
	s_nop 0
	global_load_lds_dwordx4 v130, s[78:79]
	s_add_i32 m0, s77, 0x2000
	s_nop 0
	global_load_lds_dwordx4 v134, s[78:79]
	s_add_u32 s100, s60, s34
	s_addc_u32 s101, s61, s35
	s_mov_b32 m0, s1
	s_nop 0
	global_load_lds_dwordx4 v128, s[60:61]
	s_mov_b32 m0, s10
	s_nop 0
	global_load_lds_dwordx4 v132, s[60:61]
	s_waitcnt vmcnt(8)
	s_waitcnt lgkmcnt(0)
	s_barrier
	s_waitcnt lgkmcnt(0)
	v_mfma_f32_16x16x32_bf16 v[60:63], v[142:145], v[184:187], v[60:63]
	v_mfma_f32_16x16x32_bf16 v[60:63], v[146:149], v[188:191], v[60:63]
	v_mfma_f32_16x16x32_bf16 v[56:59], v[150:153], v[184:187], v[56:59]
	v_mfma_f32_16x16x32_bf16 v[56:59], v[154:157], v[188:191], v[56:59]
	v_mfma_f32_16x16x32_bf16 v[44:47], v[142:145], v[192:195], v[44:47]
	v_mfma_f32_16x16x32_bf16 v[44:47], v[146:149], v[196:199], v[44:47]
	v_mfma_f32_16x16x32_bf16 v[40:43], v[150:153], v[192:195], v[40:43]
	v_mfma_f32_16x16x32_bf16 v[40:43], v[154:157], v[196:199], v[40:43]
	v_mfma_f32_16x16x32_bf16 v[28:31], v[142:145], v[200:203], v[28:31]
	v_mfma_f32_16x16x32_bf16 v[28:31], v[146:149], v[204:207], v[28:31]
	v_mfma_f32_16x16x32_bf16 v[24:27], v[150:153], v[200:203], v[24:27]
	v_mfma_f32_16x16x32_bf16 v[24:27], v[154:157], v[204:207], v[24:27]
	v_mfma_f32_16x16x32_bf16 v[12:15], v[142:145], v[208:211], v[12:15]
	v_mfma_f32_16x16x32_bf16 v[12:15], v[146:149], v[212:215], v[12:15]
	v_mfma_f32_16x16x32_bf16 v[8:11], v[150:153], v[208:211], v[8:11]
	v_mfma_f32_16x16x32_bf16 v[8:11], v[154:157], v[212:215], v[8:11]
	v_mfma_f32_16x16x32_bf16 v[52:55], v[166:169], v[184:187], v[52:55]
	v_mfma_f32_16x16x32_bf16 v[52:55], v[170:173], v[188:191], v[52:55]
	v_mfma_f32_16x16x32_bf16 v[48:51], v[176:179], v[184:187], v[48:51]
	v_mfma_f32_16x16x32_bf16 v[48:51], v[180:183], v[188:191], v[48:51]
	v_mfma_f32_16x16x32_bf16 v[36:39], v[166:169], v[192:195], v[36:39]
	v_mfma_f32_16x16x32_bf16 v[36:39], v[170:173], v[196:199], v[36:39]
	v_mfma_f32_16x16x32_bf16 v[32:35], v[176:179], v[192:195], v[32:35]
	v_mfma_f32_16x16x32_bf16 v[32:35], v[180:183], v[196:199], v[32:35]
	v_mfma_f32_16x16x32_bf16 v[20:23], v[166:169], v[200:203], v[20:23]
	v_mfma_f32_16x16x32_bf16 v[20:23], v[170:173], v[204:207], v[20:23]
	v_mfma_f32_16x16x32_bf16 v[16:19], v[176:179], v[200:203], v[16:19]
	v_mfma_f32_16x16x32_bf16 v[16:19], v[180:183], v[204:207], v[16:19]
	v_mfma_f32_16x16x32_bf16 v[4:7], v[166:169], v[208:211], v[4:7]
	v_mfma_f32_16x16x32_bf16 v[4:7], v[170:173], v[212:215], v[4:7]
	v_mfma_f32_16x16x32_bf16 v[0:3], v[176:179], v[208:211], v[0:3]
	v_mfma_f32_16x16x32_bf16 v[0:3], v[180:183], v[212:215], v[0:3]
	s_barrier
	s_add_i32 s77, 0, 0x18000
	v_add_u32_e32 v136, s77, v158
	s_add_i32 s78, 0, 0x1c000
	ds_read_b128 v[142:145], v136
	ds_read_b128 v[146:149], v136 offset:1024
	ds_read_b128 v[150:153], v136 offset:2048
	ds_read_b128 v[154:157], v136 offset:3072
	v_add_u32_e32 v136, s78, v158
	ds_read_b128 v[166:169], v136
	ds_read_b128 v[170:173], v136 offset:1024
	ds_read_b128 v[176:179], v136 offset:2048
	ds_read_b128 v[180:183], v136 offset:3072
	s_add_u32 s60, s60, 0x80000
	s_addc_u32 s61, s61, 0
	s_mov_b32 m0, s11
	ds_read_b128 v[184:187], v161 offset:32768
	ds_read_b128 v[188:191], v161 offset:33792
	ds_read_b128 v[192:195], v161 offset:34816
	ds_read_b128 v[196:199], v161 offset:35840
	ds_read_b128 v[200:203], v161 offset:36864
	ds_read_b128 v[204:207], v161 offset:37888
	ds_read_b128 v[208:211], v161 offset:38912
	ds_read_b128 v[212:215], v161 offset:39936
	global_load_lds_dwordx4 v128, s[60:61]
	s_mov_b32 m0, s14
	s_nop 0
	global_load_lds_dwordx4 v132, s[60:61]
	s_waitcnt vmcnt(8)
	s_waitcnt lgkmcnt(0)
	s_barrier
	s_waitcnt lgkmcnt(0)
	v_mfma_f32_16x16x32_bf16 v[124:127], v[142:145], v[184:187], v[124:127]
	v_mfma_f32_16x16x32_bf16 v[124:127], v[146:149], v[188:191], v[124:127]
	v_mfma_f32_16x16x32_bf16 v[120:123], v[150:153], v[184:187], v[120:123]
	v_mfma_f32_16x16x32_bf16 v[120:123], v[154:157], v[188:191], v[120:123]
	v_mfma_f32_16x16x32_bf16 v[108:111], v[142:145], v[192:195], v[108:111]
	v_mfma_f32_16x16x32_bf16 v[108:111], v[146:149], v[196:199], v[108:111]
	v_mfma_f32_16x16x32_bf16 v[104:107], v[150:153], v[192:195], v[104:107]
	v_mfma_f32_16x16x32_bf16 v[104:107], v[154:157], v[196:199], v[104:107]
	v_mfma_f32_16x16x32_bf16 v[92:95], v[142:145], v[200:203], v[92:95]
	v_mfma_f32_16x16x32_bf16 v[92:95], v[146:149], v[204:207], v[92:95]
	v_mfma_f32_16x16x32_bf16 v[88:91], v[150:153], v[200:203], v[88:91]
	v_mfma_f32_16x16x32_bf16 v[88:91], v[154:157], v[204:207], v[88:91]
	v_mfma_f32_16x16x32_bf16 v[76:79], v[142:145], v[208:211], v[76:79]
	v_mfma_f32_16x16x32_bf16 v[76:79], v[146:149], v[212:215], v[76:79]
	v_mfma_f32_16x16x32_bf16 v[72:75], v[150:153], v[208:211], v[72:75]
	v_mfma_f32_16x16x32_bf16 v[72:75], v[154:157], v[212:215], v[72:75]
	v_mfma_f32_16x16x32_bf16 v[116:119], v[166:169], v[184:187], v[116:119]
	v_mfma_f32_16x16x32_bf16 v[116:119], v[170:173], v[188:191], v[116:119]
	v_mfma_f32_16x16x32_bf16 v[112:115], v[176:179], v[184:187], v[112:115]
	v_mfma_f32_16x16x32_bf16 v[112:115], v[180:183], v[188:191], v[112:115]
	v_mfma_f32_16x16x32_bf16 v[100:103], v[166:169], v[192:195], v[100:103]
	v_mfma_f32_16x16x32_bf16 v[100:103], v[170:173], v[196:199], v[100:103]
	v_mfma_f32_16x16x32_bf16 v[96:99], v[176:179], v[192:195], v[96:99]
	v_mfma_f32_16x16x32_bf16 v[96:99], v[180:183], v[196:199], v[96:99]
	v_mfma_f32_16x16x32_bf16 v[84:87], v[166:169], v[200:203], v[84:87]
	v_mfma_f32_16x16x32_bf16 v[84:87], v[170:173], v[204:207], v[84:87]
	v_mfma_f32_16x16x32_bf16 v[80:83], v[176:179], v[200:203], v[80:83]
	v_mfma_f32_16x16x32_bf16 v[80:83], v[180:183], v[204:207], v[80:83]
	v_mfma_f32_16x16x32_bf16 v[68:71], v[166:169], v[208:211], v[68:71]
	v_mfma_f32_16x16x32_bf16 v[68:71], v[170:173], v[212:215], v[68:71]
	v_mfma_f32_16x16x32_bf16 v[64:67], v[176:179], v[208:211], v[64:67]
	v_mfma_f32_16x16x32_bf16 v[64:67], v[180:183], v[212:215], v[64:67]
	s_barrier
	s_add_i32 s60, s77, s0
	s_mov_b32 m0, s60
	ds_read_b128 v[184:187], v161 offset:49152
	ds_read_b128 v[188:191], v161 offset:50176
	ds_read_b128 v[192:195], v161 offset:51200
	ds_read_b128 v[196:199], v161 offset:52224
	ds_read_b128 v[200:203], v161 offset:53248
	ds_read_b128 v[204:207], v161 offset:54272
	ds_read_b128 v[208:211], v161 offset:55296
	ds_read_b128 v[212:215], v161 offset:56320
	global_load_lds_dwordx4 v130, s[98:99]
	s_add_i32 m0, s60, 0x2000
	s_add_u32 s50, s50, 0x80080
	s_addc_u32 s51, s51, 0
	s_add_i32 s60, s78, s0
	global_load_lds_dwordx4 v134, s[98:99]
	s_mov_b32 m0, s60
	s_nop 0
	global_load_lds_dwordx4 v130, s[50:51]
	s_add_i32 m0, s60, 0x2000
	s_nop 0
	global_load_lds_dwordx4 v134, s[50:51]
	s_mov_b32 m0, s15
	s_nop 0
	global_load_lds_dwordx4 v128, s[100:101]
	s_mov_b32 m0, s33
	s_nop 0
	global_load_lds_dwordx4 v132, s[100:101]
	s_waitcnt vmcnt(8)
	s_waitcnt lgkmcnt(0)
	s_barrier
	s_waitcnt lgkmcnt(0)
	v_mfma_f32_16x16x32_bf16 v[60:63], v[142:145], v[184:187], v[60:63]
	v_mfma_f32_16x16x32_bf16 v[60:63], v[146:149], v[188:191], v[60:63]
	v_mfma_f32_16x16x32_bf16 v[56:59], v[150:153], v[184:187], v[56:59]
	v_mfma_f32_16x16x32_bf16 v[56:59], v[154:157], v[188:191], v[56:59]
	v_mfma_f32_16x16x32_bf16 v[44:47], v[142:145], v[192:195], v[44:47]
	v_mfma_f32_16x16x32_bf16 v[44:47], v[146:149], v[196:199], v[44:47]
	v_mfma_f32_16x16x32_bf16 v[40:43], v[150:153], v[192:195], v[40:43]
	v_mfma_f32_16x16x32_bf16 v[40:43], v[154:157], v[196:199], v[40:43]
	v_mfma_f32_16x16x32_bf16 v[28:31], v[142:145], v[200:203], v[28:31]
	v_mfma_f32_16x16x32_bf16 v[28:31], v[146:149], v[204:207], v[28:31]
	v_mfma_f32_16x16x32_bf16 v[24:27], v[150:153], v[200:203], v[24:27]
	v_mfma_f32_16x16x32_bf16 v[24:27], v[154:157], v[204:207], v[24:27]
	v_mfma_f32_16x16x32_bf16 v[12:15], v[142:145], v[208:211], v[12:15]
	v_mfma_f32_16x16x32_bf16 v[12:15], v[146:149], v[212:215], v[12:15]
	v_mfma_f32_16x16x32_bf16 v[8:11], v[150:153], v[208:211], v[8:11]
	v_mfma_f32_16x16x32_bf16 v[8:11], v[154:157], v[212:215], v[8:11]
	v_mfma_f32_16x16x32_bf16 v[52:55], v[166:169], v[184:187], v[52:55]
	v_mfma_f32_16x16x32_bf16 v[52:55], v[170:173], v[188:191], v[52:55]
	v_mfma_f32_16x16x32_bf16 v[48:51], v[176:179], v[184:187], v[48:51]
	v_mfma_f32_16x16x32_bf16 v[48:51], v[180:183], v[188:191], v[48:51]
	v_mfma_f32_16x16x32_bf16 v[36:39], v[166:169], v[192:195], v[36:39]
	v_mfma_f32_16x16x32_bf16 v[36:39], v[170:173], v[196:199], v[36:39]
	v_mfma_f32_16x16x32_bf16 v[32:35], v[176:179], v[192:195], v[32:35]
	v_mfma_f32_16x16x32_bf16 v[32:35], v[180:183], v[196:199], v[32:35]
	v_mfma_f32_16x16x32_bf16 v[20:23], v[166:169], v[200:203], v[20:23]
	v_mfma_f32_16x16x32_bf16 v[20:23], v[170:173], v[204:207], v[20:23]
	v_mfma_f32_16x16x32_bf16 v[16:19], v[176:179], v[200:203], v[16:19]
	v_mfma_f32_16x16x32_bf16 v[16:19], v[180:183], v[204:207], v[16:19]
	v_mfma_f32_16x16x32_bf16 v[4:7], v[166:169], v[208:211], v[4:7]
	v_mfma_f32_16x16x32_bf16 v[4:7], v[170:173], v[212:215], v[4:7]
	v_mfma_f32_16x16x32_bf16 v[0:3], v[176:179], v[208:211], v[0:3]
	v_mfma_f32_16x16x32_bf16 v[0:3], v[180:183], v[212:215], v[0:3]
	s_barrier
	s_add_i32 s76, s76, 2
	s_add_u32 s48, s48, 0x100
	s_addc_u32 s49, s49, 0
	s_add_u32 s74, s74, 0x100
	s_addc_u32 s75, s75, 0
	s_cmp_gt_u32 s76, 29
	s_cbranch_scc0 .LBB0_596
	s_and_b64 vcc, exec, s[36:37]
	s_cbranch_vccz .LBB0_599
	s_barrier

.LBB0_693:
	s_add_u32 s22, s56, 0x17480000
	s_addc_u32 s23, s57, 0
	s_andn2_b64 vcc, exec, s[6:7]
	s_cbranch_vccnz .LBB0_732
	v_ashrrev_i32_e32 v1, 31, v8
	v_lshrrev_b32_e32 v1, 26, v1
	v_add_u32_e32 v1, v8, v1
	v_ashrrev_i32_e32 v9, 6, v1
	v_bfe_i32 v1, v8, 27, 1
	v_lshlrev_b32_e32 v0, 4, v8
	v_lshrrev_b32_e32 v1, 22, v1
	v_add_u32_e32 v1, v0, v1
	v_and_b32_e32 v1, 0xfffffc00, v1
	v_sub_u32_e32 v1, v0, v1
	v_lshrrev_b32_e32 v2, 4, v1
	v_bitop3_b32 v1, v2, v1, 32 bitop3:0x6c
	v_ashrrev_i32_e32 v3, 31, v1
	v_lshrrev_b32_e32 v3, 26, v3
	v_add_u32_e32 v3, v1, v3
	v_lshlrev_b32_e32 v2, 3, v9
	v_ashrrev_i32_e32 v10, 6, v3
	v_and_b32_e32 v3, 0xc0, v3
	v_and_b32_e32 v2, -16, v2
	v_sub_u32_e32 v1, v1, v3
	v_mov_b32_e32 v3, 1
	v_add_u32_e32 v2, v10, v2
	v_ashrrev_i16_sdwa v1, v3, sext(v1) dst_sel:DWORD dst_unused:UNUSED_PAD src0_sel:DWORD src1_sel:BYTE_0
	v_lshlrev_b32_e32 v4, 5, v9
	v_bfe_i32 v11, v1, 0, 16
	v_lshlrev_b32_e32 v1, 1, v2
	v_lshrrev_b32_e32 v5, 2, v2
	v_and_b32_e32 v6, 3, v10
	s_mov_b32 s0, 0x1fffe0
	v_and_b32_e32 v4, 32, v4
	v_and_b32_e32 v1, 24, v1
	v_and_b32_e32 v5, 4, v5
	v_and_or_b32 v6, v2, s0, v6
	v_or3_b32 v1, v6, v5, v1
	v_add_lshl_u32 v4, v4, v11, 1
	v_add_u32_e32 v0, 0x2000, v0
	v_lshl_add_u32 v154, v1, 11, v4
	v_ashrrev_i32_e32 v1, 31, v0
	v_lshrrev_b32_e32 v1, 22, v1
	v_add_u32_e32 v1, v0, v1
	v_ashrrev_i32_e32 v12, 10, v1
	v_mul_i32_i24_e32 v1, 0x400, v12
	v_sub_u32_e32 v0, v0, v1
	v_lshrrev_b32_e32 v1, 4, v0
	v_bitop3_b32 v0, v1, v0, 32 bitop3:0x6c
	v_lshl_add_u32 v152, v2, 11, v4
	v_ashrrev_i32_e32 v2, 31, v0
	v_lshrrev_b32_e32 v2, 26, v2
	v_add_u32_e32 v2, v0, v2
	s_lshl_b32 s1, s48, 7
	v_lshlrev_b32_e32 v1, 3, v12
	v_ashrrev_i32_e32 v13, 6, v2
	v_and_b32_e32 v2, 0xc0, v2
	s_and_b32 s1, s1, 0xfffff800
	s_lshl_b32 s14, s26, 8
	v_and_b32_e32 v1, -16, v1
	v_sub_u32_e32 v0, v0, v2
	s_add_i32 s14, s1, s14
	s_ashr_i32 s6, s27, 6
	v_add_u32_e32 v1, v13, v1
	v_ashrrev_i16_sdwa v0, v3, sext(v0) dst_sel:DWORD dst_unused:UNUSED_PAD src0_sel:DWORD src1_sel:BYTE_0
	v_and_b32_e32 v3, 3, v13
	s_ashr_i32 s49, s48, 31
	s_ashr_i32 s15, s14, 31
	v_and_or_b32 v3, v1, s0, v3
	s_ashr_i32 s7, s27, 8
	s_lshl_b32 s0, s6, 10
	s_lshl_b64 s[10:11], s[48:49], 19
	s_lshl_b64 s[14:15], s[14:15], 11
	s_add_u32 s60, s24, s14
	v_lshlrev_b32_e32 v4, 5, v12
	v_bfe_i32 v14, v0, 0, 16
	v_lshlrev_b32_e32 v0, 1, v1
	v_lshrrev_b32_e32 v2, 2, v1
	s_addc_u32 s61, s25, s15
	s_add_i32 s1, s0, 0
	v_and_b32_e32 v4, 32, v4
	v_and_b32_e32 v0, 24, v0
	v_and_b32_e32 v2, 4, v2
	s_add_i32 m0, s1, 0x10000
	v_or3_b32 v0, v3, v2, v0
	v_add_lshl_u32 v2, v4, v14, 1
	global_load_lds_dwordx4 v154, s[60:61]
	s_add_i32 m0, s1, 0x12000
	v_lshl_add_u32 v158, v0, 11, v2
	s_add_u32 s14, s60, 0x40000
	global_load_lds_dwordx4 v158, s[60:61]
	s_addc_u32 s15, s61, 0
	s_add_i32 m0, s1, 0x14000
	v_lshl_add_u32 v156, v1, 11, v2
	global_load_lds_dwordx4 v154, s[14:15]
	s_add_i32 m0, s1, 0x16000
	s_add_u32 s50, s18, s10
	s_addc_u32 s51, s19, s11
	s_add_i32 s10, s1, 0x2000
	global_load_lds_dwordx4 v158, s[14:15]
	s_mov_b32 m0, s1
	s_add_u32 s34, s50, 0x40000
	global_load_lds_dwordx4 v152, s[50:51]
	s_mov_b32 m0, s10
	s_addc_u32 s35, s51, 0
	s_add_i32 s11, s1, 0x4000
	global_load_lds_dwordx4 v156, s[50:51]
	s_mov_b32 m0, s11
	s_add_i32 s14, s1, 0x6000
	global_load_lds_dwordx4 v152, s[34:35]
	s_mov_b32 m0, s14
	v_mov_b32_e32 v155, 0
	global_load_lds_dwordx4 v156, s[34:35]
	v_mov_b32_e32 v159, v155
	v_mov_b32_e32 v153, v155
	v_mov_b32_e32 v157, v155
	s_cmp_eq_u32 s7, 1
	s_mov_b32 s41, 0
	v_lshl_add_u64 v[6:7], s[60:61], 0, v[154:155]
	v_lshl_add_u64 v[4:5], s[60:61], 0, v[158:159]
	v_lshl_add_u64 v[0:1], s[50:51], 0, v[152:153]
	s_cselect_b64 s[34:35], -1, 0
	s_cmp_lg_u32 s7, 1
	v_lshl_add_u64 v[2:3], s[50:51], 0, v[156:157]
	s_cbranch_scc1 .LBB0_696
	s_barrier
	s_setprio 1

.LBB0_707:
	ds_read_b128 v[128:131], v188
	ds_read_b128 v[132:135], v188 offset:1024
	ds_read_b128 v[136:139], v188 offset:2048
	ds_read_b128 v[140:143], v188 offset:3072
	ds_read_b128 v[144:147], v189
	ds_read_b128 v[148:151], v189 offset:1024
	ds_read_b128 v[164:167], v189 offset:2048
	ds_read_b128 v[192:195], v189 offset:3072
	s_add_u32 s60, s50, 0xfffc0080
	s_addc_u32 s61, s51, -1
	s_cmp_eq_u32 s73, 12
	s_cselect_b32 s63, s27, s61
	s_cselect_b32 s62, s41, s60
	s_cselect_b32 s61, s49, s72
	s_cselect_b32 s60, s70, s71
	s_add_i32 m0, s1, 0xc000
	ds_read_b128 v[196:199], v190
	ds_read_b128 v[200:203], v190 offset:1024
	ds_read_b128 v[204:207], v190 offset:2048
	ds_read_b128 v[208:211], v190 offset:3072
	ds_read_b128 v[212:215], v190 offset:4096
	ds_read_b128 v[216:219], v190 offset:5120
	ds_read_b128 v[220:223], v190 offset:6144
	ds_read_b128 v[224:227], v190 offset:7168
	global_load_lds_dwordx4 v160, s[50:51]
	s_add_i32 m0, s1, 0xe000
	s_nop 0
	global_load_lds_dwordx4 v162, s[50:51]
	s_waitcnt vmcnt(8)
	s_waitcnt lgkmcnt(0)
	s_barrier
	s_waitcnt lgkmcnt(0)
	v_mfma_f32_16x16x32_bf16 v[124:127], v[128:131], v[196:199], v[124:127]
	v_mfma_f32_16x16x32_bf16 v[124:127], v[132:135], v[200:203], v[124:127]
	v_mfma_f32_16x16x32_bf16 v[120:123], v[136:139], v[196:199], v[120:123]
	v_mfma_f32_16x16x32_bf16 v[120:123], v[140:143], v[200:203], v[120:123]
	v_mfma_f32_16x16x32_bf16 v[108:111], v[128:131], v[204:207], v[108:111]
	v_mfma_f32_16x16x32_bf16 v[108:111], v[132:135], v[208:211], v[108:111]
	v_mfma_f32_16x16x32_bf16 v[104:107], v[136:139], v[204:207], v[104:107]
	v_mfma_f32_16x16x32_bf16 v[104:107], v[140:143], v[208:211], v[104:107]
	v_mfma_f32_16x16x32_bf16 v[92:95], v[128:131], v[212:215], v[92:95]
	v_mfma_f32_16x16x32_bf16 v[92:95], v[132:135], v[216:219], v[92:95]
	v_mfma_f32_16x16x32_bf16 v[88:91], v[136:139], v[212:215], v[88:91]
	v_mfma_f32_16x16x32_bf16 v[88:91], v[140:143], v[216:219], v[88:91]
	v_mfma_f32_16x16x32_bf16 v[76:79], v[128:131], v[220:223], v[76:79]
	v_mfma_f32_16x16x32_bf16 v[76:79], v[132:135], v[224:227], v[76:79]
	v_mfma_f32_16x16x32_bf16 v[72:75], v[136:139], v[220:223], v[72:75]
	v_mfma_f32_16x16x32_bf16 v[72:75], v[140:143], v[224:227], v[72:75]
	v_mfma_f32_16x16x32_bf16 v[116:119], v[144:147], v[196:199], v[116:119]
	v_mfma_f32_16x16x32_bf16 v[116:119], v[148:151], v[200:203], v[116:119]
	v_mfma_f32_16x16x32_bf16 v[112:115], v[164:167], v[196:199], v[112:115]
	v_mfma_f32_16x16x32_bf16 v[112:115], v[192:195], v[200:203], v[112:115]
	v_mfma_f32_16x16x32_bf16 v[100:103], v[144:147], v[204:207], v[100:103]
	v_mfma_f32_16x16x32_bf16 v[100:103], v[148:151], v[208:211], v[100:103]
	v_mfma_f32_16x16x32_bf16 v[96:99], v[164:167], v[204:207], v[96:99]
	v_mfma_f32_16x16x32_bf16 v[96:99], v[192:195], v[208:211], v[96:99]
	v_mfma_f32_16x16x32_bf16 v[84:87], v[144:147], v[212:215], v[84:87]
	v_mfma_f32_16x16x32_bf16 v[84:87], v[148:151], v[216:219], v[84:87]
	v_mfma_f32_16x16x32_bf16 v[80:83], v[164:167], v[212:215], v[80:83]
	v_mfma_f32_16x16x32_bf16 v[80:83], v[192:195], v[216:219], v[80:83]
	v_mfma_f32_16x16x32_bf16 v[68:71], v[144:147], v[220:223], v[68:71]
	v_mfma_f32_16x16x32_bf16 v[68:71], v[148:151], v[224:227], v[68:71]
	v_mfma_f32_16x16x32_bf16 v[64:67], v[164:167], v[220:223], v[64:67]
	v_mfma_f32_16x16x32_bf16 v[64:67], v[192:195], v[224:227], v[64:67]
	s_barrier
	s_add_i32 s74, s66, s0
	s_add_u32 s98, s60, s36
	s_addc_u32 s99, s61, s37
	s_mov_b32 m0, s74
	ds_read_b128 v[196:199], v190 offset:16384
	ds_read_b128 v[200:203], v190 offset:17408
	ds_read_b128 v[204:207], v190 offset:18432
	ds_read_b128 v[208:211], v190 offset:19456
	ds_read_b128 v[212:215], v190 offset:20480
	ds_read_b128 v[216:219], v190 offset:21504
	ds_read_b128 v[220:223], v190 offset:22528
	ds_read_b128 v[224:227], v190 offset:23552
	global_load_lds_dwordx4 v154, s[60:61]
	s_add_i32 m0, s74, 0x2000
	s_add_u32 s74, s60, 0x40000
	s_addc_u32 s75, s61, 0
	s_add_i32 s76, s67, s0
	global_load_lds_dwordx4 v158, s[60:61]
	s_mov_b32 m0, s76
	s_nop 0
	global_load_lds_dwordx4 v154, s[74:75]
	s_add_i32 m0, s76, 0x2000
	s_nop 0
	global_load_lds_dwordx4 v158, s[74:75]
	s_add_u32 s100, s62, s36
	s_addc_u32 s101, s63, s37
	s_mov_b32 m0, s1
	s_nop 0
	global_load_lds_dwordx4 v152, s[62:63]
	s_mov_b32 m0, s10
	s_nop 0
	global_load_lds_dwordx4 v156, s[62:63]
	s_waitcnt vmcnt(8)
	s_waitcnt lgkmcnt(0)
	s_barrier
	s_waitcnt lgkmcnt(0)
	v_mfma_f32_16x16x32_bf16 v[60:63], v[128:131], v[196:199], v[60:63]
	v_mfma_f32_16x16x32_bf16 v[60:63], v[132:135], v[200:203], v[60:63]
	v_mfma_f32_16x16x32_bf16 v[56:59], v[136:139], v[196:199], v[56:59]
	v_mfma_f32_16x16x32_bf16 v[56:59], v[140:143], v[200:203], v[56:59]
	v_mfma_f32_16x16x32_bf16 v[44:47], v[128:131], v[204:207], v[44:47]
	v_mfma_f32_16x16x32_bf16 v[44:47], v[132:135], v[208:211], v[44:47]
	v_mfma_f32_16x16x32_bf16 v[40:43], v[136:139], v[204:207], v[40:43]
	v_mfma_f32_16x16x32_bf16 v[40:43], v[140:143], v[208:211], v[40:43]
	v_mfma_f32_16x16x32_bf16 v[28:31], v[128:131], v[212:215], v[28:31]
	v_mfma_f32_16x16x32_bf16 v[28:31], v[132:135], v[216:219], v[28:31]
	v_mfma_f32_16x16x32_bf16 v[24:27], v[136:139], v[212:215], v[24:27]
	v_mfma_f32_16x16x32_bf16 v[24:27], v[140:143], v[216:219], v[24:27]
	v_mfma_f32_16x16x32_bf16 v[12:15], v[128:131], v[220:223], v[12:15]
	v_mfma_f32_16x16x32_bf16 v[12:15], v[132:135], v[224:227], v[12:15]
	v_mfma_f32_16x16x32_bf16 v[8:11], v[136:139], v[220:223], v[8:11]
	v_mfma_f32_16x16x32_bf16 v[8:11], v[140:143], v[224:227], v[8:11]
	v_mfma_f32_16x16x32_bf16 v[52:55], v[144:147], v[196:199], v[52:55]
	v_mfma_f32_16x16x32_bf16 v[52:55], v[148:151], v[200:203], v[52:55]
	v_mfma_f32_16x16x32_bf16 v[48:51], v[164:167], v[196:199], v[48:51]
	v_mfma_f32_16x16x32_bf16 v[48:51], v[192:195], v[200:203], v[48:51]
	v_mfma_f32_16x16x32_bf16 v[36:39], v[144:147], v[204:207], v[36:39]
	v_mfma_f32_16x16x32_bf16 v[36:39], v[148:151], v[208:211], v[36:39]
	v_mfma_f32_16x16x32_bf16 v[32:35], v[164:167], v[204:207], v[32:35]
	v_mfma_f32_16x16x32_bf16 v[32:35], v[192:195], v[208:211], v[32:35]
	v_mfma_f32_16x16x32_bf16 v[20:23], v[144:147], v[212:215], v[20:23]
	v_mfma_f32_16x16x32_bf16 v[20:23], v[148:151], v[216:219], v[20:23]
	v_mfma_f32_16x16x32_bf16 v[16:19], v[164:167], v[212:215], v[16:19]
	v_mfma_f32_16x16x32_bf16 v[16:19], v[192:195], v[216:219], v[16:19]
	v_mfma_f32_16x16x32_bf16 v[4:7], v[144:147], v[220:223], v[4:7]
	v_mfma_f32_16x16x32_bf16 v[4:7], v[148:151], v[224:227], v[4:7]
	v_mfma_f32_16x16x32_bf16 v[0:3], v[164:167], v[220:223], v[0:3]
	v_mfma_f32_16x16x32_bf16 v[0:3], v[192:195], v[224:227], v[0:3]
	s_barrier
	s_add_i32 s74, 0, 0x18000
	s_add_i32 s75, 0, 0x1c000
	v_add_u32_e32 v140, s74, v171
	v_add_u32_e32 v192, s75, v171
	ds_read_b128 v[128:131], v140
	ds_read_b128 v[132:135], v140 offset:1024
	ds_read_b128 v[136:139], v140 offset:2048
	ds_read_b128 v[140:143], v140 offset:3072
	ds_read_b128 v[144:147], v192
	ds_read_b128 v[148:151], v192 offset:1024
	ds_read_b128 v[164:167], v192 offset:2048
	ds_read_b128 v[192:195], v192 offset:3072
	s_add_u32 s62, s62, 0x40000
	s_addc_u32 s63, s63, 0
	s_mov_b32 m0, s11
	ds_read_b128 v[196:199], v190 offset:32768
	ds_read_b128 v[200:203], v190 offset:33792
	ds_read_b128 v[204:207], v190 offset:34816
	ds_read_b128 v[208:211], v190 offset:35840
	ds_read_b128 v[212:215], v190 offset:36864
	ds_read_b128 v[216:219], v190 offset:37888
	ds_read_b128 v[220:223], v190 offset:38912
	ds_read_b128 v[224:227], v190 offset:39936
	global_load_lds_dwordx4 v152, s[62:63]
	s_mov_b32 m0, s14
	s_nop 0
	global_load_lds_dwordx4 v156, s[62:63]
	s_waitcnt vmcnt(8)
	s_waitcnt lgkmcnt(0)
	s_barrier
	s_waitcnt lgkmcnt(0)
	v_mfma_f32_16x16x32_bf16 v[124:127], v[128:131], v[196:199], v[124:127]
	v_mfma_f32_16x16x32_bf16 v[124:127], v[132:135], v[200:203], v[124:127]
	v_mfma_f32_16x16x32_bf16 v[120:123], v[136:139], v[196:199], v[120:123]
	v_mfma_f32_16x16x32_bf16 v[120:123], v[140:143], v[200:203], v[120:123]
	v_mfma_f32_16x16x32_bf16 v[108:111], v[128:131], v[204:207], v[108:111]
	v_mfma_f32_16x16x32_bf16 v[108:111], v[132:135], v[208:211], v[108:111]
	v_mfma_f32_16x16x32_bf16 v[104:107], v[136:139], v[204:207], v[104:107]
	v_mfma_f32_16x16x32_bf16 v[104:107], v[140:143], v[208:211], v[104:107]
	v_mfma_f32_16x16x32_bf16 v[92:95], v[128:131], v[212:215], v[92:95]
	v_mfma_f32_16x16x32_bf16 v[92:95], v[132:135], v[216:219], v[92:95]
	v_mfma_f32_16x16x32_bf16 v[88:91], v[136:139], v[212:215], v[88:91]
	v_mfma_f32_16x16x32_bf16 v[88:91], v[140:143], v[216:219], v[88:91]
	v_mfma_f32_16x16x32_bf16 v[76:79], v[128:131], v[220:223], v[76:79]
	v_mfma_f32_16x16x32_bf16 v[76:79], v[132:135], v[224:227], v[76:79]
	v_mfma_f32_16x16x32_bf16 v[72:75], v[136:139], v[220:223], v[72:75]
	v_mfma_f32_16x16x32_bf16 v[72:75], v[140:143], v[224:227], v[72:75]
	v_mfma_f32_16x16x32_bf16 v[116:119], v[144:147], v[196:199], v[116:119]
	v_mfma_f32_16x16x32_bf16 v[116:119], v[148:151], v[200:203], v[116:119]
	v_mfma_f32_16x16x32_bf16 v[112:115], v[164:167], v[196:199], v[112:115]
	v_mfma_f32_16x16x32_bf16 v[112:115], v[192:195], v[200:203], v[112:115]
	v_mfma_f32_16x16x32_bf16 v[100:103], v[144:147], v[204:207], v[100:103]
	v_mfma_f32_16x16x32_bf16 v[100:103], v[148:151], v[208:211], v[100:103]
	v_mfma_f32_16x16x32_bf16 v[96:99], v[164:167], v[204:207], v[96:99]
	v_mfma_f32_16x16x32_bf16 v[96:99], v[192:195], v[208:211], v[96:99]
	v_mfma_f32_16x16x32_bf16 v[84:87], v[144:147], v[212:215], v[84:87]
	v_mfma_f32_16x16x32_bf16 v[84:87], v[148:151], v[216:219], v[84:87]
	v_mfma_f32_16x16x32_bf16 v[80:83], v[164:167], v[212:215], v[80:83]
	v_mfma_f32_16x16x32_bf16 v[80:83], v[192:195], v[216:219], v[80:83]
	v_mfma_f32_16x16x32_bf16 v[68:71], v[144:147], v[220:223], v[68:71]
	v_mfma_f32_16x16x32_bf16 v[68:71], v[148:151], v[224:227], v[68:71]
	v_mfma_f32_16x16x32_bf16 v[64:67], v[164:167], v[220:223], v[64:67]
	v_mfma_f32_16x16x32_bf16 v[64:67], v[192:195], v[224:227], v[64:67]
	s_barrier
	s_add_i32 s62, s74, s0
	s_mov_b32 m0, s62
	ds_read_b128 v[196:199], v190 offset:49152
	ds_read_b128 v[200:203], v190 offset:50176
	ds_read_b128 v[204:207], v190 offset:51200
	ds_read_b128 v[208:211], v190 offset:52224
	ds_read_b128 v[212:215], v190 offset:53248
	ds_read_b128 v[216:219], v190 offset:54272
	ds_read_b128 v[220:223], v190 offset:55296
	ds_read_b128 v[224:227], v190 offset:56320
	global_load_lds_dwordx4 v154, s[98:99]
	s_add_i32 m0, s62, 0x2000
	s_add_u32 s60, s60, 0x40080
	s_addc_u32 s61, s61, 0
	s_add_i32 s62, s75, s0
	global_load_lds_dwordx4 v158, s[98:99]
	s_mov_b32 m0, s62
	s_nop 0
	global_load_lds_dwordx4 v154, s[60:61]
	s_add_i32 m0, s62, 0x2000
	s_nop 0
	global_load_lds_dwordx4 v158, s[60:61]
	s_mov_b32 m0, s15
	s_nop 0
	global_load_lds_dwordx4 v152, s[100:101]
	s_mov_b32 m0, s33
	s_nop 0
	global_load_lds_dwordx4 v156, s[100:101]
	s_waitcnt vmcnt(8)
	s_waitcnt lgkmcnt(0)
	s_barrier
	s_waitcnt lgkmcnt(0)
	v_mfma_f32_16x16x32_bf16 v[60:63], v[128:131], v[196:199], v[60:63]
	v_mfma_f32_16x16x32_bf16 v[60:63], v[132:135], v[200:203], v[60:63]
	v_mfma_f32_16x16x32_bf16 v[56:59], v[136:139], v[196:199], v[56:59]
	v_mfma_f32_16x16x32_bf16 v[56:59], v[140:143], v[200:203], v[56:59]
	v_mfma_f32_16x16x32_bf16 v[44:47], v[128:131], v[204:207], v[44:47]
	v_mfma_f32_16x16x32_bf16 v[44:47], v[132:135], v[208:211], v[44:47]
	v_mfma_f32_16x16x32_bf16 v[40:43], v[136:139], v[204:207], v[40:43]
	v_mfma_f32_16x16x32_bf16 v[40:43], v[140:143], v[208:211], v[40:43]
	v_mfma_f32_16x16x32_bf16 v[28:31], v[128:131], v[212:215], v[28:31]
	v_mfma_f32_16x16x32_bf16 v[28:31], v[132:135], v[216:219], v[28:31]
	v_mfma_f32_16x16x32_bf16 v[24:27], v[136:139], v[212:215], v[24:27]
	v_mfma_f32_16x16x32_bf16 v[24:27], v[140:143], v[216:219], v[24:27]
	v_mfma_f32_16x16x32_bf16 v[12:15], v[128:131], v[220:223], v[12:15]
	v_mfma_f32_16x16x32_bf16 v[12:15], v[132:135], v[224:227], v[12:15]
	v_mfma_f32_16x16x32_bf16 v[8:11], v[136:139], v[220:223], v[8:11]
	v_mfma_f32_16x16x32_bf16 v[8:11], v[140:143], v[224:227], v[8:11]
	v_mfma_f32_16x16x32_bf16 v[52:55], v[144:147], v[196:199], v[52:55]
	v_mfma_f32_16x16x32_bf16 v[52:55], v[148:151], v[200:203], v[52:55]
	v_mfma_f32_16x16x32_bf16 v[48:51], v[164:167], v[196:199], v[48:51]
	v_mfma_f32_16x16x32_bf16 v[48:51], v[192:195], v[200:203], v[48:51]
	v_mfma_f32_16x16x32_bf16 v[36:39], v[144:147], v[204:207], v[36:39]
	v_mfma_f32_16x16x32_bf16 v[36:39], v[148:151], v[208:211], v[36:39]
	v_mfma_f32_16x16x32_bf16 v[32:35], v[164:167], v[204:207], v[32:35]
	v_mfma_f32_16x16x32_bf16 v[32:35], v[192:195], v[208:211], v[32:35]
	v_mfma_f32_16x16x32_bf16 v[20:23], v[144:147], v[212:215], v[20:23]
	v_mfma_f32_16x16x32_bf16 v[20:23], v[148:151], v[216:219], v[20:23]
	v_mfma_f32_16x16x32_bf16 v[16:19], v[164:167], v[212:215], v[16:19]
	v_mfma_f32_16x16x32_bf16 v[16:19], v[192:195], v[216:219], v[16:19]
	v_mfma_f32_16x16x32_bf16 v[4:7], v[144:147], v[220:223], v[4:7]
	v_mfma_f32_16x16x32_bf16 v[4:7], v[148:151], v[224:227], v[4:7]
	v_mfma_f32_16x16x32_bf16 v[0:3], v[164:167], v[220:223], v[0:3]
	v_mfma_f32_16x16x32_bf16 v[0:3], v[192:195], v[224:227], v[0:3]
	s_barrier
	s_add_i32 s73, s73, 2
	s_add_u32 s50, s50, 0x100
	s_addc_u32 s51, s51, 0
	s_add_u32 s71, s71, 0x100
	s_addc_u32 s72, s72, 0
	s_cmp_gt_u32 s73, 13
	s_cbranch_scc0 .LBB0_707
	s_and_b64 vcc, exec, s[38:39]
	s_cbranch_vccz .LBB0_710
	s_barrier

.LBB0_856:
	v_readlane_b32 s4, v240, 27
	v_readlane_b32 s5, v240, 28
	s_and_b64 vcc, exec, s[4:5]
	s_cbranch_vccnz .LBB0_898
	v_ashrrev_i32_e32 v1, 31, v8
	v_lshrrev_b32_e32 v1, 26, v1
	v_add_u32_e32 v1, v8, v1
	v_ashrrev_i32_e32 v9, 6, v1
	v_bfe_i32 v1, v8, 27, 1
	v_lshlrev_b32_e32 v0, 4, v8
	v_lshrrev_b32_e32 v1, 22, v1
	v_add_u32_e32 v1, v0, v1
	v_and_b32_e32 v1, 0xfffffc00, v1
	v_sub_u32_e32 v1, v0, v1
	v_lshrrev_b32_e32 v2, 4, v1
	v_bitop3_b32 v1, v2, v1, 32 bitop3:0x6c
	v_ashrrev_i32_e32 v3, 31, v1
	v_lshrrev_b32_e32 v3, 26, v3
	v_lshlrev_b32_e32 v2, 3, v9
	v_add_u32_e32 v3, v1, v3
	v_and_b32_e32 v2, -16, v2
	v_ashrrev_i32_e32 v10, 6, v3
	v_and_b32_e32 v3, 0xc0, v3
	v_add_u32_e32 v2, v10, v2
	v_lshlrev_b32_e32 v4, 5, v9
	v_sub_u32_e32 v1, v1, v3
	v_mov_b32_e32 v3, 1
	v_and_b32_e32 v11, 32, v4
	v_ashrrev_i16_sdwa v1, v3, sext(v1) dst_sel:DWORD dst_unused:UNUSED_PAD src0_sel:DWORD src1_sel:BYTE_0
	v_lshlrev_b32_e32 v4, 1, v2
	v_lshrrev_b32_e32 v5, 2, v2
	v_and_b32_e32 v6, 3, v10
	s_mov_b32 s5, 0x7fffe0
	v_bfe_i32 v12, v1, 0, 16
	v_and_b32_e32 v4, 24, v4
	v_and_b32_e32 v5, 4, v5
	v_and_or_b32 v6, v2, s5, v6
	s_movk_i32 s1, 0x1600
	v_add_u32_e32 v1, v11, v12
	v_or3_b32 v4, v6, v5, v4
	v_mul_lo_u32 v2, v2, s1
	v_add_lshl_u32 v152, v1, v2, 1
	v_mul_u32_u24_e32 v2, 0x1600, v4
	v_add_u32_e32 v0, 0x2000, v0
	v_add_lshl_u32 v154, v2, v1, 1
	v_ashrrev_i32_e32 v1, 31, v0
	v_lshrrev_b32_e32 v1, 22, v1
	v_add_u32_e32 v1, v0, v1
	v_ashrrev_i32_e32 v13, 10, v1
	v_mul_i32_i24_e32 v1, 0x400, v13
	v_sub_u32_e32 v0, v0, v1
	v_lshrrev_b32_e32 v1, 4, v0
	v_bitop3_b32 v0, v1, v0, 32 bitop3:0x6c
	v_ashrrev_i32_e32 v2, 31, v0
	v_lshrrev_b32_e32 v2, 26, v2
	v_lshlrev_b32_e32 v1, 3, v13
	v_add_u32_e32 v2, v0, v2
	s_ashr_i32 s4, s0, 6
	v_and_b32_e32 v1, -16, v1
	v_ashrrev_i32_e32 v14, 6, v2
	v_and_b32_e32 v2, 0xc0, v2
	v_add_u32_e32 v1, v14, v1
	v_lshlrev_b32_e32 v4, 5, v13
	v_sub_u32_e32 v0, v0, v2
	s_ashr_i32 s6, s0, 8
	s_lshl_b32 s10, s4, 10
	s_mul_i32 s14, s8, 0x2c0000
	v_and_b32_e32 v15, 32, v4
	v_ashrrev_i16_sdwa v0, v3, sext(v0) dst_sel:DWORD dst_unused:UNUSED_PAD src0_sel:DWORD src1_sel:BYTE_0
	v_lshlrev_b32_e32 v2, 1, v1
	v_lshrrev_b32_e32 v3, 2, v1
	v_and_b32_e32 v4, 3, v14
	s_mul_hi_i32 s11, s8, 0x2c0000
	s_add_u32 s34, s16, s14
	v_bfe_i32 v16, v0, 0, 16
	v_and_b32_e32 v2, 24, v2
	v_and_b32_e32 v3, 4, v3
	v_and_or_b32 v4, v1, s5, v4
	s_addc_u32 s35, s17, s11
	s_add_i32 s11, s10, 0
	v_add_u32_e32 v0, v15, v16
	v_or3_b32 v2, v4, v3, v2
	v_mul_lo_u32 v1, v1, s1
	s_add_i32 m0, s11, 0x10000
	v_add_lshl_u32 v156, v0, v1, 1
	v_mul_u32_u24_e32 v1, 0x1600, v2
	global_load_lds_dwordx4 v154, s[34:35]
	s_add_i32 m0, s11, 0x12000
	v_add_lshl_u32 v158, v1, v0, 1
	s_add_u32 s14, s34, 0x160000
	global_load_lds_dwordx4 v158, s[34:35]
	s_addc_u32 s15, s35, 0
	s_add_i32 m0, s11, 0x14000
	s_mul_i32 s7, s9, 0x2c0000
	global_load_lds_dwordx4 v154, s[14:15]
	s_add_i32 m0, s11, 0x16000
	s_mul_hi_i32 s5, s9, 0x2c0000
	s_add_u32 s26, s12, s7
	s_addc_u32 s27, s13, s5
	s_add_i32 s33, s11, 0x2000
	global_load_lds_dwordx4 v158, s[14:15]
	s_mov_b32 m0, s11
	s_add_u32 s14, s26, 0x160000
	global_load_lds_dwordx4 v152, s[26:27]
	s_mov_b32 m0, s33
	s_addc_u32 s15, s27, 0
	s_add_i32 s40, s11, 0x4000
	global_load_lds_dwordx4 v156, s[26:27]
	s_mov_b32 m0, s40
	s_add_i32 s41, s11, 0x6000
	global_load_lds_dwordx4 v152, s[14:15]
	s_mov_b32 m0, s41
	v_mov_b32_e32 v155, 0
	global_load_lds_dwordx4 v156, s[14:15]
	v_mov_b32_e32 v159, v155
	v_mov_b32_e32 v153, v155
	v_mov_b32_e32 v157, v155
	s_cmp_eq_u32 s6, 1
	s_mov_b32 s42, 0
	v_lshl_add_u64 v[6:7], s[34:35], 0, v[154:155]
	v_lshl_add_u64 v[2:3], s[34:35], 0, v[158:159]
	s_mov_b32 s5, 0x16000
	v_lshl_add_u64 v[0:1], s[26:27], 0, v[152:153]
	s_cselect_b64 s[14:15], -1, 0
	s_cmp_lg_u32 s6, 1
	v_lshl_add_u64 v[4:5], s[26:27], 0, v[156:157]
	s_cbranch_scc1 .LBB0_859
	s_barrier
	s_setprio 1

.LBB0_873:
	ds_read_b128 v[128:131], v192
	ds_read_b128 v[132:135], v192 offset:1024
	ds_read_b128 v[136:139], v192 offset:2048
	ds_read_b128 v[140:143], v192 offset:3072
	ds_read_b128 v[144:147], v193
	ds_read_b128 v[148:151], v193 offset:1024
	ds_read_b128 v[168:171], v193 offset:2048
	ds_read_b128 v[196:199], v193 offset:3072
	s_add_u32 s34, s26, 0x100
	s_addc_u32 s35, s27, 0
	s_cmpk_eq_i32 s51, 0x54
	s_cselect_b32 s39, s1, s35
	s_cselect_b32 s38, s0, s34
	s_cselect_b32 s37, s25, s50
	s_cselect_b32 s36, s24, s49
	v_lshl_add_u64 v[172:173], s[26:27], 0, v[160:161]
	s_add_i32 m0, s11, 0xc000
	ds_read_b128 v[200:203], v194
	ds_read_b128 v[204:207], v194 offset:1024
	ds_read_b128 v[208:211], v194 offset:2048
	ds_read_b128 v[212:215], v194 offset:3072
	ds_read_b128 v[216:219], v194 offset:4096
	ds_read_b128 v[220:223], v194 offset:5120
	ds_read_b128 v[224:227], v194 offset:6144
	ds_read_b128 v[228:231], v194 offset:7168
	global_load_lds_dwordx4 v[172:173], off
	v_lshl_add_u64 v[172:173], s[26:27], 0, v[162:163]
	s_add_i32 m0, s11, 0xe000
	s_nop 0
	global_load_lds_dwordx4 v[172:173], off
	s_waitcnt vmcnt(8)
	s_waitcnt lgkmcnt(0)
	s_barrier
	s_waitcnt lgkmcnt(0)
	v_mfma_f32_16x16x32_bf16 v[124:127], v[128:131], v[200:203], v[124:127]
	v_mfma_f32_16x16x32_bf16 v[124:127], v[132:135], v[204:207], v[124:127]
	v_mfma_f32_16x16x32_bf16 v[120:123], v[136:139], v[200:203], v[120:123]
	v_mfma_f32_16x16x32_bf16 v[120:123], v[140:143], v[204:207], v[120:123]
	v_mfma_f32_16x16x32_bf16 v[108:111], v[128:131], v[208:211], v[108:111]
	v_mfma_f32_16x16x32_bf16 v[108:111], v[132:135], v[212:215], v[108:111]
	v_mfma_f32_16x16x32_bf16 v[104:107], v[136:139], v[208:211], v[104:107]
	v_mfma_f32_16x16x32_bf16 v[104:107], v[140:143], v[212:215], v[104:107]
	v_mfma_f32_16x16x32_bf16 v[92:95], v[128:131], v[216:219], v[92:95]
	v_mfma_f32_16x16x32_bf16 v[92:95], v[132:135], v[220:223], v[92:95]
	v_mfma_f32_16x16x32_bf16 v[88:91], v[136:139], v[216:219], v[88:91]
	v_mfma_f32_16x16x32_bf16 v[88:91], v[140:143], v[220:223], v[88:91]
	v_mfma_f32_16x16x32_bf16 v[76:79], v[128:131], v[224:227], v[76:79]
	v_mfma_f32_16x16x32_bf16 v[76:79], v[132:135], v[228:231], v[76:79]
	v_mfma_f32_16x16x32_bf16 v[72:75], v[136:139], v[224:227], v[72:75]
	v_mfma_f32_16x16x32_bf16 v[72:75], v[140:143], v[228:231], v[72:75]
	v_mfma_f32_16x16x32_bf16 v[116:119], v[144:147], v[200:203], v[116:119]
	v_mfma_f32_16x16x32_bf16 v[116:119], v[148:151], v[204:207], v[116:119]
	v_mfma_f32_16x16x32_bf16 v[112:115], v[168:171], v[200:203], v[112:115]
	v_mfma_f32_16x16x32_bf16 v[112:115], v[196:199], v[204:207], v[112:115]
	v_mfma_f32_16x16x32_bf16 v[100:103], v[144:147], v[208:211], v[100:103]
	v_mfma_f32_16x16x32_bf16 v[100:103], v[148:151], v[212:215], v[100:103]
	v_mfma_f32_16x16x32_bf16 v[96:99], v[168:171], v[208:211], v[96:99]
	v_mfma_f32_16x16x32_bf16 v[96:99], v[196:199], v[212:215], v[96:99]
	v_mfma_f32_16x16x32_bf16 v[84:87], v[144:147], v[216:219], v[84:87]
	v_mfma_f32_16x16x32_bf16 v[84:87], v[148:151], v[220:223], v[84:87]
	v_mfma_f32_16x16x32_bf16 v[80:83], v[168:171], v[216:219], v[80:83]
	v_mfma_f32_16x16x32_bf16 v[80:83], v[196:199], v[220:223], v[80:83]
	v_mfma_f32_16x16x32_bf16 v[68:71], v[144:147], v[224:227], v[68:71]
	v_mfma_f32_16x16x32_bf16 v[68:71], v[148:151], v[228:231], v[68:71]
	v_mfma_f32_16x16x32_bf16 v[64:67], v[168:171], v[224:227], v[64:67]
	v_mfma_f32_16x16x32_bf16 v[64:67], v[196:199], v[228:231], v[64:67]
	s_barrier
	s_add_i32 s26, s45, s10
	v_lshl_add_u64 v[172:173], s[36:37], 0, v[154:155]
	s_mov_b32 m0, s26
	ds_read_b128 v[200:203], v194 offset:16384
	ds_read_b128 v[204:207], v194 offset:17408
	ds_read_b128 v[208:211], v194 offset:18432
	ds_read_b128 v[212:215], v194 offset:19456
	ds_read_b128 v[216:219], v194 offset:20480
	ds_read_b128 v[220:223], v194 offset:21504
	ds_read_b128 v[224:227], v194 offset:22528
	ds_read_b128 v[228:231], v194 offset:23552
	global_load_lds_dwordx4 v[172:173], off
	s_add_i32 m0, s26, 0x2000
	s_add_u32 s26, s36, 0x160000
	v_lshl_add_u64 v[232:233], s[36:37], 0, v[158:159]
	s_addc_u32 s27, s37, 0
	s_add_i32 s60, s46, s10
	global_load_lds_dwordx4 v[232:233], off
	v_lshl_add_u64 v[234:235], s[26:27], 0, v[154:155]
	s_mov_b32 m0, s60
	v_lshl_add_u64 v[236:237], s[38:39], 0, v[156:157]
	global_load_lds_dwordx4 v[234:235], off
	v_lshl_add_u64 v[234:235], s[26:27], 0, v[158:159]
	s_add_i32 m0, s60, 0x2000
	s_nop 0
	global_load_lds_dwordx4 v[234:235], off
	v_lshl_add_u64 v[234:235], s[38:39], 0, v[152:153]
	s_mov_b32 m0, s11
	s_nop 0
	global_load_lds_dwordx4 v[234:235], off
	s_mov_b32 m0, s33
	s_nop 0
	global_load_lds_dwordx4 v[236:237], off
	s_waitcnt vmcnt(8)
	s_waitcnt lgkmcnt(0)
	s_barrier
	s_waitcnt lgkmcnt(0)
	v_mfma_f32_16x16x32_bf16 v[60:63], v[128:131], v[200:203], v[60:63]
	v_mfma_f32_16x16x32_bf16 v[60:63], v[132:135], v[204:207], v[60:63]
	v_mfma_f32_16x16x32_bf16 v[56:59], v[136:139], v[200:203], v[56:59]
	v_mfma_f32_16x16x32_bf16 v[56:59], v[140:143], v[204:207], v[56:59]
	v_mfma_f32_16x16x32_bf16 v[44:47], v[128:131], v[208:211], v[44:47]
	v_mfma_f32_16x16x32_bf16 v[44:47], v[132:135], v[212:215], v[44:47]
	v_mfma_f32_16x16x32_bf16 v[40:43], v[136:139], v[208:211], v[40:43]
	v_mfma_f32_16x16x32_bf16 v[40:43], v[140:143], v[212:215], v[40:43]
	v_mfma_f32_16x16x32_bf16 v[28:31], v[128:131], v[216:219], v[28:31]
	v_mfma_f32_16x16x32_bf16 v[28:31], v[132:135], v[220:223], v[28:31]
	v_mfma_f32_16x16x32_bf16 v[24:27], v[136:139], v[216:219], v[24:27]
	v_mfma_f32_16x16x32_bf16 v[24:27], v[140:143], v[220:223], v[24:27]
	v_mfma_f32_16x16x32_bf16 v[12:15], v[128:131], v[224:227], v[12:15]
	v_mfma_f32_16x16x32_bf16 v[12:15], v[132:135], v[228:231], v[12:15]
	v_mfma_f32_16x16x32_bf16 v[8:11], v[136:139], v[224:227], v[8:11]
	v_mfma_f32_16x16x32_bf16 v[8:11], v[140:143], v[228:231], v[8:11]
	v_mfma_f32_16x16x32_bf16 v[52:55], v[144:147], v[200:203], v[52:55]
	v_mfma_f32_16x16x32_bf16 v[52:55], v[148:151], v[204:207], v[52:55]
	v_mfma_f32_16x16x32_bf16 v[48:51], v[168:171], v[200:203], v[48:51]
	v_mfma_f32_16x16x32_bf16 v[48:51], v[196:199], v[204:207], v[48:51]
	v_mfma_f32_16x16x32_bf16 v[36:39], v[144:147], v[208:211], v[36:39]
	v_mfma_f32_16x16x32_bf16 v[36:39], v[148:151], v[212:215], v[36:39]
	v_mfma_f32_16x16x32_bf16 v[32:35], v[168:171], v[208:211], v[32:35]
	v_mfma_f32_16x16x32_bf16 v[32:35], v[196:199], v[212:215], v[32:35]
	v_mfma_f32_16x16x32_bf16 v[20:23], v[144:147], v[216:219], v[20:23]
	v_mfma_f32_16x16x32_bf16 v[20:23], v[148:151], v[220:223], v[20:23]
	v_mfma_f32_16x16x32_bf16 v[16:19], v[168:171], v[216:219], v[16:19]
	v_mfma_f32_16x16x32_bf16 v[16:19], v[196:199], v[220:223], v[16:19]
	v_mfma_f32_16x16x32_bf16 v[4:7], v[144:147], v[224:227], v[4:7]
	v_mfma_f32_16x16x32_bf16 v[4:7], v[148:151], v[228:231], v[4:7]
	v_mfma_f32_16x16x32_bf16 v[0:3], v[168:171], v[224:227], v[0:3]
	v_mfma_f32_16x16x32_bf16 v[0:3], v[196:199], v[228:231], v[0:3]
	s_barrier
	s_add_i32 s60, 0, 0x18000
	s_add_i32 s61, 0, 0x1c000
	v_add_u32_e32 v140, s60, v177
	v_add_u32_e32 v196, s61, v177
	ds_read_b128 v[128:131], v140
	ds_read_b128 v[132:135], v140 offset:1024
	ds_read_b128 v[136:139], v140 offset:2048
	ds_read_b128 v[140:143], v140 offset:3072
	ds_read_b128 v[144:147], v196
	ds_read_b128 v[148:151], v196 offset:1024
	ds_read_b128 v[168:171], v196 offset:2048
	ds_read_b128 v[196:199], v196 offset:3072
	s_add_u32 s26, s38, 0x160000
	s_addc_u32 s27, s39, 0
	s_mov_b32 m0, s40
	v_lshl_add_u64 v[238:239], s[26:27], 0, v[152:153]
	ds_read_b128 v[200:203], v194 offset:32768
	ds_read_b128 v[204:207], v194 offset:33792
	ds_read_b128 v[208:211], v194 offset:34816
	ds_read_b128 v[212:215], v194 offset:35840
	ds_read_b128 v[216:219], v194 offset:36864
	ds_read_b128 v[220:223], v194 offset:37888
	ds_read_b128 v[224:227], v194 offset:38912
	ds_read_b128 v[228:231], v194 offset:39936
	global_load_lds_dwordx4 v[238:239], off
	v_lshl_add_u64 v[238:239], s[26:27], 0, v[156:157]
	s_mov_b32 m0, s41
	s_nop 0
	global_load_lds_dwordx4 v[238:239], off
	s_waitcnt vmcnt(8)
	s_waitcnt lgkmcnt(0)
	s_barrier
	s_waitcnt lgkmcnt(0)
	v_mfma_f32_16x16x32_bf16 v[124:127], v[128:131], v[200:203], v[124:127]
	v_mfma_f32_16x16x32_bf16 v[124:127], v[132:135], v[204:207], v[124:127]
	v_mfma_f32_16x16x32_bf16 v[120:123], v[136:139], v[200:203], v[120:123]
	v_mfma_f32_16x16x32_bf16 v[120:123], v[140:143], v[204:207], v[120:123]
	v_mfma_f32_16x16x32_bf16 v[108:111], v[128:131], v[208:211], v[108:111]
	v_mfma_f32_16x16x32_bf16 v[108:111], v[132:135], v[212:215], v[108:111]
	v_mfma_f32_16x16x32_bf16 v[104:107], v[136:139], v[208:211], v[104:107]
	v_mfma_f32_16x16x32_bf16 v[104:107], v[140:143], v[212:215], v[104:107]
	v_mfma_f32_16x16x32_bf16 v[92:95], v[128:131], v[216:219], v[92:95]
	v_mfma_f32_16x16x32_bf16 v[92:95], v[132:135], v[220:223], v[92:95]
	v_mfma_f32_16x16x32_bf16 v[88:91], v[136:139], v[216:219], v[88:91]
	v_mfma_f32_16x16x32_bf16 v[88:91], v[140:143], v[220:223], v[88:91]
	v_mfma_f32_16x16x32_bf16 v[76:79], v[128:131], v[224:227], v[76:79]
	v_mfma_f32_16x16x32_bf16 v[76:79], v[132:135], v[228:231], v[76:79]
	v_mfma_f32_16x16x32_bf16 v[72:75], v[136:139], v[224:227], v[72:75]
	v_mfma_f32_16x16x32_bf16 v[72:75], v[140:143], v[228:231], v[72:75]
	v_mfma_f32_16x16x32_bf16 v[116:119], v[144:147], v[200:203], v[116:119]
	v_mfma_f32_16x16x32_bf16 v[116:119], v[148:151], v[204:207], v[116:119]
	v_mfma_f32_16x16x32_bf16 v[112:115], v[168:171], v[200:203], v[112:115]
	v_mfma_f32_16x16x32_bf16 v[112:115], v[196:199], v[204:207], v[112:115]
	v_mfma_f32_16x16x32_bf16 v[100:103], v[144:147], v[208:211], v[100:103]
	v_mfma_f32_16x16x32_bf16 v[100:103], v[148:151], v[212:215], v[100:103]
	v_mfma_f32_16x16x32_bf16 v[96:99], v[168:171], v[208:211], v[96:99]
	v_mfma_f32_16x16x32_bf16 v[96:99], v[196:199], v[212:215], v[96:99]
	v_mfma_f32_16x16x32_bf16 v[84:87], v[144:147], v[216:219], v[84:87]
	v_mfma_f32_16x16x32_bf16 v[84:87], v[148:151], v[220:223], v[84:87]
	v_mfma_f32_16x16x32_bf16 v[80:83], v[168:171], v[216:219], v[80:83]
	v_mfma_f32_16x16x32_bf16 v[80:83], v[196:199], v[220:223], v[80:83]
	v_mfma_f32_16x16x32_bf16 v[68:71], v[144:147], v[224:227], v[68:71]
	v_mfma_f32_16x16x32_bf16 v[68:71], v[148:151], v[228:231], v[68:71]
	v_mfma_f32_16x16x32_bf16 v[64:67], v[168:171], v[224:227], v[64:67]
	v_mfma_f32_16x16x32_bf16 v[64:67], v[196:199], v[228:231], v[64:67]
	s_barrier
	s_add_i32 s26, s60, s10
	v_lshl_add_u64 v[172:173], v[172:173], 0, s[20:21]
	s_mov_b32 m0, s26
	ds_read_b128 v[200:203], v194 offset:49152
	ds_read_b128 v[204:207], v194 offset:50176
	ds_read_b128 v[208:211], v194 offset:51200
	ds_read_b128 v[212:215], v194 offset:52224
	ds_read_b128 v[216:219], v194 offset:53248
	ds_read_b128 v[220:223], v194 offset:54272
	ds_read_b128 v[224:227], v194 offset:55296
	ds_read_b128 v[228:231], v194 offset:56320
	global_load_lds_dwordx4 v[172:173], off
	s_add_i32 m0, s26, 0x2000
	s_add_u32 s26, s36, 0x160080
	v_lshl_add_u64 v[172:173], v[232:233], 0, s[20:21]
	s_addc_u32 s27, s37, 0
	s_add_i32 s36, s61, s10
	global_load_lds_dwordx4 v[172:173], off
	v_lshl_add_u64 v[172:173], s[26:27], 0, v[154:155]
	s_mov_b32 m0, s36
	s_nop 0
	global_load_lds_dwordx4 v[172:173], off
	v_lshl_add_u64 v[172:173], s[26:27], 0, v[158:159]
	s_add_i32 m0, s36, 0x2000
	s_nop 0
	global_load_lds_dwordx4 v[172:173], off
	v_lshl_add_u64 v[172:173], v[234:235], 0, s[20:21]
	s_mov_b32 m0, s43
	s_nop 0
	global_load_lds_dwordx4 v[172:173], off
	v_lshl_add_u64 v[172:173], v[236:237], 0, s[20:21]
	s_mov_b32 m0, s44
	s_nop 0
	global_load_lds_dwordx4 v[172:173], off
	s_waitcnt vmcnt(8)
	s_waitcnt lgkmcnt(0)
	s_barrier
	s_waitcnt lgkmcnt(0)
	v_mfma_f32_16x16x32_bf16 v[60:63], v[128:131], v[200:203], v[60:63]
	v_mfma_f32_16x16x32_bf16 v[60:63], v[132:135], v[204:207], v[60:63]
	v_mfma_f32_16x16x32_bf16 v[56:59], v[136:139], v[200:203], v[56:59]
	v_mfma_f32_16x16x32_bf16 v[56:59], v[140:143], v[204:207], v[56:59]
	v_mfma_f32_16x16x32_bf16 v[44:47], v[128:131], v[208:211], v[44:47]
	v_mfma_f32_16x16x32_bf16 v[44:47], v[132:135], v[212:215], v[44:47]
	v_mfma_f32_16x16x32_bf16 v[40:43], v[136:139], v[208:211], v[40:43]
	v_mfma_f32_16x16x32_bf16 v[40:43], v[140:143], v[212:215], v[40:43]
	v_mfma_f32_16x16x32_bf16 v[28:31], v[128:131], v[216:219], v[28:31]
	v_mfma_f32_16x16x32_bf16 v[28:31], v[132:135], v[220:223], v[28:31]
	v_mfma_f32_16x16x32_bf16 v[24:27], v[136:139], v[216:219], v[24:27]
	v_mfma_f32_16x16x32_bf16 v[24:27], v[140:143], v[220:223], v[24:27]
	v_mfma_f32_16x16x32_bf16 v[12:15], v[128:131], v[224:227], v[12:15]
	v_mfma_f32_16x16x32_bf16 v[12:15], v[132:135], v[228:231], v[12:15]
	v_mfma_f32_16x16x32_bf16 v[8:11], v[136:139], v[224:227], v[8:11]
	v_mfma_f32_16x16x32_bf16 v[8:11], v[140:143], v[228:231], v[8:11]
	v_mfma_f32_16x16x32_bf16 v[52:55], v[144:147], v[200:203], v[52:55]
	v_mfma_f32_16x16x32_bf16 v[52:55], v[148:151], v[204:207], v[52:55]
	v_mfma_f32_16x16x32_bf16 v[48:51], v[168:171], v[200:203], v[48:51]
	v_mfma_f32_16x16x32_bf16 v[48:51], v[196:199], v[204:207], v[48:51]
	v_mfma_f32_16x16x32_bf16 v[36:39], v[144:147], v[208:211], v[36:39]
	v_mfma_f32_16x16x32_bf16 v[36:39], v[148:151], v[212:215], v[36:39]
	v_mfma_f32_16x16x32_bf16 v[32:35], v[168:171], v[208:211], v[32:35]
	v_mfma_f32_16x16x32_bf16 v[32:35], v[196:199], v[212:215], v[32:35]
	v_mfma_f32_16x16x32_bf16 v[20:23], v[144:147], v[216:219], v[20:23]
	v_mfma_f32_16x16x32_bf16 v[20:23], v[148:151], v[220:223], v[20:23]
	v_mfma_f32_16x16x32_bf16 v[16:19], v[168:171], v[216:219], v[16:19]
	v_mfma_f32_16x16x32_bf16 v[16:19], v[196:199], v[220:223], v[16:19]
	v_mfma_f32_16x16x32_bf16 v[4:7], v[144:147], v[224:227], v[4:7]
	v_mfma_f32_16x16x32_bf16 v[4:7], v[148:151], v[228:231], v[4:7]
	v_mfma_f32_16x16x32_bf16 v[0:3], v[168:171], v[224:227], v[0:3]
	v_mfma_f32_16x16x32_bf16 v[0:3], v[196:199], v[228:231], v[0:3]
	s_barrier
	s_add_i32 s51, s51, 2
	s_add_u32 s49, s49, 0x100
	s_addc_u32 s50, s50, 0
	s_cmpk_gt_u32 s51, 0x55
	s_mov_b64 s[26:27], s[34:35]
	s_cbranch_scc0 .LBB0_873
	s_and_b64 vcc, exec, s[22:23]
	s_cbranch_vccz .LBB0_876
	s_barrier

.LBB0_966:
	s_and_b64 vcc, exec, s[4:5]
	s_cbranch_vccz .LBB0_1014
	s_mov_b32 s3, 0x7fffe0
	v_ashrrev_i32_e32 v1, 31, v174
	v_lshrrev_b32_e32 v1, 26, v1
	v_add_u32_e32 v1, v174, v1
	v_ashrrev_i32_e32 v8, 6, v1
	v_bfe_i32 v1, v174, 27, 1
	v_lshlrev_b32_e32 v0, 4, v174
	v_lshrrev_b32_e32 v1, 22, v1
	v_add_u32_e32 v1, v0, v1
	v_and_b32_e32 v1, 0xfffffc00, v1
	v_sub_u32_e32 v1, v0, v1
	v_lshrrev_b32_e32 v2, 4, v1
	v_bitop3_b32 v1, v2, v1, 32 bitop3:0x6c
	v_ashrrev_i32_e32 v3, 31, v1
	v_lshrrev_b32_e32 v3, 26, v3
	v_lshlrev_b32_e32 v2, 3, v8
	v_add_u32_e32 v3, v1, v3
	v_and_b32_e32 v2, -16, v2
	v_ashrrev_i32_e32 v9, 6, v3
	v_and_b32_e32 v3, 0xc0, v3
	v_add_u32_e32 v2, v9, v2
	v_lshlrev_b32_e32 v4, 5, v8
	v_sub_u32_e32 v1, v1, v3
	v_mov_b32_e32 v3, 1
	v_and_b32_e32 v10, 32, v4
	v_ashrrev_i16_sdwa v1, v3, sext(v1) dst_sel:DWORD dst_unused:UNUSED_PAD src0_sel:DWORD src1_sel:BYTE_0
	v_lshlrev_b32_e32 v4, 1, v2
	v_lshrrev_b32_e32 v5, 2, v2
	v_and_b32_e32 v6, 3, v9
	v_bfe_i32 v11, v1, 0, 16
	v_and_b32_e32 v4, 24, v4
	v_and_b32_e32 v5, 4, v5
	v_and_or_b32 v6, v2, s3, v6
	s_movk_i32 s1, 0x1600
	v_add_u32_e32 v1, v10, v11
	v_or3_b32 v4, v6, v5, v4
	v_mul_lo_u32 v2, v2, s1
	v_add_lshl_u32 v152, v1, v2, 1
	v_mul_u32_u24_e32 v2, 0x1600, v4
	v_add_u32_e32 v0, 0x2000, v0
	v_add_lshl_u32 v154, v2, v1, 1
	v_ashrrev_i32_e32 v1, 31, v0
	v_lshrrev_b32_e32 v1, 22, v1
	v_add_u32_e32 v1, v0, v1
	v_ashrrev_i32_e32 v12, 10, v1
	v_mul_i32_i24_e32 v1, 0x400, v12
	v_sub_u32_e32 v0, v0, v1
	v_lshrrev_b32_e32 v1, 4, v0
	v_bitop3_b32 v0, v1, v0, 32 bitop3:0x6c
	v_ashrrev_i32_e32 v2, 31, v0
	v_lshrrev_b32_e32 v2, 26, v2
	v_lshlrev_b32_e32 v1, 3, v12
	v_add_u32_e32 v2, v0, v2
	v_and_b32_e32 v1, -16, v1
	v_ashrrev_i32_e32 v13, 6, v2
	v_lshlrev_b32_e32 v4, 5, v12
	v_add_u32_e32 v1, v13, v1
	v_and_b32_e32 v14, 32, v4
	v_and_b32_e32 v4, 3, v13
	v_readfirstlane_b32 s0, v174
	v_and_or_b32 v4, v1, s3, v4
	s_lshl_b32 s3, s2, 2
	s_ashr_i32 s6, s0, 6
	v_and_b32_e32 v2, 0xc0, v2
	s_and_b32 s30, s3, 28
	s_ashr_i32 s3, s2, 6
	s_bfe_u32 s14, s2, 0x30003
	v_sub_u32_e32 v0, v0, v2
	s_ashr_i32 s10, s0, 8
	s_add_i32 s30, s30, s3
	s_lshl_b32 s31, s6, 10
	s_mul_i32 s2, s14, 0x2c0000
	v_ashrrev_i16_sdwa v0, v3, sext(v0) dst_sel:DWORD dst_unused:UNUSED_PAD src0_sel:DWORD src1_sel:BYTE_0
	v_lshlrev_b32_e32 v2, 1, v1
	v_lshrrev_b32_e32 v3, 2, v1
	s_add_u32 s2, s16, s2
	v_bfe_i32 v15, v0, 0, 16
	v_and_b32_e32 v2, 24, v2
	v_and_b32_e32 v3, 4, v3
	s_addc_u32 s3, s17, 0
	s_add_i32 s33, s31, 0
	v_add_u32_e32 v0, v14, v15
	v_or3_b32 v2, v4, v3, v2
	v_mul_lo_u32 v1, v1, s1
	s_add_i32 m0, s33, 0x10000
	v_add_lshl_u32 v156, v0, v1, 1
	v_mul_u32_u24_e32 v1, 0x1600, v2
	global_load_lds_dwordx4 v154, s[2:3]
	s_add_i32 m0, s33, 0x12000
	v_add_lshl_u32 v158, v1, v0, 1
	s_add_u32 s4, s2, 0x160000
	global_load_lds_dwordx4 v158, s[2:3]
	s_addc_u32 s5, s3, 0
	s_add_i32 m0, s33, 0x14000
	s_mul_i32 s8, s30, 0x2c0000
	global_load_lds_dwordx4 v154, s[4:5]
	s_add_i32 m0, s33, 0x16000
	s_mul_hi_i32 s7, s30, 0x2c0000
	s_add_u32 s20, s12, s8
	s_addc_u32 s21, s13, s7
	s_add_i32 s34, s33, 0x2000
	global_load_lds_dwordx4 v158, s[4:5]
	s_mov_b32 m0, s33
	s_add_u32 s4, s20, 0x160000
	global_load_lds_dwordx4 v152, s[20:21]
	s_mov_b32 m0, s34
	s_addc_u32 s5, s21, 0
	s_add_i32 s35, s33, 0x4000
	global_load_lds_dwordx4 v156, s[20:21]
	s_mov_b32 m0, s35
	s_add_i32 s36, s33, 0x6000
	global_load_lds_dwordx4 v152, s[4:5]
	s_mov_b32 m0, s36
	v_mov_b32_e32 v161, 0
	global_load_lds_dwordx4 v156, s[4:5]
	v_mov_b32_e32 v155, v161
	v_mov_b32_e32 v159, v161
	v_mov_b32_e32 v153, v161
	v_mov_b32_e32 v157, v161
	s_cmp_eq_u32 s10, 1
	s_mov_b32 s24, 32
	v_lshl_add_u64 v[6:7], s[2:3], 0, v[154:155]
	v_lshl_add_u64 v[2:3], s[2:3], 0, v[158:159]
	s_mov_b32 s16, 0x16000
	v_lshl_add_u64 v[0:1], s[20:21], 0, v[152:153]
	s_cselect_b64 s[4:5], -1, 0
	s_cmp_lg_u32 s10, 1
	v_lshl_add_u64 v[4:5], s[20:21], 0, v[156:157]
	s_cbranch_scc1 .LBB0_969
	s_barrier
	s_setprio 1

.LBB0_975:
	ds_read_b128 v[132:135], v179
	ds_read_b128 v[136:139], v179 offset:1024
	ds_read_b128 v[140:143], v179 offset:2048
	ds_read_b128 v[144:147], v179 offset:3072
	ds_read_b128 v[148:151], v180
	ds_read_b128 v[166:169], v180 offset:1024
	ds_read_b128 v[170:173], v180 offset:2048
	ds_read_b128 v[174:177], v180 offset:3072
	s_add_u32 s22, s20, 0x100
	s_addc_u32 s23, s21, 0
	s_add_u32 s24, s62, s20
	s_addc_u32 s25, s63, s21
	s_cmpk_eq_i32 s64, 0x54
	s_cselect_b32 s26, s16, s24
	s_cselect_b32 s24, 0, s22
	s_cselect_b32 s27, s17, s25
	s_cselect_b32 s25, 0, s23
	s_add_u32 s24, s2, s24
	s_addc_u32 s25, s3, s25
	s_mov_b32 m0, s57
	v_lshl_add_u64 v[218:219], v[128:129], 0, s[20:21]
	ds_read_b128 v[186:189], v181
	ds_read_b128 v[190:193], v181 offset:1024
	ds_read_b128 v[194:197], v181 offset:2048
	ds_read_b128 v[198:201], v181 offset:3072
	ds_read_b128 v[202:205], v181 offset:4096
	ds_read_b128 v[206:209], v181 offset:5120
	ds_read_b128 v[210:213], v181 offset:6144
	ds_read_b128 v[214:217], v181 offset:7168
	global_load_lds_dwordx4 v[218:219], off
	v_lshl_add_u64 v[218:219], v[130:131], 0, s[20:21]
	s_mov_b32 m0, s58
	s_nop 0
	global_load_lds_dwordx4 v[218:219], off
	s_waitcnt vmcnt(8)
	s_waitcnt lgkmcnt(0)
	s_barrier
	s_waitcnt lgkmcnt(0)
	v_mfma_f32_16x16x32_bf16 v[124:127], v[132:135], v[186:189], v[124:127]
	v_mfma_f32_16x16x32_bf16 v[124:127], v[136:139], v[190:193], v[124:127]
	v_mfma_f32_16x16x32_bf16 v[120:123], v[140:143], v[186:189], v[120:123]
	v_mfma_f32_16x16x32_bf16 v[120:123], v[144:147], v[190:193], v[120:123]
	v_mfma_f32_16x16x32_bf16 v[108:111], v[132:135], v[194:197], v[108:111]
	v_mfma_f32_16x16x32_bf16 v[108:111], v[136:139], v[198:201], v[108:111]
	v_mfma_f32_16x16x32_bf16 v[104:107], v[140:143], v[194:197], v[104:107]
	v_mfma_f32_16x16x32_bf16 v[104:107], v[144:147], v[198:201], v[104:107]
	v_mfma_f32_16x16x32_bf16 v[92:95], v[132:135], v[202:205], v[92:95]
	v_mfma_f32_16x16x32_bf16 v[92:95], v[136:139], v[206:209], v[92:95]
	v_mfma_f32_16x16x32_bf16 v[88:91], v[140:143], v[202:205], v[88:91]
	v_mfma_f32_16x16x32_bf16 v[88:91], v[144:147], v[206:209], v[88:91]
	v_mfma_f32_16x16x32_bf16 v[76:79], v[132:135], v[210:213], v[76:79]
	v_mfma_f32_16x16x32_bf16 v[76:79], v[136:139], v[214:217], v[76:79]
	v_mfma_f32_16x16x32_bf16 v[72:75], v[140:143], v[210:213], v[72:75]
	v_mfma_f32_16x16x32_bf16 v[72:75], v[144:147], v[214:217], v[72:75]
	v_mfma_f32_16x16x32_bf16 v[116:119], v[148:151], v[186:189], v[116:119]
	v_mfma_f32_16x16x32_bf16 v[116:119], v[166:169], v[190:193], v[116:119]
	v_mfma_f32_16x16x32_bf16 v[112:115], v[170:173], v[186:189], v[112:115]
	v_mfma_f32_16x16x32_bf16 v[112:115], v[174:177], v[190:193], v[112:115]
	v_mfma_f32_16x16x32_bf16 v[100:103], v[148:151], v[194:197], v[100:103]
	v_mfma_f32_16x16x32_bf16 v[100:103], v[166:169], v[198:201], v[100:103]
	v_mfma_f32_16x16x32_bf16 v[96:99], v[170:173], v[194:197], v[96:99]
	v_mfma_f32_16x16x32_bf16 v[96:99], v[174:177], v[198:201], v[96:99]
	v_mfma_f32_16x16x32_bf16 v[84:87], v[148:151], v[202:205], v[84:87]
	v_mfma_f32_16x16x32_bf16 v[84:87], v[166:169], v[206:209], v[84:87]
	v_mfma_f32_16x16x32_bf16 v[80:83], v[170:173], v[202:205], v[80:83]
	v_mfma_f32_16x16x32_bf16 v[80:83], v[174:177], v[206:209], v[80:83]
	v_mfma_f32_16x16x32_bf16 v[68:71], v[148:151], v[210:213], v[68:71]
	v_mfma_f32_16x16x32_bf16 v[68:71], v[166:169], v[214:217], v[68:71]
	v_mfma_f32_16x16x32_bf16 v[64:67], v[170:173], v[210:213], v[64:67]
	v_mfma_f32_16x16x32_bf16 v[64:67], v[174:177], v[214:217], v[64:67]
	s_barrier
	s_mov_b32 m0, s59
	s_add_u32 s98, s24, s6
	s_addc_u32 s99, s25, s7
	ds_read_b128 v[186:189], v181 offset:16384
	ds_read_b128 v[190:193], v181 offset:17408
	ds_read_b128 v[194:197], v181 offset:18432
	ds_read_b128 v[198:201], v181 offset:19456
	ds_read_b128 v[202:205], v181 offset:20480
	ds_read_b128 v[206:209], v181 offset:21504
	ds_read_b128 v[210:213], v181 offset:22528
	ds_read_b128 v[214:217], v181 offset:23552
	global_load_lds_dwordx4 v154, s[24:25]
	s_add_i32 m0, s59, 0x2000
	s_add_u32 s20, s24, 0x160000
	s_addc_u32 s21, s25, 0
	s_add_i32 s65, s56, s31
	global_load_lds_dwordx4 v158, s[24:25]
	s_mov_b32 m0, s65
	s_nop 0
	global_load_lds_dwordx4 v154, s[20:21]
	s_add_i32 m0, s65, 0x2000
	s_nop 0
	global_load_lds_dwordx4 v158, s[20:21]
	s_add_u32 s100, s26, s6
	s_addc_u32 s101, s27, s7
	s_mov_b32 m0, s33
	s_nop 0
	global_load_lds_dwordx4 v152, s[26:27]
	s_mov_b32 m0, s34
	s_nop 0
	global_load_lds_dwordx4 v156, s[26:27]
	s_waitcnt vmcnt(8)
	s_waitcnt lgkmcnt(0)
	s_barrier
	s_waitcnt lgkmcnt(0)
	v_mfma_f32_16x16x32_bf16 v[60:63], v[132:135], v[186:189], v[60:63]
	v_mfma_f32_16x16x32_bf16 v[60:63], v[136:139], v[190:193], v[60:63]
	v_mfma_f32_16x16x32_bf16 v[56:59], v[140:143], v[186:189], v[56:59]
	v_mfma_f32_16x16x32_bf16 v[56:59], v[144:147], v[190:193], v[56:59]
	v_mfma_f32_16x16x32_bf16 v[44:47], v[132:135], v[194:197], v[44:47]
	v_mfma_f32_16x16x32_bf16 v[44:47], v[136:139], v[198:201], v[44:47]
	v_mfma_f32_16x16x32_bf16 v[40:43], v[140:143], v[194:197], v[40:43]
	v_mfma_f32_16x16x32_bf16 v[40:43], v[144:147], v[198:201], v[40:43]
	v_mfma_f32_16x16x32_bf16 v[28:31], v[132:135], v[202:205], v[28:31]
	v_mfma_f32_16x16x32_bf16 v[28:31], v[136:139], v[206:209], v[28:31]
	v_mfma_f32_16x16x32_bf16 v[24:27], v[140:143], v[202:205], v[24:27]
	v_mfma_f32_16x16x32_bf16 v[24:27], v[144:147], v[206:209], v[24:27]
	v_mfma_f32_16x16x32_bf16 v[12:15], v[132:135], v[210:213], v[12:15]
	v_mfma_f32_16x16x32_bf16 v[12:15], v[136:139], v[214:217], v[12:15]
	v_mfma_f32_16x16x32_bf16 v[8:11], v[140:143], v[210:213], v[8:11]
	v_mfma_f32_16x16x32_bf16 v[8:11], v[144:147], v[214:217], v[8:11]
	v_mfma_f32_16x16x32_bf16 v[52:55], v[148:151], v[186:189], v[52:55]
	v_mfma_f32_16x16x32_bf16 v[52:55], v[166:169], v[190:193], v[52:55]
	v_mfma_f32_16x16x32_bf16 v[48:51], v[170:173], v[186:189], v[48:51]
	v_mfma_f32_16x16x32_bf16 v[48:51], v[174:177], v[190:193], v[48:51]
	v_mfma_f32_16x16x32_bf16 v[36:39], v[148:151], v[194:197], v[36:39]
	v_mfma_f32_16x16x32_bf16 v[36:39], v[166:169], v[198:201], v[36:39]
	v_mfma_f32_16x16x32_bf16 v[32:35], v[170:173], v[194:197], v[32:35]
	v_mfma_f32_16x16x32_bf16 v[32:35], v[174:177], v[198:201], v[32:35]
	v_mfma_f32_16x16x32_bf16 v[20:23], v[148:151], v[202:205], v[20:23]
	v_mfma_f32_16x16x32_bf16 v[20:23], v[166:169], v[206:209], v[20:23]
	v_mfma_f32_16x16x32_bf16 v[16:19], v[170:173], v[202:205], v[16:19]
	v_mfma_f32_16x16x32_bf16 v[16:19], v[174:177], v[206:209], v[16:19]
	v_mfma_f32_16x16x32_bf16 v[4:7], v[148:151], v[210:213], v[4:7]
	v_mfma_f32_16x16x32_bf16 v[4:7], v[166:169], v[214:217], v[4:7]
	v_mfma_f32_16x16x32_bf16 v[0:3], v[170:173], v[210:213], v[0:3]
	v_mfma_f32_16x16x32_bf16 v[0:3], v[174:177], v[214:217], v[0:3]
	s_barrier
	s_add_i32 s65, 0, 0x18000
	s_add_i32 s66, 0, 0x1c000
	v_add_u32_e32 v144, s65, v178
	v_add_u32_e32 v160, s66, v178
	ds_read_b128 v[132:135], v144
	ds_read_b128 v[136:139], v144 offset:1024
	ds_read_b128 v[140:143], v144 offset:2048
	ds_read_b128 v[144:147], v144 offset:3072
	ds_read_b128 v[148:151], v160
	ds_read_b128 v[166:169], v160 offset:1024
	ds_read_b128 v[170:173], v160 offset:2048
	ds_read_b128 v[174:177], v160 offset:3072
	s_add_u32 s20, s26, 0x160000
	s_addc_u32 s21, s27, 0
	s_mov_b32 m0, s35
	ds_read_b128 v[186:189], v181 offset:32768
	ds_read_b128 v[190:193], v181 offset:33792
	ds_read_b128 v[194:197], v181 offset:34816
	ds_read_b128 v[198:201], v181 offset:35840
	ds_read_b128 v[202:205], v181 offset:36864
	ds_read_b128 v[206:209], v181 offset:37888
	ds_read_b128 v[210:213], v181 offset:38912
	ds_read_b128 v[214:217], v181 offset:39936
	global_load_lds_dwordx4 v152, s[20:21]
	s_mov_b32 m0, s36
	s_nop 0
	global_load_lds_dwordx4 v156, s[20:21]
	s_waitcnt vmcnt(8)
	s_waitcnt lgkmcnt(0)
	s_barrier
	s_waitcnt lgkmcnt(0)
	v_mfma_f32_16x16x32_bf16 v[124:127], v[132:135], v[186:189], v[124:127]
	v_mfma_f32_16x16x32_bf16 v[124:127], v[136:139], v[190:193], v[124:127]
	v_mfma_f32_16x16x32_bf16 v[120:123], v[140:143], v[186:189], v[120:123]
	v_mfma_f32_16x16x32_bf16 v[120:123], v[144:147], v[190:193], v[120:123]
	v_mfma_f32_16x16x32_bf16 v[108:111], v[132:135], v[194:197], v[108:111]
	v_mfma_f32_16x16x32_bf16 v[108:111], v[136:139], v[198:201], v[108:111]
	v_mfma_f32_16x16x32_bf16 v[104:107], v[140:143], v[194:197], v[104:107]
	v_mfma_f32_16x16x32_bf16 v[104:107], v[144:147], v[198:201], v[104:107]
	v_mfma_f32_16x16x32_bf16 v[92:95], v[132:135], v[202:205], v[92:95]
	v_mfma_f32_16x16x32_bf16 v[92:95], v[136:139], v[206:209], v[92:95]
	v_mfma_f32_16x16x32_bf16 v[88:91], v[140:143], v[202:205], v[88:91]
	v_mfma_f32_16x16x32_bf16 v[88:91], v[144:147], v[206:209], v[88:91]
	v_mfma_f32_16x16x32_bf16 v[76:79], v[132:135], v[210:213], v[76:79]
	v_mfma_f32_16x16x32_bf16 v[76:79], v[136:139], v[214:217], v[76:79]
	v_mfma_f32_16x16x32_bf16 v[72:75], v[140:143], v[210:213], v[72:75]
	v_mfma_f32_16x16x32_bf16 v[72:75], v[144:147], v[214:217], v[72:75]
	v_mfma_f32_16x16x32_bf16 v[116:119], v[148:151], v[186:189], v[116:119]
	v_mfma_f32_16x16x32_bf16 v[116:119], v[166:169], v[190:193], v[116:119]
	v_mfma_f32_16x16x32_bf16 v[112:115], v[170:173], v[186:189], v[112:115]
	v_mfma_f32_16x16x32_bf16 v[112:115], v[174:177], v[190:193], v[112:115]
	v_mfma_f32_16x16x32_bf16 v[100:103], v[148:151], v[194:197], v[100:103]
	v_mfma_f32_16x16x32_bf16 v[100:103], v[166:169], v[198:201], v[100:103]
	v_mfma_f32_16x16x32_bf16 v[96:99], v[170:173], v[194:197], v[96:99]
	v_mfma_f32_16x16x32_bf16 v[96:99], v[174:177], v[198:201], v[96:99]
	v_mfma_f32_16x16x32_bf16 v[84:87], v[148:151], v[202:205], v[84:87]
	v_mfma_f32_16x16x32_bf16 v[84:87], v[166:169], v[206:209], v[84:87]
	v_mfma_f32_16x16x32_bf16 v[80:83], v[170:173], v[202:205], v[80:83]
	v_mfma_f32_16x16x32_bf16 v[80:83], v[174:177], v[206:209], v[80:83]
	v_mfma_f32_16x16x32_bf16 v[68:71], v[148:151], v[210:213], v[68:71]
	v_mfma_f32_16x16x32_bf16 v[68:71], v[166:169], v[214:217], v[68:71]
	v_mfma_f32_16x16x32_bf16 v[64:67], v[170:173], v[210:213], v[64:67]
	v_mfma_f32_16x16x32_bf16 v[64:67], v[174:177], v[214:217], v[64:67]
	s_barrier
	s_add_i32 s20, s65, s31
	s_mov_b32 m0, s20
	ds_read_b128 v[186:189], v181 offset:49152
	ds_read_b128 v[190:193], v181 offset:50176
	ds_read_b128 v[194:197], v181 offset:51200
	ds_read_b128 v[198:201], v181 offset:52224
	ds_read_b128 v[202:205], v181 offset:53248
	ds_read_b128 v[206:209], v181 offset:54272
	ds_read_b128 v[210:213], v181 offset:55296
	ds_read_b128 v[214:217], v181 offset:56320
	global_load_lds_dwordx4 v154, s[98:99]
	s_add_i32 m0, s20, 0x2000
	s_add_u32 s20, s24, 0x160080
	s_addc_u32 s21, s25, 0
	s_add_i32 s24, s66, s31
	global_load_lds_dwordx4 v158, s[98:99]
	s_mov_b32 m0, s24
	s_nop 0
	global_load_lds_dwordx4 v154, s[20:21]
	s_add_i32 m0, s24, 0x2000
	s_nop 0
	global_load_lds_dwordx4 v158, s[20:21]
	s_mov_b32 m0, s39
	s_nop 0
	global_load_lds_dwordx4 v152, s[100:101]
	s_mov_b32 m0, s40
	s_nop 0
	global_load_lds_dwordx4 v156, s[100:101]
	s_waitcnt vmcnt(8)
	s_waitcnt lgkmcnt(0)
	s_barrier
	s_waitcnt lgkmcnt(0)
	v_mfma_f32_16x16x32_bf16 v[60:63], v[132:135], v[186:189], v[60:63]
	v_mfma_f32_16x16x32_bf16 v[60:63], v[136:139], v[190:193], v[60:63]
	v_mfma_f32_16x16x32_bf16 v[56:59], v[140:143], v[186:189], v[56:59]
	v_mfma_f32_16x16x32_bf16 v[56:59], v[144:147], v[190:193], v[56:59]
	v_mfma_f32_16x16x32_bf16 v[44:47], v[132:135], v[194:197], v[44:47]
	v_mfma_f32_16x16x32_bf16 v[44:47], v[136:139], v[198:201], v[44:47]
	v_mfma_f32_16x16x32_bf16 v[40:43], v[140:143], v[194:197], v[40:43]
	v_mfma_f32_16x16x32_bf16 v[40:43], v[144:147], v[198:201], v[40:43]
	v_mfma_f32_16x16x32_bf16 v[28:31], v[132:135], v[202:205], v[28:31]
	v_mfma_f32_16x16x32_bf16 v[28:31], v[136:139], v[206:209], v[28:31]
	v_mfma_f32_16x16x32_bf16 v[24:27], v[140:143], v[202:205], v[24:27]
	v_mfma_f32_16x16x32_bf16 v[24:27], v[144:147], v[206:209], v[24:27]
	v_mfma_f32_16x16x32_bf16 v[12:15], v[132:135], v[210:213], v[12:15]
	v_mfma_f32_16x16x32_bf16 v[12:15], v[136:139], v[214:217], v[12:15]
	v_mfma_f32_16x16x32_bf16 v[8:11], v[140:143], v[210:213], v[8:11]
	v_mfma_f32_16x16x32_bf16 v[8:11], v[144:147], v[214:217], v[8:11]
	v_mfma_f32_16x16x32_bf16 v[52:55], v[148:151], v[186:189], v[52:55]
	v_mfma_f32_16x16x32_bf16 v[52:55], v[166:169], v[190:193], v[52:55]
	v_mfma_f32_16x16x32_bf16 v[48:51], v[170:173], v[186:189], v[48:51]
	v_mfma_f32_16x16x32_bf16 v[48:51], v[174:177], v[190:193], v[48:51]
	v_mfma_f32_16x16x32_bf16 v[36:39], v[148:151], v[194:197], v[36:39]
	v_mfma_f32_16x16x32_bf16 v[36:39], v[166:169], v[198:201], v[36:39]
	v_mfma_f32_16x16x32_bf16 v[32:35], v[170:173], v[194:197], v[32:35]
	v_mfma_f32_16x16x32_bf16 v[32:35], v[174:177], v[198:201], v[32:35]
	v_mfma_f32_16x16x32_bf16 v[20:23], v[148:151], v[202:205], v[20:23]
	v_mfma_f32_16x16x32_bf16 v[20:23], v[166:169], v[206:209], v[20:23]
	v_mfma_f32_16x16x32_bf16 v[16:19], v[170:173], v[202:205], v[16:19]
	v_mfma_f32_16x16x32_bf16 v[16:19], v[174:177], v[206:209], v[16:19]
	v_mfma_f32_16x16x32_bf16 v[4:7], v[148:151], v[210:213], v[4:7]
	v_mfma_f32_16x16x32_bf16 v[4:7], v[166:169], v[214:217], v[4:7]
	v_mfma_f32_16x16x32_bf16 v[0:3], v[170:173], v[210:213], v[0:3]
	v_mfma_f32_16x16x32_bf16 v[0:3], v[174:177], v[214:217], v[0:3]
	s_barrier
	s_add_i32 s64, s64, 2
	s_cmpk_gt_u32 s64, 0x55
	s_mov_b64 s[20:21], s[22:23]
	s_cbranch_scc0 .LBB0_975
	s_and_b64 vcc, exec, s[8:9]
	s_cbranch_vccz .LBB0_978
	s_barrier
